# all GEMM/attention LDS-DMA sites with scalar base + zero-extended 32-bit lane offset now use the saddr form (107 v_lshl_add_u64 removed)
# baseline (speedup 1.0000x reference)
.LBB0_299:
	s_add_u32 s8, s4, 0x9600000
	s_addc_u32 s9, s5, 0
	s_lshl_b32 s4, s12, 5
	s_and_b32 s12, s4, 0x60
	s_add_i32 m0, s44, 0x18000
	v_lshl_add_u64 v[6:7], v[6:7], 0, s[92:93]
	s_lshl_b32 s13, s11, 13
	s_lshl_b32 s14, s12, 7
	s_waitcnt vmcnt(2)
	s_barrier
	global_load_lds_dwordx4 v[6:7], off
	v_lshl_add_u64 v[4:5], v[4:5], 0, s[92:93]
	s_add_i32 m0, s44, 0x1a000
	s_add_i32 s48, s44, 0x8000
	s_add_i32 s49, s44, 0xa000
	global_load_lds_dwordx4 v[4:5], off
	v_lshl_add_u64 v[0:1], v[0:1], 0, s[92:93]
	s_mov_b32 m0, s48
	s_add_u32 s4, s22, 0x40080
	global_load_lds_dwordx4 v[0:1], off
	v_lshl_add_u64 v[0:1], v[2:3], 0, s[92:93]
	s_mov_b32 m0, s49
	s_addc_u32 s5, s23, 0
	global_load_lds_dwordx4 v[0:1], off
	s_add_i32 m0, s44, 0x1c000
	s_nop 0
	global_load_lds_dwordx4 v208, s[4:5]
	s_add_i32 m0, s44, 0x1e000
	s_cmpk_lt_u32 s10, 0x100
	global_load_lds_dwordx4 v128, s[4:5]
	v_lshrrev_b32_e32 v1, 1, v8
	v_and_b32_e32 v1, 24, v1
	v_and_b32_e32 v0, 15, v8
	v_lshlrev_b32_e32 v2, 1, v1
	v_lshl_or_b32 v140, s11, 6, v0
	v_lshl_or_b32 v0, v0, 6, v2
	v_lshlrev_b32_e32 v2, 2, v8
	v_and_b32_e32 v2, 32, v2
	v_bitop3_b32 v3, v0, s13, v2 bitop3:0xde
	v_bitop3_b32 v141, v0, s14, v2 bitop3:0xde
	v_lshlrev_b32_e32 v0, 14, v13
	v_and_b32_e32 v0, 0xffff8000, v0
	v_or_b32_e32 v142, s12, v1
	v_lshl_add_u32 v0, v12, 11, v0
	v_and_b32_e32 v1, 1, v13
	v_lshl_or_b32 v0, v1, 6, v0
	v_lshl_add_u32 v134, v14, 1, v0
	v_lshlrev_b32_e32 v0, 14, v9
	v_and_b32_e32 v0, 0xffff8000, v0
	s_waitcnt vmcnt(6)
	v_lshl_add_u32 v0, v10, 11, v0
	v_and_b32_e32 v1, 1, v9
	v_lshl_or_b32 v0, v1, 6, v0
	v_readlane_b32 s4, v253, 45
	s_cselect_b64 s[10:11], -1, 0
	v_mov_b32_e32 v135, v209
	v_lshl_add_u32 v136, v11, 1, v0
	v_mov_b32_e32 v137, v209
	s_mov_b32 s50, 0
	v_add_u32_e32 v143, 0, v3
	v_readlane_b32 s34, v253, 43
	s_mov_b32 s51, s4
	s_barrier
	v_readlane_b32 s5, v253, 46
	s_branch .LBB0_302

.LBB0_309:
	s_add_u32 s22, s0, 0xfffc0080
	s_addc_u32 s23, s1, -1
	s_add_i32 s61, 0, 0x10000
	s_cmp_eq_u32 s60, 12
	s_cselect_b32 s43, s15, s23
	s_cselect_b32 s42, s24, s22
	v_add_u32_e32 v138, s61, v141
	s_cselect_b32 s23, s13, s55
	s_cselect_b32 s22, s25, s54
	s_add_i32 s63, 0, 0x14000
	ds_read_b128 v[144:147], v138
	ds_read_b128 v[148:151], v138 offset:1024
	ds_read_b128 v[152:155], v138 offset:2048
	ds_read_b128 v[156:159], v138 offset:3072
	v_add_u32_e32 v138, s63, v141
	ds_read_b128 v[160:163], v138
	ds_read_b128 v[164:167], v138 offset:1024
	ds_read_b128 v[168:171], v138 offset:2048
	ds_read_b128 v[172:175], v138 offset:3072
	s_add_i32 m0, s44, 0xc000
	ds_read_b128 v[176:179], v143
	ds_read_b128 v[180:183], v143 offset:1024
	ds_read_b128 v[184:187], v143 offset:2048
	ds_read_b128 v[188:191], v143 offset:3072
	ds_read_b128 v[192:195], v143 offset:4096
	ds_read_b128 v[196:199], v143 offset:5120
	ds_read_b128 v[200:203], v143 offset:6144
	ds_read_b128 v[204:207], v143 offset:7168
	global_load_lds_dwordx4 v134, s[0:1]
	s_add_i32 m0, s44, 0xe000
	s_nop 0
	global_load_lds_dwordx4 v136, s[0:1]
	s_waitcnt vmcnt(8)
	s_waitcnt lgkmcnt(0)
	s_barrier
	s_setprio 1
	s_waitcnt lgkmcnt(0)
	v_mfma_f32_16x16x32_bf16 v[124:127], v[144:147], v[176:179], v[124:127]
	v_mfma_f32_16x16x32_bf16 v[116:119], v[152:155], v[176:179], v[116:119]
	v_mfma_f32_16x16x32_bf16 v[108:111], v[144:147], v[184:187], v[108:111]
	v_mfma_f32_16x16x32_bf16 v[100:103], v[152:155], v[184:187], v[100:103]
	v_mfma_f32_16x16x32_bf16 v[92:95], v[144:147], v[192:195], v[92:95]
	v_mfma_f32_16x16x32_bf16 v[84:87], v[152:155], v[192:195], v[84:87]
	v_mfma_f32_16x16x32_bf16 v[76:79], v[144:147], v[200:203], v[76:79]
	v_mfma_f32_16x16x32_bf16 v[68:71], v[152:155], v[200:203], v[68:71]
	v_mfma_f32_16x16x32_bf16 v[124:127], v[148:151], v[180:183], v[124:127]
	v_mfma_f32_16x16x32_bf16 v[116:119], v[156:159], v[180:183], v[116:119]
	v_mfma_f32_16x16x32_bf16 v[108:111], v[148:151], v[188:191], v[108:111]
	v_mfma_f32_16x16x32_bf16 v[100:103], v[156:159], v[188:191], v[100:103]
	v_mfma_f32_16x16x32_bf16 v[92:95], v[148:151], v[196:199], v[92:95]
	v_mfma_f32_16x16x32_bf16 v[84:87], v[156:159], v[196:199], v[84:87]
	v_mfma_f32_16x16x32_bf16 v[76:79], v[148:151], v[204:207], v[76:79]
	v_mfma_f32_16x16x32_bf16 v[68:71], v[156:159], v[204:207], v[68:71]
	s_setprio 0
	s_setprio 1
	v_mfma_f32_16x16x32_bf16 v[120:123], v[160:163], v[176:179], v[120:123]
	v_mfma_f32_16x16x32_bf16 v[112:115], v[168:171], v[176:179], v[112:115]
	v_mfma_f32_16x16x32_bf16 v[104:107], v[160:163], v[184:187], v[104:107]
	v_mfma_f32_16x16x32_bf16 v[96:99], v[168:171], v[184:187], v[96:99]
	v_mfma_f32_16x16x32_bf16 v[88:91], v[160:163], v[192:195], v[88:91]
	v_mfma_f32_16x16x32_bf16 v[80:83], v[168:171], v[192:195], v[80:83]
	v_mfma_f32_16x16x32_bf16 v[72:75], v[160:163], v[200:203], v[72:75]
	v_mfma_f32_16x16x32_bf16 v[64:67], v[168:171], v[200:203], v[64:67]
	v_mfma_f32_16x16x32_bf16 v[120:123], v[164:167], v[180:183], v[120:123]
	v_mfma_f32_16x16x32_bf16 v[112:115], v[172:175], v[180:183], v[112:115]
	v_mfma_f32_16x16x32_bf16 v[104:107], v[164:167], v[188:191], v[104:107]
	v_mfma_f32_16x16x32_bf16 v[96:99], v[172:175], v[188:191], v[96:99]
	v_mfma_f32_16x16x32_bf16 v[88:91], v[164:167], v[196:199], v[88:91]
	v_mfma_f32_16x16x32_bf16 v[80:83], v[172:175], v[196:199], v[80:83]
	v_mfma_f32_16x16x32_bf16 v[72:75], v[164:167], v[204:207], v[72:75]
	v_mfma_f32_16x16x32_bf16 v[64:67], v[172:175], v[204:207], v[64:67]
	s_setprio 0
	s_barrier
	s_add_i32 s61, s61, s35
	v_lshl_add_u64 v[138:139], s[22:23], 0, v[208:209]
	s_mov_b32 m0, s61
	ds_read_b128 v[176:179], v143 offset:16384
	ds_read_b128 v[180:183], v143 offset:17408
	ds_read_b128 v[184:187], v143 offset:18432
	ds_read_b128 v[188:191], v143 offset:19456
	ds_read_b128 v[192:195], v143 offset:20480
	ds_read_b128 v[196:199], v143 offset:21504
	ds_read_b128 v[200:203], v143 offset:22528
	ds_read_b128 v[204:207], v143 offset:23552
	global_load_lds_dwordx4 v[138:139], off
	s_add_i32 m0, s61, 0x2000
	s_add_u32 s66, s22, 0x40000
	v_lshl_add_u64 v[214:215], s[22:23], 0, v[128:129]
	s_addc_u32 s67, s23, 0
	s_add_i32 s61, s63, s35
	global_load_lds_dwordx4 v[214:215], off
	s_mov_b32 m0, s61
	v_lshl_add_u64 v[224:225], s[42:43], 0, v[130:131]
	global_load_lds_dwordx4 v208, s[66:67]
	s_add_i32 m0, s61, 0x2000
	s_nop 0
	global_load_lds_dwordx4 v128, s[66:67]
	v_lshl_add_u64 v[216:217], s[42:43], 0, v[132:133]
	s_mov_b32 m0, s44
	s_nop 0
	global_load_lds_dwordx4 v[216:217], off
	s_mov_b32 m0, s45
	s_nop 0
	global_load_lds_dwordx4 v[224:225], off
	s_waitcnt vmcnt(8)
	s_waitcnt lgkmcnt(0)
	s_barrier
	s_setprio 1
	s_waitcnt lgkmcnt(0)
	v_mfma_f32_16x16x32_bf16 v[60:63], v[144:147], v[176:179], v[60:63]
	v_mfma_f32_16x16x32_bf16 v[52:55], v[152:155], v[176:179], v[52:55]
	v_mfma_f32_16x16x32_bf16 v[44:47], v[144:147], v[184:187], v[44:47]
	v_mfma_f32_16x16x32_bf16 v[36:39], v[152:155], v[184:187], v[36:39]
	v_mfma_f32_16x16x32_bf16 v[28:31], v[144:147], v[192:195], v[28:31]
	v_mfma_f32_16x16x32_bf16 v[20:23], v[152:155], v[192:195], v[20:23]
	v_mfma_f32_16x16x32_bf16 v[12:15], v[144:147], v[200:203], v[12:15]
	v_mfma_f32_16x16x32_bf16 v[4:7], v[152:155], v[200:203], v[4:7]
	v_mfma_f32_16x16x32_bf16 v[60:63], v[148:151], v[180:183], v[60:63]
	v_mfma_f32_16x16x32_bf16 v[52:55], v[156:159], v[180:183], v[52:55]
	v_mfma_f32_16x16x32_bf16 v[44:47], v[148:151], v[188:191], v[44:47]
	v_mfma_f32_16x16x32_bf16 v[36:39], v[156:159], v[188:191], v[36:39]
	v_mfma_f32_16x16x32_bf16 v[28:31], v[148:151], v[196:199], v[28:31]
	v_mfma_f32_16x16x32_bf16 v[20:23], v[156:159], v[196:199], v[20:23]
	v_mfma_f32_16x16x32_bf16 v[12:15], v[148:151], v[204:207], v[12:15]
	v_mfma_f32_16x16x32_bf16 v[4:7], v[156:159], v[204:207], v[4:7]
	s_setprio 0
	s_setprio 1
	v_mfma_f32_16x16x32_bf16 v[56:59], v[160:163], v[176:179], v[56:59]
	v_mfma_f32_16x16x32_bf16 v[48:51], v[168:171], v[176:179], v[48:51]
	v_mfma_f32_16x16x32_bf16 v[40:43], v[160:163], v[184:187], v[40:43]
	v_mfma_f32_16x16x32_bf16 v[32:35], v[168:171], v[184:187], v[32:35]
	v_mfma_f32_16x16x32_bf16 v[24:27], v[160:163], v[192:195], v[24:27]
	v_mfma_f32_16x16x32_bf16 v[16:19], v[168:171], v[192:195], v[16:19]
	v_mfma_f32_16x16x32_bf16 v[8:11], v[160:163], v[200:203], v[8:11]
	v_mfma_f32_16x16x32_bf16 v[0:3], v[168:171], v[200:203], v[0:3]
	v_mfma_f32_16x16x32_bf16 v[56:59], v[164:167], v[180:183], v[56:59]
	v_mfma_f32_16x16x32_bf16 v[48:51], v[172:175], v[180:183], v[48:51]
	v_mfma_f32_16x16x32_bf16 v[40:43], v[164:167], v[188:191], v[40:43]
	v_mfma_f32_16x16x32_bf16 v[32:35], v[172:175], v[188:191], v[32:35]
	v_mfma_f32_16x16x32_bf16 v[24:27], v[164:167], v[196:199], v[24:27]
	v_mfma_f32_16x16x32_bf16 v[16:19], v[172:175], v[196:199], v[16:19]
	v_mfma_f32_16x16x32_bf16 v[8:11], v[164:167], v[204:207], v[8:11]
	v_mfma_f32_16x16x32_bf16 v[0:3], v[172:175], v[204:207], v[0:3]
	s_setprio 0
	s_barrier
	s_add_i32 s61, 0, 0x18000
	s_add_i32 s63, 0, 0x1c000
	v_add_u32_e32 v156, s61, v141
	v_add_u32_e32 v172, s63, v141
	ds_read_b128 v[144:147], v156
	ds_read_b128 v[148:151], v156 offset:1024
	ds_read_b128 v[152:155], v156 offset:2048
	ds_read_b128 v[156:159], v156 offset:3072
	ds_read_b128 v[160:163], v172
	ds_read_b128 v[164:167], v172 offset:1024
	ds_read_b128 v[168:171], v172 offset:2048
	ds_read_b128 v[172:175], v172 offset:3072
	s_add_u32 s42, s42, 0x40000
	s_addc_u32 s43, s43, 0
	s_mov_b32 m0, s46
	ds_read_b128 v[176:179], v143 offset:32768
	ds_read_b128 v[180:183], v143 offset:33792
	ds_read_b128 v[184:187], v143 offset:34816
	ds_read_b128 v[188:191], v143 offset:35840
	ds_read_b128 v[192:195], v143 offset:36864
	ds_read_b128 v[196:199], v143 offset:37888
	ds_read_b128 v[200:203], v143 offset:38912
	ds_read_b128 v[204:207], v143 offset:39936
	global_load_lds_dwordx4 v132, s[42:43]
	s_mov_b32 m0, s47
	s_nop 0
	global_load_lds_dwordx4 v130, s[42:43]
	s_waitcnt vmcnt(8)
	s_waitcnt lgkmcnt(0)
	s_barrier
	s_setprio 1
	s_waitcnt lgkmcnt(0)
	v_mfma_f32_16x16x32_bf16 v[124:127], v[144:147], v[176:179], v[124:127]
	v_mfma_f32_16x16x32_bf16 v[116:119], v[152:155], v[176:179], v[116:119]
	v_mfma_f32_16x16x32_bf16 v[108:111], v[144:147], v[184:187], v[108:111]
	v_mfma_f32_16x16x32_bf16 v[100:103], v[152:155], v[184:187], v[100:103]
	v_mfma_f32_16x16x32_bf16 v[92:95], v[144:147], v[192:195], v[92:95]
	v_mfma_f32_16x16x32_bf16 v[84:87], v[152:155], v[192:195], v[84:87]
	v_mfma_f32_16x16x32_bf16 v[76:79], v[144:147], v[200:203], v[76:79]
	v_mfma_f32_16x16x32_bf16 v[68:71], v[152:155], v[200:203], v[68:71]
	v_mfma_f32_16x16x32_bf16 v[124:127], v[148:151], v[180:183], v[124:127]
	v_mfma_f32_16x16x32_bf16 v[116:119], v[156:159], v[180:183], v[116:119]
	v_mfma_f32_16x16x32_bf16 v[108:111], v[148:151], v[188:191], v[108:111]
	v_mfma_f32_16x16x32_bf16 v[100:103], v[156:159], v[188:191], v[100:103]
	v_mfma_f32_16x16x32_bf16 v[92:95], v[148:151], v[196:199], v[92:95]
	v_mfma_f32_16x16x32_bf16 v[84:87], v[156:159], v[196:199], v[84:87]
	v_mfma_f32_16x16x32_bf16 v[76:79], v[148:151], v[204:207], v[76:79]
	v_mfma_f32_16x16x32_bf16 v[68:71], v[156:159], v[204:207], v[68:71]
	s_setprio 0
	s_setprio 1
	v_mfma_f32_16x16x32_bf16 v[120:123], v[160:163], v[176:179], v[120:123]
	v_mfma_f32_16x16x32_bf16 v[112:115], v[168:171], v[176:179], v[112:115]
	v_mfma_f32_16x16x32_bf16 v[104:107], v[160:163], v[184:187], v[104:107]
	v_mfma_f32_16x16x32_bf16 v[96:99], v[168:171], v[184:187], v[96:99]
	v_mfma_f32_16x16x32_bf16 v[88:91], v[160:163], v[192:195], v[88:91]
	v_mfma_f32_16x16x32_bf16 v[80:83], v[168:171], v[192:195], v[80:83]
	v_mfma_f32_16x16x32_bf16 v[72:75], v[160:163], v[200:203], v[72:75]
	v_mfma_f32_16x16x32_bf16 v[64:67], v[168:171], v[200:203], v[64:67]
	v_mfma_f32_16x16x32_bf16 v[120:123], v[164:167], v[180:183], v[120:123]
	v_mfma_f32_16x16x32_bf16 v[112:115], v[172:175], v[180:183], v[112:115]
	v_mfma_f32_16x16x32_bf16 v[104:107], v[164:167], v[188:191], v[104:107]
	v_mfma_f32_16x16x32_bf16 v[96:99], v[172:175], v[188:191], v[96:99]
	v_mfma_f32_16x16x32_bf16 v[88:91], v[164:167], v[196:199], v[88:91]
	v_mfma_f32_16x16x32_bf16 v[80:83], v[172:175], v[196:199], v[80:83]
	v_mfma_f32_16x16x32_bf16 v[72:75], v[164:167], v[204:207], v[72:75]
	v_mfma_f32_16x16x32_bf16 v[64:67], v[172:175], v[204:207], v[64:67]
	s_setprio 0
	s_barrier
	s_add_i32 s42, s61, s35
	v_lshl_add_u64 v[138:139], v[138:139], 0, s[92:93]
	s_mov_b32 m0, s42
	ds_read_b128 v[176:179], v143 offset:49152
	ds_read_b128 v[180:183], v143 offset:50176
	ds_read_b128 v[184:187], v143 offset:51200
	ds_read_b128 v[188:191], v143 offset:52224
	ds_read_b128 v[192:195], v143 offset:53248
	ds_read_b128 v[196:199], v143 offset:54272
	ds_read_b128 v[200:203], v143 offset:55296
	ds_read_b128 v[204:207], v143 offset:56320
	global_load_lds_dwordx4 v[138:139], off
	s_add_i32 m0, s42, 0x2000
	s_add_u32 s22, s22, 0x40080
	v_lshl_add_u64 v[138:139], v[214:215], 0, s[92:93]
	s_addc_u32 s23, s23, 0
	s_add_i32 s42, s63, s35
	global_load_lds_dwordx4 v[138:139], off
	s_mov_b32 m0, s42
	s_nop 0
	global_load_lds_dwordx4 v208, s[22:23]
	s_add_i32 m0, s42, 0x2000
	s_nop 0
	global_load_lds_dwordx4 v128, s[22:23]
	v_lshl_add_u64 v[138:139], v[216:217], 0, s[92:93]
	s_mov_b32 m0, s48
	s_nop 0
	global_load_lds_dwordx4 v[138:139], off
	v_lshl_add_u64 v[138:139], v[224:225], 0, s[92:93]
	s_mov_b32 m0, s49
	s_nop 0
	global_load_lds_dwordx4 v[138:139], off
	s_waitcnt vmcnt(8)
	s_waitcnt lgkmcnt(0)
	s_barrier
	s_setprio 1
	s_waitcnt lgkmcnt(0)
	v_mfma_f32_16x16x32_bf16 v[60:63], v[144:147], v[176:179], v[60:63]
	v_mfma_f32_16x16x32_bf16 v[52:55], v[152:155], v[176:179], v[52:55]
	v_mfma_f32_16x16x32_bf16 v[44:47], v[144:147], v[184:187], v[44:47]
	v_mfma_f32_16x16x32_bf16 v[36:39], v[152:155], v[184:187], v[36:39]
	v_mfma_f32_16x16x32_bf16 v[28:31], v[144:147], v[192:195], v[28:31]
	v_mfma_f32_16x16x32_bf16 v[20:23], v[152:155], v[192:195], v[20:23]
	v_mfma_f32_16x16x32_bf16 v[12:15], v[144:147], v[200:203], v[12:15]
	v_mfma_f32_16x16x32_bf16 v[4:7], v[152:155], v[200:203], v[4:7]
	v_mfma_f32_16x16x32_bf16 v[60:63], v[148:151], v[180:183], v[60:63]
	v_mfma_f32_16x16x32_bf16 v[52:55], v[156:159], v[180:183], v[52:55]
	v_mfma_f32_16x16x32_bf16 v[44:47], v[148:151], v[188:191], v[44:47]
	v_mfma_f32_16x16x32_bf16 v[36:39], v[156:159], v[188:191], v[36:39]
	v_mfma_f32_16x16x32_bf16 v[28:31], v[148:151], v[196:199], v[28:31]
	v_mfma_f32_16x16x32_bf16 v[20:23], v[156:159], v[196:199], v[20:23]
	v_mfma_f32_16x16x32_bf16 v[12:15], v[148:151], v[204:207], v[12:15]
	v_mfma_f32_16x16x32_bf16 v[4:7], v[156:159], v[204:207], v[4:7]
	s_setprio 0
	s_setprio 1
	v_mfma_f32_16x16x32_bf16 v[56:59], v[160:163], v[176:179], v[56:59]
	v_mfma_f32_16x16x32_bf16 v[48:51], v[168:171], v[176:179], v[48:51]
	v_mfma_f32_16x16x32_bf16 v[40:43], v[160:163], v[184:187], v[40:43]
	v_mfma_f32_16x16x32_bf16 v[32:35], v[168:171], v[184:187], v[32:35]
	v_mfma_f32_16x16x32_bf16 v[24:27], v[160:163], v[192:195], v[24:27]
	v_mfma_f32_16x16x32_bf16 v[16:19], v[168:171], v[192:195], v[16:19]
	v_mfma_f32_16x16x32_bf16 v[8:11], v[160:163], v[200:203], v[8:11]
	v_mfma_f32_16x16x32_bf16 v[0:3], v[168:171], v[200:203], v[0:3]
	v_mfma_f32_16x16x32_bf16 v[56:59], v[164:167], v[180:183], v[56:59]
	v_mfma_f32_16x16x32_bf16 v[48:51], v[172:175], v[180:183], v[48:51]
	v_mfma_f32_16x16x32_bf16 v[40:43], v[164:167], v[188:191], v[40:43]
	v_mfma_f32_16x16x32_bf16 v[32:35], v[172:175], v[188:191], v[32:35]
	v_mfma_f32_16x16x32_bf16 v[24:27], v[164:167], v[196:199], v[24:27]
	v_mfma_f32_16x16x32_bf16 v[16:19], v[172:175], v[196:199], v[16:19]
	v_mfma_f32_16x16x32_bf16 v[8:11], v[164:167], v[204:207], v[8:11]
	v_mfma_f32_16x16x32_bf16 v[0:3], v[172:175], v[204:207], v[0:3]
	s_setprio 0
	s_barrier
	s_add_i32 s60, s60, 2
	s_add_u32 s0, s0, 0x100
	s_addc_u32 s1, s1, 0
	s_add_u32 s54, s54, 0x100
	s_addc_u32 s55, s55, 0
	s_cmp_gt_u32 s60, 13
	s_cbranch_scc0 .LBB0_309
	s_and_b64 vcc, exec, s[10:11]
	s_cbranch_vccz .LBB0_312
	s_barrier

.LBB0_378:
	s_add_u32 s67, s14, 0x3300000
	s_addc_u32 s70, s15, 0
	s_and_b64 s[8:9], s[36:37], exec
	s_waitcnt lgkmcnt(0)
	s_cselect_b32 s71, s1, s70
	s_cselect_b32 s72, s0, s67
	s_add_u32 s73, s48, 0x2000
	s_addc_u32 s74, s49, 0
	s_lshl_b32 s0, s4, 5
	s_and_b32 s8, s0, 0x60
	s_add_i32 m0, s55, 0x18000
	v_lshl_add_u64 v[6:7], v[6:7], 0, s[92:93]
	s_lshl_b32 s7, s6, 13
	s_lshl_b32 s9, s8, 7
	s_waitcnt vmcnt(2)
	s_barrier
	global_load_lds_dwordx4 v[6:7], off
	v_lshl_add_u64 v[4:5], v[4:5], 0, s[92:93]
	s_add_i32 m0, s55, 0x1a000
	s_add_i32 s75, s55, 0x8000
	s_add_i32 s4, s55, 0xa000
	global_load_lds_dwordx4 v[4:5], off
	v_lshl_add_u64 v[0:1], v[0:1], 0, s[92:93]
	s_mov_b32 m0, s75
	s_add_u32 s0, s42, 0xb0080
	global_load_lds_dwordx4 v[0:1], off
	v_lshl_add_u64 v[0:1], v[2:3], 0, s[92:93]
	s_mov_b32 m0, s4
	s_addc_u32 s1, s43, 0
	global_load_lds_dwordx4 v[0:1], off
	s_add_i32 m0, s55, 0x1c000
	s_nop 0
	global_load_lds_dwordx4 v208, s[0:1]
	s_add_i32 m0, s55, 0x1e000
	v_bfe_u32 v4, v12, 4, 2
	global_load_lds_dwordx4 v128, s[0:1]
	v_and_b32_e32 v1, 15, v12
	v_lshlrev_b32_e32 v2, 4, v4
	v_lshl_or_b32 v0, s6, 6, v1
	v_lshl_or_b32 v1, v1, 6, v2
	v_lshlrev_b32_e32 v2, 2, v12
	v_and_b32_e32 v2, 32, v2
	v_bitop3_b32 v5, v1, s7, v2 bitop3:0xde
	v_bitop3_b32 v171, v1, s9, v2 bitop3:0xde
	v_or_b32_e32 v2, 16, v0
	v_ashrrev_i32_e32 v3, 31, v2
	v_lshlrev_b64 v[132:133], 12, v[2:3]
	v_or_b32_e32 v2, 32, v0
	v_ashrrev_i32_e32 v3, 31, v2
	v_lshlrev_b64 v[134:135], 12, v[2:3]
	v_or_b32_e32 v2, 48, v0
	v_ashrrev_i32_e32 v3, 31, v2
	v_lshlrev_b64 v[136:137], 12, v[2:3]
	v_add_u32_e32 v2, 0x90, v0
	v_ashrrev_i32_e32 v1, 31, v0
	v_ashrrev_i32_e32 v3, 31, v2
	v_lshlrev_b64 v[130:131], 12, v[0:1]
	v_lshlrev_b64 v[140:141], 12, v[2:3]
	v_add_u32_e32 v2, 0xa0, v0
	v_add_u32_e32 v0, 0xb0, v0
	v_ashrrev_i32_e32 v1, 31, v0
	s_movk_i32 s6, 0xb00
	s_cmpk_lt_u32 s5, 0x100
	v_lshlrev_b64 v[144:145], 12, v[0:1]
	v_lshrrev_b32_e32 v1, 1, v14
	v_mul_lo_u32 v0, v13, s6
	s_mov_b32 s5, 0xb000
	v_mad_u64_u32 v[0:1], s[0:1], v1, s5, v[0:1]
	v_or_b32_e32 v0, v0, v15
	v_lshl_or_b32 v172, v4, 2, s8
	v_add_lshl_u32 v0, v0, v16, 1
	v_mov_b32_e32 v1, v209
	s_mov_b64 s[8:9], 0xb0080
	v_lshl_add_u64 v[146:147], v[0:1], 0, s[8:9]
	v_lshrrev_b32_e32 v1, 1, v8
	v_mul_lo_u32 v0, v9, s6
	v_mad_u64_u32 v[0:1], s[0:1], v1, s5, v[0:1]
	s_waitcnt vmcnt(6)
	v_or_b32_e32 v0, v0, v10
	v_ashrrev_i32_e32 v3, 31, v2
	v_add_lshl_u32 v0, v0, v11, 1
	v_mov_b32_e32 v1, v209
	s_cselect_b64 s[36:37], -1, 0
	v_lshl_add_u64 v[138:139], v[130:131], 0, s[28:29]
	v_lshlrev_b64 v[142:143], 12, v[2:3]
	v_lshl_add_u64 v[148:149], v[0:1], 0, s[8:9]
	s_mov_b32 s5, 0
	v_add_u32_e32 v173, 0, v5
	v_readlane_b32 s34, v252, 55
	v_readlane_b32 s0, v252, 53
	s_barrier
	v_readlane_b32 s1, v252, 54
	s_branch .LBB0_381

.LBB0_392:
	s_add_u32 s42, s22, 0x100
	s_addc_u32 s43, s23, 0
	s_add_i32 s30, 0, 0x10000
	s_cmp_eq_u32 s25, 40
	s_cselect_b32 s47, s9, s43
	s_cselect_b32 s46, s8, s42
	s_cselect_b32 s45, s41, s24
	s_cselect_b32 s44, s40, s1
	s_add_i32 s31, 0, 0x14000
	v_add_u32_e32 v162, s30, v171
	v_add_u32_e32 v182, s31, v171
	ds_read_b128 v[150:153], v162
	ds_read_b128 v[154:157], v162 offset:1024
	ds_read_b128 v[158:161], v162 offset:2048
	ds_read_b128 v[162:165], v162 offset:3072
	ds_read_b128 v[166:169], v182
	ds_read_b128 v[174:177], v182 offset:1024
	ds_read_b128 v[178:181], v182 offset:2048
	ds_read_b128 v[182:185], v182 offset:3072
	v_lshl_add_u64 v[206:207], s[22:23], 0, v[146:147]
	s_add_i32 m0, s55, 0xc000
	ds_read_b128 v[186:189], v173
	ds_read_b128 v[190:193], v173 offset:1024
	ds_read_b128 v[194:197], v173 offset:2048
	ds_read_b128 v[198:201], v173 offset:3072
	ds_read_b128 v[202:205], v173 offset:4096
	ds_read_b128 v[214:217], v173 offset:5120
	ds_read_b128 v[224:227], v173 offset:6144
	ds_read_b128 v[228:231], v173 offset:7168
	global_load_lds_dwordx4 v[206:207], off
	v_lshl_add_u64 v[206:207], s[22:23], 0, v[148:149]
	s_add_i32 m0, s55, 0xe000
	s_nop 0
	global_load_lds_dwordx4 v[206:207], off
	s_waitcnt vmcnt(8)
	s_waitcnt lgkmcnt(0)
	s_barrier
	s_setprio 1
	s_waitcnt lgkmcnt(0)
	v_mfma_f32_16x16x32_bf16 v[124:127], v[150:153], v[186:189], v[124:127]
	v_mfma_f32_16x16x32_bf16 v[120:123], v[158:161], v[186:189], v[120:123]
	v_mfma_f32_16x16x32_bf16 v[108:111], v[150:153], v[194:197], v[108:111]
	v_mfma_f32_16x16x32_bf16 v[104:107], v[158:161], v[194:197], v[104:107]
	v_mfma_f32_16x16x32_bf16 v[92:95], v[150:153], v[202:205], v[92:95]
	v_mfma_f32_16x16x32_bf16 v[88:91], v[158:161], v[202:205], v[88:91]
	v_mfma_f32_16x16x32_bf16 v[76:79], v[150:153], v[224:227], v[76:79]
	v_mfma_f32_16x16x32_bf16 v[72:75], v[158:161], v[224:227], v[72:75]
	v_mfma_f32_16x16x32_bf16 v[124:127], v[154:157], v[190:193], v[124:127]
	v_mfma_f32_16x16x32_bf16 v[120:123], v[162:165], v[190:193], v[120:123]
	v_mfma_f32_16x16x32_bf16 v[108:111], v[154:157], v[198:201], v[108:111]
	v_mfma_f32_16x16x32_bf16 v[104:107], v[162:165], v[198:201], v[104:107]
	v_mfma_f32_16x16x32_bf16 v[92:95], v[154:157], v[214:217], v[92:95]
	v_mfma_f32_16x16x32_bf16 v[88:91], v[162:165], v[214:217], v[88:91]
	v_mfma_f32_16x16x32_bf16 v[76:79], v[154:157], v[228:231], v[76:79]
	v_mfma_f32_16x16x32_bf16 v[72:75], v[162:165], v[228:231], v[72:75]
	s_setprio 0
	s_setprio 1
	v_mfma_f32_16x16x32_bf16 v[116:119], v[166:169], v[186:189], v[116:119]
	v_mfma_f32_16x16x32_bf16 v[112:115], v[178:181], v[186:189], v[112:115]
	v_mfma_f32_16x16x32_bf16 v[100:103], v[166:169], v[194:197], v[100:103]
	v_mfma_f32_16x16x32_bf16 v[96:99], v[178:181], v[194:197], v[96:99]
	v_mfma_f32_16x16x32_bf16 v[84:87], v[166:169], v[202:205], v[84:87]
	v_mfma_f32_16x16x32_bf16 v[80:83], v[178:181], v[202:205], v[80:83]
	v_mfma_f32_16x16x32_bf16 v[68:71], v[166:169], v[224:227], v[68:71]
	v_mfma_f32_16x16x32_bf16 v[64:67], v[178:181], v[224:227], v[64:67]
	v_mfma_f32_16x16x32_bf16 v[116:119], v[174:177], v[190:193], v[116:119]
	v_mfma_f32_16x16x32_bf16 v[112:115], v[182:185], v[190:193], v[112:115]
	v_mfma_f32_16x16x32_bf16 v[100:103], v[174:177], v[198:201], v[100:103]
	v_mfma_f32_16x16x32_bf16 v[96:99], v[182:185], v[198:201], v[96:99]
	v_mfma_f32_16x16x32_bf16 v[84:87], v[174:177], v[214:217], v[84:87]
	v_mfma_f32_16x16x32_bf16 v[80:83], v[182:185], v[214:217], v[80:83]
	v_mfma_f32_16x16x32_bf16 v[68:71], v[174:177], v[228:231], v[68:71]
	v_mfma_f32_16x16x32_bf16 v[64:67], v[182:185], v[228:231], v[64:67]
	s_setprio 0
	s_barrier
	s_add_i32 s22, s30, s54
	v_lshl_add_u64 v[206:207], s[44:45], 0, v[208:209]
	s_mov_b32 m0, s22
	ds_read_b128 v[186:189], v173 offset:16384
	ds_read_b128 v[190:193], v173 offset:17408
	ds_read_b128 v[194:197], v173 offset:18432
	ds_read_b128 v[198:201], v173 offset:19456
	ds_read_b128 v[202:205], v173 offset:20480
	ds_read_b128 v[214:217], v173 offset:21504
	ds_read_b128 v[224:227], v173 offset:22528
	ds_read_b128 v[228:231], v173 offset:23552
	global_load_lds_dwordx4 v[206:207], off
	s_add_i32 m0, s22, 0x2000
	s_add_u32 s22, s44, 0xb0000
	v_lshl_add_u64 v[232:233], s[44:45], 0, v[128:129]
	s_addc_u32 s23, s45, 0
	s_add_i32 s30, s31, s54
	global_load_lds_dwordx4 v[232:233], off
	s_mov_b32 m0, s30
	v_lshl_add_u64 v[238:239], s[46:47], 0, v[128:129]
	global_load_lds_dwordx4 v208, s[22:23]
	s_add_i32 m0, s30, 0x2000
	s_nop 0
	global_load_lds_dwordx4 v128, s[22:23]
	v_lshl_add_u64 v[234:235], s[46:47], 0, v[208:209]
	s_mov_b32 m0, s55
	s_nop 0
	global_load_lds_dwordx4 v[234:235], off
	s_mov_b32 m0, s60
	s_nop 0
	global_load_lds_dwordx4 v[238:239], off
	s_waitcnt vmcnt(8)
	s_waitcnt lgkmcnt(0)
	s_barrier
	s_setprio 1
	s_waitcnt lgkmcnt(0)
	v_mfma_f32_16x16x32_bf16 v[60:63], v[150:153], v[186:189], v[60:63]
	v_mfma_f32_16x16x32_bf16 v[56:59], v[158:161], v[186:189], v[56:59]
	v_mfma_f32_16x16x32_bf16 v[44:47], v[150:153], v[194:197], v[44:47]
	v_mfma_f32_16x16x32_bf16 v[40:43], v[158:161], v[194:197], v[40:43]
	v_mfma_f32_16x16x32_bf16 v[28:31], v[150:153], v[202:205], v[28:31]
	v_mfma_f32_16x16x32_bf16 v[24:27], v[158:161], v[202:205], v[24:27]
	v_mfma_f32_16x16x32_bf16 v[12:15], v[150:153], v[224:227], v[12:15]
	v_mfma_f32_16x16x32_bf16 v[8:11], v[158:161], v[224:227], v[8:11]
	v_mfma_f32_16x16x32_bf16 v[60:63], v[154:157], v[190:193], v[60:63]
	v_mfma_f32_16x16x32_bf16 v[56:59], v[162:165], v[190:193], v[56:59]
	v_mfma_f32_16x16x32_bf16 v[44:47], v[154:157], v[198:201], v[44:47]
	v_mfma_f32_16x16x32_bf16 v[40:43], v[162:165], v[198:201], v[40:43]
	v_mfma_f32_16x16x32_bf16 v[28:31], v[154:157], v[214:217], v[28:31]
	v_mfma_f32_16x16x32_bf16 v[24:27], v[162:165], v[214:217], v[24:27]
	v_mfma_f32_16x16x32_bf16 v[12:15], v[154:157], v[228:231], v[12:15]
	v_mfma_f32_16x16x32_bf16 v[8:11], v[162:165], v[228:231], v[8:11]
	s_setprio 0
	s_setprio 1
	v_mfma_f32_16x16x32_bf16 v[52:55], v[166:169], v[186:189], v[52:55]
	v_mfma_f32_16x16x32_bf16 v[48:51], v[178:181], v[186:189], v[48:51]
	v_mfma_f32_16x16x32_bf16 v[36:39], v[166:169], v[194:197], v[36:39]
	v_mfma_f32_16x16x32_bf16 v[32:35], v[178:181], v[194:197], v[32:35]
	v_mfma_f32_16x16x32_bf16 v[20:23], v[166:169], v[202:205], v[20:23]
	v_mfma_f32_16x16x32_bf16 v[16:19], v[178:181], v[202:205], v[16:19]
	v_mfma_f32_16x16x32_bf16 v[4:7], v[166:169], v[224:227], v[4:7]
	v_mfma_f32_16x16x32_bf16 v[0:3], v[178:181], v[224:227], v[0:3]
	v_mfma_f32_16x16x32_bf16 v[52:55], v[174:177], v[190:193], v[52:55]
	v_mfma_f32_16x16x32_bf16 v[48:51], v[182:185], v[190:193], v[48:51]
	v_mfma_f32_16x16x32_bf16 v[36:39], v[174:177], v[198:201], v[36:39]
	v_mfma_f32_16x16x32_bf16 v[32:35], v[182:185], v[198:201], v[32:35]
	v_mfma_f32_16x16x32_bf16 v[20:23], v[174:177], v[214:217], v[20:23]
	v_mfma_f32_16x16x32_bf16 v[16:19], v[182:185], v[214:217], v[16:19]
	v_mfma_f32_16x16x32_bf16 v[4:7], v[174:177], v[228:231], v[4:7]
	v_mfma_f32_16x16x32_bf16 v[0:3], v[182:185], v[228:231], v[0:3]
	s_setprio 0
	s_barrier
	s_add_i32 s30, 0, 0x18000
	s_add_i32 s31, 0, 0x1c000
	v_add_u32_e32 v162, s30, v171
	v_add_u32_e32 v182, s31, v171
	ds_read_b128 v[150:153], v162
	ds_read_b128 v[154:157], v162 offset:1024
	ds_read_b128 v[158:161], v162 offset:2048
	ds_read_b128 v[162:165], v162 offset:3072
	ds_read_b128 v[166:169], v182
	ds_read_b128 v[174:177], v182 offset:1024
	ds_read_b128 v[178:181], v182 offset:2048
	ds_read_b128 v[182:185], v182 offset:3072
	s_add_u32 s22, s46, 0xb0000
	s_addc_u32 s23, s47, 0
	s_mov_b32 m0, s61
	ds_read_b128 v[186:189], v173 offset:32768
	ds_read_b128 v[190:193], v173 offset:33792
	ds_read_b128 v[194:197], v173 offset:34816
	ds_read_b128 v[198:201], v173 offset:35840
	ds_read_b128 v[202:205], v173 offset:36864
	ds_read_b128 v[214:217], v173 offset:37888
	ds_read_b128 v[224:227], v173 offset:38912
	ds_read_b128 v[228:231], v173 offset:39936
	global_load_lds_dwordx4 v208, s[22:23]
	s_mov_b32 m0, s63
	s_nop 0
	global_load_lds_dwordx4 v128, s[22:23]
	s_waitcnt vmcnt(8)
	s_waitcnt lgkmcnt(0)
	s_barrier
	s_setprio 1
	s_waitcnt lgkmcnt(0)
	v_mfma_f32_16x16x32_bf16 v[124:127], v[150:153], v[186:189], v[124:127]
	v_mfma_f32_16x16x32_bf16 v[120:123], v[158:161], v[186:189], v[120:123]
	v_mfma_f32_16x16x32_bf16 v[108:111], v[150:153], v[194:197], v[108:111]
	v_mfma_f32_16x16x32_bf16 v[104:107], v[158:161], v[194:197], v[104:107]
	v_mfma_f32_16x16x32_bf16 v[92:95], v[150:153], v[202:205], v[92:95]
	v_mfma_f32_16x16x32_bf16 v[88:91], v[158:161], v[202:205], v[88:91]
	v_mfma_f32_16x16x32_bf16 v[76:79], v[150:153], v[224:227], v[76:79]
	v_mfma_f32_16x16x32_bf16 v[72:75], v[158:161], v[224:227], v[72:75]
	v_mfma_f32_16x16x32_bf16 v[124:127], v[154:157], v[190:193], v[124:127]
	v_mfma_f32_16x16x32_bf16 v[120:123], v[162:165], v[190:193], v[120:123]
	v_mfma_f32_16x16x32_bf16 v[108:111], v[154:157], v[198:201], v[108:111]
	v_mfma_f32_16x16x32_bf16 v[104:107], v[162:165], v[198:201], v[104:107]
	v_mfma_f32_16x16x32_bf16 v[92:95], v[154:157], v[214:217], v[92:95]
	v_mfma_f32_16x16x32_bf16 v[88:91], v[162:165], v[214:217], v[88:91]
	v_mfma_f32_16x16x32_bf16 v[76:79], v[154:157], v[228:231], v[76:79]
	v_mfma_f32_16x16x32_bf16 v[72:75], v[162:165], v[228:231], v[72:75]
	s_setprio 0
	s_setprio 1
	v_mfma_f32_16x16x32_bf16 v[116:119], v[166:169], v[186:189], v[116:119]
	v_mfma_f32_16x16x32_bf16 v[112:115], v[178:181], v[186:189], v[112:115]
	v_mfma_f32_16x16x32_bf16 v[100:103], v[166:169], v[194:197], v[100:103]
	v_mfma_f32_16x16x32_bf16 v[96:99], v[178:181], v[194:197], v[96:99]
	v_mfma_f32_16x16x32_bf16 v[84:87], v[166:169], v[202:205], v[84:87]
	v_mfma_f32_16x16x32_bf16 v[80:83], v[178:181], v[202:205], v[80:83]
	v_mfma_f32_16x16x32_bf16 v[68:71], v[166:169], v[224:227], v[68:71]
	v_mfma_f32_16x16x32_bf16 v[64:67], v[178:181], v[224:227], v[64:67]
	v_mfma_f32_16x16x32_bf16 v[116:119], v[174:177], v[190:193], v[116:119]
	v_mfma_f32_16x16x32_bf16 v[112:115], v[182:185], v[190:193], v[112:115]
	v_mfma_f32_16x16x32_bf16 v[100:103], v[174:177], v[198:201], v[100:103]
	v_mfma_f32_16x16x32_bf16 v[96:99], v[182:185], v[198:201], v[96:99]
	v_mfma_f32_16x16x32_bf16 v[84:87], v[174:177], v[214:217], v[84:87]
	v_mfma_f32_16x16x32_bf16 v[80:83], v[182:185], v[214:217], v[80:83]
	v_mfma_f32_16x16x32_bf16 v[68:71], v[174:177], v[228:231], v[68:71]
	v_mfma_f32_16x16x32_bf16 v[64:67], v[182:185], v[228:231], v[64:67]
	s_setprio 0
	s_barrier
	s_add_i32 s22, s30, s54
	v_lshl_add_u64 v[206:207], v[206:207], 0, s[92:93]
	s_mov_b32 m0, s22
	ds_read_b128 v[186:189], v173 offset:49152
	ds_read_b128 v[190:193], v173 offset:50176
	ds_read_b128 v[194:197], v173 offset:51200
	ds_read_b128 v[198:201], v173 offset:52224
	ds_read_b128 v[202:205], v173 offset:53248
	ds_read_b128 v[214:217], v173 offset:54272
	ds_read_b128 v[224:227], v173 offset:55296
	ds_read_b128 v[228:231], v173 offset:56320
	global_load_lds_dwordx4 v[206:207], off
	s_add_i32 m0, s22, 0x2000
	s_add_u32 s22, s44, 0xb0080
	v_lshl_add_u64 v[206:207], v[232:233], 0, s[92:93]
	s_addc_u32 s23, s45, 0
	s_add_i32 s30, s31, s54
	global_load_lds_dwordx4 v[206:207], off
	s_mov_b32 m0, s30
	s_nop 0
	global_load_lds_dwordx4 v208, s[22:23]
	s_add_i32 m0, s30, 0x2000
	s_nop 0
	global_load_lds_dwordx4 v128, s[22:23]
	v_lshl_add_u64 v[206:207], v[234:235], 0, s[92:93]
	s_mov_b32 m0, s75
	s_nop 0
	global_load_lds_dwordx4 v[206:207], off
	v_lshl_add_u64 v[206:207], v[238:239], 0, s[92:93]
	s_mov_b32 m0, s4
	s_nop 0
	global_load_lds_dwordx4 v[206:207], off
	s_waitcnt vmcnt(8)
	s_waitcnt lgkmcnt(0)
	s_barrier
	s_setprio 1
	s_waitcnt lgkmcnt(0)
	v_mfma_f32_16x16x32_bf16 v[60:63], v[150:153], v[186:189], v[60:63]
	v_mfma_f32_16x16x32_bf16 v[56:59], v[158:161], v[186:189], v[56:59]
	v_mfma_f32_16x16x32_bf16 v[44:47], v[150:153], v[194:197], v[44:47]
	v_mfma_f32_16x16x32_bf16 v[40:43], v[158:161], v[194:197], v[40:43]
	v_mfma_f32_16x16x32_bf16 v[28:31], v[150:153], v[202:205], v[28:31]
	v_mfma_f32_16x16x32_bf16 v[24:27], v[158:161], v[202:205], v[24:27]
	v_mfma_f32_16x16x32_bf16 v[12:15], v[150:153], v[224:227], v[12:15]
	v_mfma_f32_16x16x32_bf16 v[8:11], v[158:161], v[224:227], v[8:11]
	v_mfma_f32_16x16x32_bf16 v[60:63], v[154:157], v[190:193], v[60:63]
	v_mfma_f32_16x16x32_bf16 v[56:59], v[162:165], v[190:193], v[56:59]
	v_mfma_f32_16x16x32_bf16 v[44:47], v[154:157], v[198:201], v[44:47]
	v_mfma_f32_16x16x32_bf16 v[40:43], v[162:165], v[198:201], v[40:43]
	v_mfma_f32_16x16x32_bf16 v[28:31], v[154:157], v[214:217], v[28:31]
	v_mfma_f32_16x16x32_bf16 v[24:27], v[162:165], v[214:217], v[24:27]
	v_mfma_f32_16x16x32_bf16 v[12:15], v[154:157], v[228:231], v[12:15]
	v_mfma_f32_16x16x32_bf16 v[8:11], v[162:165], v[228:231], v[8:11]
	s_setprio 0
	s_setprio 1
	v_mfma_f32_16x16x32_bf16 v[52:55], v[166:169], v[186:189], v[52:55]
	v_mfma_f32_16x16x32_bf16 v[48:51], v[178:181], v[186:189], v[48:51]
	v_mfma_f32_16x16x32_bf16 v[36:39], v[166:169], v[194:197], v[36:39]
	v_mfma_f32_16x16x32_bf16 v[32:35], v[178:181], v[194:197], v[32:35]
	v_mfma_f32_16x16x32_bf16 v[20:23], v[166:169], v[202:205], v[20:23]
	v_mfma_f32_16x16x32_bf16 v[16:19], v[178:181], v[202:205], v[16:19]
	v_mfma_f32_16x16x32_bf16 v[4:7], v[166:169], v[224:227], v[4:7]
	v_mfma_f32_16x16x32_bf16 v[0:3], v[178:181], v[224:227], v[0:3]
	v_mfma_f32_16x16x32_bf16 v[52:55], v[174:177], v[190:193], v[52:55]
	v_mfma_f32_16x16x32_bf16 v[48:51], v[182:185], v[190:193], v[48:51]
	v_mfma_f32_16x16x32_bf16 v[36:39], v[174:177], v[198:201], v[36:39]
	v_mfma_f32_16x16x32_bf16 v[32:35], v[182:185], v[198:201], v[32:35]
	v_mfma_f32_16x16x32_bf16 v[20:23], v[174:177], v[214:217], v[20:23]
	v_mfma_f32_16x16x32_bf16 v[16:19], v[182:185], v[214:217], v[16:19]
	v_mfma_f32_16x16x32_bf16 v[4:7], v[174:177], v[228:231], v[4:7]
	v_mfma_f32_16x16x32_bf16 v[0:3], v[182:185], v[228:231], v[0:3]
	s_setprio 0
	s_barrier
	s_add_i32 s25, s25, 2
	s_add_u32 s1, s1, 0x100
	s_addc_u32 s24, s24, 0
	s_cmp_gt_u32 s25, 41
	s_mov_b64 s[22:23], s[42:43]
	s_cbranch_scc0 .LBB0_392
	s_and_b64 vcc, exec, s[36:37]
	s_cbranch_vccz .LBB0_395
	s_barrier

.LBB0_540:
	s_add_u32 s36, s6, 0x9600000
	s_addc_u32 s37, s7, 0
	s_add_u32 s38, s6, 0xb700000
	s_addc_u32 s39, s7, 0
	s_add_u32 s40, s6, 0xd800000
	s_addc_u32 s41, s7, 0
	s_add_u32 s42, s6, 0xf900000
	s_addc_u32 s43, s7, 0
	v_bfe_u32 v15, v14, 4, 2
	s_add_u32 s44, s6, 0x48000
	v_and_b32_e32 v154, 15, v14
	v_lshlrev_b32_e32 v16, 4, v15
	v_lshlrev_b32_e32 v14, 2, v14
	s_addc_u32 s45, s7, 0
	s_and_b32 s1, s5, 3
	v_lshl_or_b32 v16, v154, 6, v16
	s_lshl_b32 s5, s8, 13
	v_and_b32_e32 v14, 32, v14
	s_add_i32 m0, s60, 0x18000
	v_lshl_add_u64 v[6:7], v[6:7], 0, s[92:93]
	s_lshl_b32 s26, s8, 6
	v_bitop3_b32 v17, v16, s5, v14 bitop3:0xde
	s_lshl_b32 s5, s1, 12
	s_waitcnt vmcnt(2)
	s_barrier
	global_load_lds_dwordx4 v[6:7], off
	v_lshl_add_u64 v[4:5], v[4:5], 0, s[92:93]
	s_add_i32 m0, s60, 0x1a000
	s_add_i32 s27, s60, 0x8000
	s_add_i32 s74, s60, 0xa000
	global_load_lds_dwordx4 v[4:5], off
	v_lshl_add_u64 v[0:1], v[0:1], 0, s[92:93]
	s_mov_b32 m0, s27
	s_add_u32 s6, s22, 0x40080
	global_load_lds_dwordx4 v[0:1], off
	v_lshl_add_u64 v[0:1], v[2:3], 0, s[92:93]
	s_mov_b32 m0, s74
	s_addc_u32 s7, s23, 0
	global_load_lds_dwordx4 v[0:1], off
	s_add_i32 m0, s60, 0x1c000
	s_nop 0
	global_load_lds_dwordx4 v136, s[6:7]
	s_add_i32 m0, s60, 0x1e000
	s_cmpk_lt_u32 s4, 0x100
	global_load_lds_dwordx4 v138, s[6:7]
	v_lshlrev_b32_e32 v0, 14, v8
	v_and_b32_e32 v0, 0xffff8000, v0
	v_lshl_add_u32 v0, v9, 11, v0
	v_and_b32_e32 v1, 1, v8
	v_lshl_or_b32 v0, v1, 6, v0
	v_lshl_add_u32 v140, v10, 1, v0
	v_lshlrev_b32_e32 v0, 14, v11
	v_and_b32_e32 v0, 0xffff8000, v0
	s_waitcnt vmcnt(6)
	v_lshl_add_u32 v0, v12, 11, v0
	v_and_b32_e32 v1, 1, v11
	s_cselect_b64 s[46:47], -1, 0
	s_bitcmp0_b32 s4, 6
	v_lshlrev_b32_e32 v156, 2, v15
	v_lshl_or_b32 v0, v1, 6, v0
	v_bitop3_b32 v155, v16, s5, v14 bitop3:0xde
	s_mov_b32 s75, 0
	s_cselect_b64 s[6:7], -1, 0
	v_lshl_or_b32 v157, s1, 5, v156
	v_mov_b32_e32 v141, v209
	v_lshl_add_u32 v142, v13, 1, v0
	v_mov_b32_e32 v143, v209
	v_add_u32_e32 v158, 0, v17
	s_barrier
	s_branch .LBB0_543

.LBB0_550:
	s_add_u32 s22, s12, 0xfffc0080
	s_addc_u32 s23, s13, -1
	s_add_i32 s49, 0, 0x10000
	s_cmp_eq_u32 s34, 12
	s_cselect_b32 vcc_hi, s1, s23
	s_cselect_b32 vcc_lo, s4, s22
	s_cselect_b32 s23, s5, s25
	s_cselect_b32 s22, s11, s24
	s_add_i32 s51, 0, 0x14000
	v_add_u32_e32 v148, s49, v155
	v_add_u32_e32 v152, s51, v155
	ds_read_b128 v[128:131], v148
	ds_read_b128 v[132:135], v148 offset:1024
	ds_read_b128 v[144:147], v148 offset:2048
	ds_read_b128 v[148:151], v148 offset:3072
	ds_read_b128 v[160:163], v152
	ds_read_b128 v[164:167], v152 offset:1024
	ds_read_b128 v[168:171], v152 offset:2048
	ds_read_b128 v[172:175], v152 offset:3072
	s_add_i32 m0, s60, 0xc000
	ds_read_b128 v[176:179], v158
	ds_read_b128 v[180:183], v158 offset:1024
	ds_read_b128 v[184:187], v158 offset:2048
	ds_read_b128 v[188:191], v158 offset:3072
	ds_read_b128 v[192:195], v158 offset:4096
	ds_read_b128 v[196:199], v158 offset:5120
	ds_read_b128 v[200:203], v158 offset:6144
	ds_read_b128 v[204:207], v158 offset:7168
	global_load_lds_dwordx4 v140, s[12:13]
	s_add_i32 m0, s60, 0xe000
	s_nop 0
	global_load_lds_dwordx4 v142, s[12:13]
	s_waitcnt vmcnt(8)
	s_waitcnt lgkmcnt(0)
	s_barrier
	s_setprio 1
	s_waitcnt lgkmcnt(0)
	v_mfma_f32_16x16x32_bf16 v[124:127], v[128:131], v[176:179], v[124:127]
	v_mfma_f32_16x16x32_bf16 v[120:123], v[144:147], v[176:179], v[120:123]
	v_mfma_f32_16x16x32_bf16 v[108:111], v[128:131], v[184:187], v[108:111]
	v_mfma_f32_16x16x32_bf16 v[104:107], v[144:147], v[184:187], v[104:107]
	v_mfma_f32_16x16x32_bf16 v[92:95], v[128:131], v[192:195], v[92:95]
	v_mfma_f32_16x16x32_bf16 v[88:91], v[144:147], v[192:195], v[88:91]
	v_mfma_f32_16x16x32_bf16 v[76:79], v[128:131], v[200:203], v[76:79]
	v_mfma_f32_16x16x32_bf16 v[72:75], v[144:147], v[200:203], v[72:75]
	v_mfma_f32_16x16x32_bf16 v[124:127], v[132:135], v[180:183], v[124:127]
	v_mfma_f32_16x16x32_bf16 v[120:123], v[148:151], v[180:183], v[120:123]
	v_mfma_f32_16x16x32_bf16 v[108:111], v[132:135], v[188:191], v[108:111]
	v_mfma_f32_16x16x32_bf16 v[104:107], v[148:151], v[188:191], v[104:107]
	v_mfma_f32_16x16x32_bf16 v[92:95], v[132:135], v[196:199], v[92:95]
	v_mfma_f32_16x16x32_bf16 v[88:91], v[148:151], v[196:199], v[88:91]
	v_mfma_f32_16x16x32_bf16 v[76:79], v[132:135], v[204:207], v[76:79]
	v_mfma_f32_16x16x32_bf16 v[72:75], v[148:151], v[204:207], v[72:75]
	s_setprio 0
	s_setprio 1
	v_mfma_f32_16x16x32_bf16 v[116:119], v[160:163], v[176:179], v[116:119]
	v_mfma_f32_16x16x32_bf16 v[112:115], v[168:171], v[176:179], v[112:115]
	v_mfma_f32_16x16x32_bf16 v[100:103], v[160:163], v[184:187], v[100:103]
	v_mfma_f32_16x16x32_bf16 v[96:99], v[168:171], v[184:187], v[96:99]
	v_mfma_f32_16x16x32_bf16 v[84:87], v[160:163], v[192:195], v[84:87]
	v_mfma_f32_16x16x32_bf16 v[80:83], v[168:171], v[192:195], v[80:83]
	v_mfma_f32_16x16x32_bf16 v[68:71], v[160:163], v[200:203], v[68:71]
	v_mfma_f32_16x16x32_bf16 v[64:67], v[168:171], v[200:203], v[64:67]
	v_mfma_f32_16x16x32_bf16 v[116:119], v[164:167], v[180:183], v[116:119]
	v_mfma_f32_16x16x32_bf16 v[112:115], v[172:175], v[180:183], v[112:115]
	v_mfma_f32_16x16x32_bf16 v[100:103], v[164:167], v[188:191], v[100:103]
	v_mfma_f32_16x16x32_bf16 v[96:99], v[172:175], v[188:191], v[96:99]
	v_mfma_f32_16x16x32_bf16 v[84:87], v[164:167], v[196:199], v[84:87]
	v_mfma_f32_16x16x32_bf16 v[80:83], v[172:175], v[196:199], v[80:83]
	v_mfma_f32_16x16x32_bf16 v[68:71], v[164:167], v[204:207], v[68:71]
	v_mfma_f32_16x16x32_bf16 v[64:67], v[172:175], v[204:207], v[64:67]
	s_setprio 0
	s_barrier
	s_add_i32 s49, s49, s55
	v_lshl_add_u64 v[152:153], s[22:23], 0, v[136:137]
	s_mov_b32 m0, s49
	ds_read_b128 v[176:179], v158 offset:16384
	ds_read_b128 v[180:183], v158 offset:17408
	ds_read_b128 v[184:187], v158 offset:18432
	ds_read_b128 v[188:191], v158 offset:19456
	ds_read_b128 v[192:195], v158 offset:20480
	ds_read_b128 v[196:199], v158 offset:21504
	ds_read_b128 v[200:203], v158 offset:22528
	ds_read_b128 v[204:207], v158 offset:23552
	global_load_lds_dwordx4 v[152:153], off
	s_add_i32 m0, s49, 0x2000
	s_add_u32 s68, s22, 0x40000
	v_lshl_add_u64 v[214:215], s[22:23], 0, v[138:139]
	s_addc_u32 s69, s23, 0
	s_add_i32 s49, s51, s55
	global_load_lds_dwordx4 v[214:215], off
	s_mov_b32 m0, s49
	v_lshl_add_u64 v[224:225], vcc, 0, v[138:139]
	global_load_lds_dwordx4 v136, s[68:69]
	s_add_i32 m0, s49, 0x2000
	s_nop 0
	global_load_lds_dwordx4 v138, s[68:69]
	v_lshl_add_u64 v[216:217], vcc, 0, v[136:137]
	s_mov_b32 m0, s60
	s_nop 0
	global_load_lds_dwordx4 v[216:217], off
	s_mov_b32 m0, s61
	s_nop 0
	global_load_lds_dwordx4 v[224:225], off
	s_waitcnt vmcnt(8)
	s_waitcnt lgkmcnt(0)
	s_barrier
	s_setprio 1
	s_waitcnt lgkmcnt(0)
	v_mfma_f32_16x16x32_bf16 v[60:63], v[128:131], v[176:179], v[60:63]
	v_mfma_f32_16x16x32_bf16 v[56:59], v[144:147], v[176:179], v[56:59]
	v_mfma_f32_16x16x32_bf16 v[44:47], v[128:131], v[184:187], v[44:47]
	v_mfma_f32_16x16x32_bf16 v[40:43], v[144:147], v[184:187], v[40:43]
	v_mfma_f32_16x16x32_bf16 v[28:31], v[128:131], v[192:195], v[28:31]
	v_mfma_f32_16x16x32_bf16 v[24:27], v[144:147], v[192:195], v[24:27]
	v_mfma_f32_16x16x32_bf16 v[12:15], v[128:131], v[200:203], v[12:15]
	v_mfma_f32_16x16x32_bf16 v[8:11], v[144:147], v[200:203], v[8:11]
	v_mfma_f32_16x16x32_bf16 v[60:63], v[132:135], v[180:183], v[60:63]
	v_mfma_f32_16x16x32_bf16 v[56:59], v[148:151], v[180:183], v[56:59]
	v_mfma_f32_16x16x32_bf16 v[44:47], v[132:135], v[188:191], v[44:47]
	v_mfma_f32_16x16x32_bf16 v[40:43], v[148:151], v[188:191], v[40:43]
	v_mfma_f32_16x16x32_bf16 v[28:31], v[132:135], v[196:199], v[28:31]
	v_mfma_f32_16x16x32_bf16 v[24:27], v[148:151], v[196:199], v[24:27]
	v_mfma_f32_16x16x32_bf16 v[12:15], v[132:135], v[204:207], v[12:15]
	v_mfma_f32_16x16x32_bf16 v[8:11], v[148:151], v[204:207], v[8:11]
	s_setprio 0
	s_setprio 1
	v_mfma_f32_16x16x32_bf16 v[52:55], v[160:163], v[176:179], v[52:55]
	v_mfma_f32_16x16x32_bf16 v[48:51], v[168:171], v[176:179], v[48:51]
	v_mfma_f32_16x16x32_bf16 v[36:39], v[160:163], v[184:187], v[36:39]
	v_mfma_f32_16x16x32_bf16 v[32:35], v[168:171], v[184:187], v[32:35]
	v_mfma_f32_16x16x32_bf16 v[20:23], v[160:163], v[192:195], v[20:23]
	v_mfma_f32_16x16x32_bf16 v[16:19], v[168:171], v[192:195], v[16:19]
	v_mfma_f32_16x16x32_bf16 v[4:7], v[160:163], v[200:203], v[4:7]
	v_mfma_f32_16x16x32_bf16 v[0:3], v[168:171], v[200:203], v[0:3]
	v_mfma_f32_16x16x32_bf16 v[52:55], v[164:167], v[180:183], v[52:55]
	v_mfma_f32_16x16x32_bf16 v[48:51], v[172:175], v[180:183], v[48:51]
	v_mfma_f32_16x16x32_bf16 v[36:39], v[164:167], v[188:191], v[36:39]
	v_mfma_f32_16x16x32_bf16 v[32:35], v[172:175], v[188:191], v[32:35]
	v_mfma_f32_16x16x32_bf16 v[20:23], v[164:167], v[196:199], v[20:23]
	v_mfma_f32_16x16x32_bf16 v[16:19], v[172:175], v[196:199], v[16:19]
	v_mfma_f32_16x16x32_bf16 v[4:7], v[164:167], v[204:207], v[4:7]
	v_mfma_f32_16x16x32_bf16 v[0:3], v[172:175], v[204:207], v[0:3]
	s_setprio 0
	s_barrier
	s_add_i32 s49, 0, 0x18000
	s_add_i32 s51, 0, 0x1c000
	v_add_u32_e32 v148, s49, v155
	v_add_u32_e32 v159, s51, v155
	ds_read_b128 v[128:131], v148
	ds_read_b128 v[132:135], v148 offset:1024
	ds_read_b128 v[144:147], v148 offset:2048
	ds_read_b128 v[148:151], v148 offset:3072
	ds_read_b128 v[160:163], v159
	ds_read_b128 v[164:167], v159 offset:1024
	ds_read_b128 v[168:171], v159 offset:2048
	ds_read_b128 v[172:175], v159 offset:3072
	s_add_u32 s68, vcc_lo, 0x40000
	s_addc_u32 s69, vcc_hi, 0
	s_mov_b32 m0, s63
	ds_read_b128 v[176:179], v158 offset:32768
	ds_read_b128 v[180:183], v158 offset:33792
	ds_read_b128 v[184:187], v158 offset:34816
	ds_read_b128 v[188:191], v158 offset:35840
	ds_read_b128 v[192:195], v158 offset:36864
	ds_read_b128 v[196:199], v158 offset:37888
	ds_read_b128 v[200:203], v158 offset:38912
	ds_read_b128 v[204:207], v158 offset:39936
	global_load_lds_dwordx4 v136, s[68:69]
	s_mov_b32 m0, s67
	s_nop 0
	global_load_lds_dwordx4 v138, s[68:69]
	s_waitcnt vmcnt(8)
	s_waitcnt lgkmcnt(0)
	s_barrier
	s_setprio 1
	s_waitcnt lgkmcnt(0)
	v_mfma_f32_16x16x32_bf16 v[124:127], v[128:131], v[176:179], v[124:127]
	v_mfma_f32_16x16x32_bf16 v[120:123], v[144:147], v[176:179], v[120:123]
	v_mfma_f32_16x16x32_bf16 v[108:111], v[128:131], v[184:187], v[108:111]
	v_mfma_f32_16x16x32_bf16 v[104:107], v[144:147], v[184:187], v[104:107]
	v_mfma_f32_16x16x32_bf16 v[92:95], v[128:131], v[192:195], v[92:95]
	v_mfma_f32_16x16x32_bf16 v[88:91], v[144:147], v[192:195], v[88:91]
	v_mfma_f32_16x16x32_bf16 v[76:79], v[128:131], v[200:203], v[76:79]
	v_mfma_f32_16x16x32_bf16 v[72:75], v[144:147], v[200:203], v[72:75]
	v_mfma_f32_16x16x32_bf16 v[124:127], v[132:135], v[180:183], v[124:127]
	v_mfma_f32_16x16x32_bf16 v[120:123], v[148:151], v[180:183], v[120:123]
	v_mfma_f32_16x16x32_bf16 v[108:111], v[132:135], v[188:191], v[108:111]
	v_mfma_f32_16x16x32_bf16 v[104:107], v[148:151], v[188:191], v[104:107]
	v_mfma_f32_16x16x32_bf16 v[92:95], v[132:135], v[196:199], v[92:95]
	v_mfma_f32_16x16x32_bf16 v[88:91], v[148:151], v[196:199], v[88:91]
	v_mfma_f32_16x16x32_bf16 v[76:79], v[132:135], v[204:207], v[76:79]
	v_mfma_f32_16x16x32_bf16 v[72:75], v[148:151], v[204:207], v[72:75]
	s_setprio 0
	s_setprio 1
	v_mfma_f32_16x16x32_bf16 v[116:119], v[160:163], v[176:179], v[116:119]
	v_mfma_f32_16x16x32_bf16 v[112:115], v[168:171], v[176:179], v[112:115]
	v_mfma_f32_16x16x32_bf16 v[100:103], v[160:163], v[184:187], v[100:103]
	v_mfma_f32_16x16x32_bf16 v[96:99], v[168:171], v[184:187], v[96:99]
	v_mfma_f32_16x16x32_bf16 v[84:87], v[160:163], v[192:195], v[84:87]
	v_mfma_f32_16x16x32_bf16 v[80:83], v[168:171], v[192:195], v[80:83]
	v_mfma_f32_16x16x32_bf16 v[68:71], v[160:163], v[200:203], v[68:71]
	v_mfma_f32_16x16x32_bf16 v[64:67], v[168:171], v[200:203], v[64:67]
	v_mfma_f32_16x16x32_bf16 v[116:119], v[164:167], v[180:183], v[116:119]
	v_mfma_f32_16x16x32_bf16 v[112:115], v[172:175], v[180:183], v[112:115]
	v_mfma_f32_16x16x32_bf16 v[100:103], v[164:167], v[188:191], v[100:103]
	v_mfma_f32_16x16x32_bf16 v[96:99], v[172:175], v[188:191], v[96:99]
	v_mfma_f32_16x16x32_bf16 v[84:87], v[164:167], v[196:199], v[84:87]
	v_mfma_f32_16x16x32_bf16 v[80:83], v[172:175], v[196:199], v[80:83]
	v_mfma_f32_16x16x32_bf16 v[68:71], v[164:167], v[204:207], v[68:71]
	v_mfma_f32_16x16x32_bf16 v[64:67], v[172:175], v[204:207], v[64:67]
	s_setprio 0
	s_barrier
	s_add_i32 s49, s49, s55
	v_lshl_add_u64 v[152:153], v[152:153], 0, s[92:93]
	s_mov_b32 m0, s49
	ds_read_b128 v[176:179], v158 offset:49152
	ds_read_b128 v[180:183], v158 offset:50176
	ds_read_b128 v[184:187], v158 offset:51200
	ds_read_b128 v[188:191], v158 offset:52224
	ds_read_b128 v[192:195], v158 offset:53248
	ds_read_b128 v[196:199], v158 offset:54272
	ds_read_b128 v[200:203], v158 offset:55296
	ds_read_b128 v[204:207], v158 offset:56320
	global_load_lds_dwordx4 v[152:153], off
	s_add_i32 m0, s49, 0x2000
	s_add_u32 s22, s22, 0x40080
	v_lshl_add_u64 v[152:153], v[214:215], 0, s[92:93]
	s_addc_u32 s23, s23, 0
	s_add_i32 s49, s51, s55
	global_load_lds_dwordx4 v[152:153], off
	s_mov_b32 m0, s49
	s_nop 0
	global_load_lds_dwordx4 v136, s[22:23]
	s_add_i32 m0, s49, 0x2000
	s_nop 0
	global_load_lds_dwordx4 v138, s[22:23]
	v_lshl_add_u64 v[152:153], v[216:217], 0, s[92:93]
	s_mov_b32 m0, s27
	s_nop 0
	global_load_lds_dwordx4 v[152:153], off
	v_lshl_add_u64 v[152:153], v[224:225], 0, s[92:93]
	s_mov_b32 m0, s74
	s_nop 0
	global_load_lds_dwordx4 v[152:153], off
	s_waitcnt vmcnt(8)
	s_waitcnt lgkmcnt(0)
	s_barrier
	s_setprio 1
	s_waitcnt lgkmcnt(0)
	v_mfma_f32_16x16x32_bf16 v[60:63], v[128:131], v[176:179], v[60:63]
	v_mfma_f32_16x16x32_bf16 v[56:59], v[144:147], v[176:179], v[56:59]
	v_mfma_f32_16x16x32_bf16 v[44:47], v[128:131], v[184:187], v[44:47]
	v_mfma_f32_16x16x32_bf16 v[40:43], v[144:147], v[184:187], v[40:43]
	v_mfma_f32_16x16x32_bf16 v[28:31], v[128:131], v[192:195], v[28:31]
	v_mfma_f32_16x16x32_bf16 v[24:27], v[144:147], v[192:195], v[24:27]
	v_mfma_f32_16x16x32_bf16 v[12:15], v[128:131], v[200:203], v[12:15]
	v_mfma_f32_16x16x32_bf16 v[8:11], v[144:147], v[200:203], v[8:11]
	v_mfma_f32_16x16x32_bf16 v[60:63], v[132:135], v[180:183], v[60:63]
	v_mfma_f32_16x16x32_bf16 v[56:59], v[148:151], v[180:183], v[56:59]
	v_mfma_f32_16x16x32_bf16 v[44:47], v[132:135], v[188:191], v[44:47]
	v_mfma_f32_16x16x32_bf16 v[40:43], v[148:151], v[188:191], v[40:43]
	v_mfma_f32_16x16x32_bf16 v[28:31], v[132:135], v[196:199], v[28:31]
	v_mfma_f32_16x16x32_bf16 v[24:27], v[148:151], v[196:199], v[24:27]
	v_mfma_f32_16x16x32_bf16 v[12:15], v[132:135], v[204:207], v[12:15]
	v_mfma_f32_16x16x32_bf16 v[8:11], v[148:151], v[204:207], v[8:11]
	s_setprio 0
	s_setprio 1
	v_mfma_f32_16x16x32_bf16 v[52:55], v[160:163], v[176:179], v[52:55]
	v_mfma_f32_16x16x32_bf16 v[48:51], v[168:171], v[176:179], v[48:51]
	v_mfma_f32_16x16x32_bf16 v[36:39], v[160:163], v[184:187], v[36:39]
	v_mfma_f32_16x16x32_bf16 v[32:35], v[168:171], v[184:187], v[32:35]
	v_mfma_f32_16x16x32_bf16 v[20:23], v[160:163], v[192:195], v[20:23]
	v_mfma_f32_16x16x32_bf16 v[16:19], v[168:171], v[192:195], v[16:19]
	v_mfma_f32_16x16x32_bf16 v[4:7], v[160:163], v[200:203], v[4:7]
	v_mfma_f32_16x16x32_bf16 v[0:3], v[168:171], v[200:203], v[0:3]
	v_mfma_f32_16x16x32_bf16 v[52:55], v[164:167], v[180:183], v[52:55]
	v_mfma_f32_16x16x32_bf16 v[48:51], v[172:175], v[180:183], v[48:51]
	v_mfma_f32_16x16x32_bf16 v[36:39], v[164:167], v[188:191], v[36:39]
	v_mfma_f32_16x16x32_bf16 v[32:35], v[172:175], v[188:191], v[32:35]
	v_mfma_f32_16x16x32_bf16 v[20:23], v[164:167], v[196:199], v[20:23]
	v_mfma_f32_16x16x32_bf16 v[16:19], v[172:175], v[196:199], v[16:19]
	v_mfma_f32_16x16x32_bf16 v[4:7], v[164:167], v[204:207], v[4:7]
	v_mfma_f32_16x16x32_bf16 v[0:3], v[172:175], v[204:207], v[0:3]
	s_setprio 0
	s_barrier
	s_add_i32 s34, s34, 2
	s_add_u32 s12, s12, 0x100
	s_addc_u32 s13, s13, 0
	s_add_u32 s24, s24, 0x100
	s_addc_u32 s25, s25, 0
	s_cmp_gt_u32 s34, 13
	s_cbranch_scc0 .LBB0_550
	s_and_b64 vcc, exec, s[46:47]
	s_cbranch_vccz .LBB0_553
	s_barrier

.LBB0_983:
	v_lshrrev_b32_e32 v16, 1, v14
	s_add_u32 s38, s14, 0xb700000
	v_and_b32_e32 v16, 24, v16
	s_addc_u32 s39, s15, 0
	v_and_b32_e32 v15, 15, v14
	v_lshlrev_b32_e32 v17, 1, v16
	v_lshlrev_b32_e32 v14, 2, v14
	s_lshl_b32 s5, s5, 5
	v_lshl_or_b32 v151, s8, 6, v15
	v_lshl_or_b32 v15, v15, 6, v17
	s_lshl_b32 s8, s8, 13
	v_and_b32_e32 v14, 32, v14
	s_and_b32 s5, s5, 0x60
	s_add_i32 m0, s55, 0x18000
	v_lshl_add_u64 v[6:7], v[6:7], 0, s[92:93]
	v_bitop3_b32 v17, v15, s8, v14 bitop3:0xde
	s_lshl_b32 s8, s5, 7
	s_waitcnt vmcnt(2)
	s_barrier
	global_load_lds_dwordx4 v[6:7], off
	v_lshl_add_u64 v[4:5], v[4:5], 0, s[92:93]
	s_add_i32 m0, s55, 0x1a000
	s_add_i32 s70, s55, 0x8000
	s_add_i32 s71, s55, 0xa000
	v_bitop3_b32 v152, v15, s8, v14 bitop3:0xde
	global_load_lds_dwordx4 v[4:5], off
	v_lshl_add_u64 v[0:1], v[0:1], 0, s[92:93]
	s_mov_b32 m0, s70
	s_add_u32 s8, s22, 0x40080
	global_load_lds_dwordx4 v[0:1], off
	v_lshl_add_u64 v[0:1], v[2:3], 0, s[92:93]
	s_mov_b32 m0, s71
	s_addc_u32 s9, s23, 0
	global_load_lds_dwordx4 v[0:1], off
	s_add_i32 m0, s55, 0x1c000
	s_nop 0
	global_load_lds_dwordx4 v208, s[8:9]
	s_add_i32 m0, s55, 0x1e000
	s_cmpk_lt_u32 s4, 0x100
	global_load_lds_dwordx4 v136, s[8:9]
	v_lshlrev_b32_e32 v0, 14, v12
	v_and_b32_e32 v0, 0xffff8000, v0
	v_lshl_add_u32 v0, v11, 11, v0
	v_and_b32_e32 v1, 1, v12
	v_lshl_or_b32 v0, v1, 6, v0
	v_lshl_add_u32 v142, v13, 1, v0
	v_lshlrev_b32_e32 v0, 14, v8
	v_and_b32_e32 v0, 0xffff8000, v0
	s_waitcnt vmcnt(6)
	v_lshl_add_u32 v0, v9, 11, v0
	v_and_b32_e32 v1, 1, v8
	v_lshl_or_b32 v0, v1, 6, v0
	v_readlane_b32 s8, v253, 35
	s_cselect_b64 s[40:41], -1, 0
	v_or_b32_e32 v153, s5, v16
	v_mov_b32_e32 v143, v209
	v_lshl_add_u32 v144, v10, 1, v0
	v_mov_b32_e32 v145, v209
	s_mov_b32 s72, 0
	v_add_u32_e32 v154, 0, v17
	v_readlane_b32 s4, v253, 37
	s_mov_b32 s5, s8
	s_barrier
	v_readlane_b32 s9, v253, 36
	s_branch .LBB0_986

.LBB0_993:
	s_add_u32 s22, s0, 0xfffc0080
	s_addc_u32 s23, s1, -1
	s_add_i32 s69, 0, 0x10000
	s_cmp_eq_u32 s68, 12
	s_cselect_b32 s51, s24, s23
	s_cselect_b32 s50, s25, s22
	v_add_u32_e32 v155, s69, v152
	s_cselect_b32 s23, s34, s66
	s_cselect_b32 s22, s43, s45
	s_add_i32 s73, 0, 0x14000
	ds_read_b128 v[104:107], v155
	ds_read_b128 v[108:111], v155 offset:1024
	ds_read_b128 v[146:149], v155 offset:2048
	ds_read_b128 v[156:159], v155 offset:3072
	v_add_u32_e32 v155, s73, v152
	ds_read_b128 v[160:163], v155
	ds_read_b128 v[164:167], v155 offset:1024
	ds_read_b128 v[168:171], v155 offset:2048
	ds_read_b128 v[172:175], v155 offset:3072
	s_add_i32 m0, s55, 0xc000
	ds_read_b128 v[176:179], v154
	ds_read_b128 v[180:183], v154 offset:1024
	ds_read_b128 v[184:187], v154 offset:2048
	ds_read_b128 v[188:191], v154 offset:3072
	ds_read_b128 v[192:195], v154 offset:4096
	ds_read_b128 v[196:199], v154 offset:5120
	ds_read_b128 v[200:203], v154 offset:6144
	ds_read_b128 v[204:207], v154 offset:7168
	global_load_lds_dwordx4 v142, s[0:1]
	s_add_i32 m0, s55, 0xe000
	s_nop 0
	global_load_lds_dwordx4 v144, s[0:1]
	s_waitcnt vmcnt(8)
	s_waitcnt lgkmcnt(0)
	s_barrier
	s_setprio 1
	s_waitcnt lgkmcnt(0)
	v_mfma_f32_16x16x32_bf16 v[132:135], v[104:107], v[176:179], v[132:135]
	v_mfma_f32_16x16x32_bf16 v[128:131], v[146:149], v[176:179], v[128:131]
	v_mfma_f32_16x16x32_bf16 v[124:127], v[104:107], v[184:187], v[124:127]
	v_mfma_f32_16x16x32_bf16 v[120:123], v[146:149], v[184:187], v[120:123]
	v_mfma_f32_16x16x32_bf16 v[116:119], v[104:107], v[192:195], v[116:119]
	v_mfma_f32_16x16x32_bf16 v[112:115], v[146:149], v[192:195], v[112:115]
	v_mfma_f32_16x16x32_bf16 v[100:103], v[104:107], v[200:203], v[100:103]
	v_mfma_f32_16x16x32_bf16 v[96:99], v[146:149], v[200:203], v[96:99]
	v_mfma_f32_16x16x32_bf16 v[132:135], v[108:111], v[180:183], v[132:135]
	v_mfma_f32_16x16x32_bf16 v[128:131], v[156:159], v[180:183], v[128:131]
	v_mfma_f32_16x16x32_bf16 v[124:127], v[108:111], v[188:191], v[124:127]
	v_mfma_f32_16x16x32_bf16 v[120:123], v[156:159], v[188:191], v[120:123]
	v_mfma_f32_16x16x32_bf16 v[116:119], v[108:111], v[196:199], v[116:119]
	v_mfma_f32_16x16x32_bf16 v[112:115], v[156:159], v[196:199], v[112:115]
	v_mfma_f32_16x16x32_bf16 v[100:103], v[108:111], v[204:207], v[100:103]
	v_mfma_f32_16x16x32_bf16 v[96:99], v[156:159], v[204:207], v[96:99]
	s_setprio 0
	s_setprio 1
	v_mfma_f32_16x16x32_bf16 v[60:63], v[160:163], v[176:179], v[60:63]
	v_mfma_f32_16x16x32_bf16 v[56:59], v[168:171], v[176:179], v[56:59]
	v_mfma_f32_16x16x32_bf16 v[52:55], v[160:163], v[184:187], v[52:55]
	v_mfma_f32_16x16x32_bf16 v[48:51], v[168:171], v[184:187], v[48:51]
	v_mfma_f32_16x16x32_bf16 v[44:47], v[160:163], v[192:195], v[44:47]
	v_mfma_f32_16x16x32_bf16 v[40:43], v[168:171], v[192:195], v[40:43]
	v_mfma_f32_16x16x32_bf16 v[36:39], v[160:163], v[200:203], v[36:39]
	v_mfma_f32_16x16x32_bf16 v[32:35], v[168:171], v[200:203], v[32:35]
	v_mfma_f32_16x16x32_bf16 v[60:63], v[164:167], v[180:183], v[60:63]
	v_mfma_f32_16x16x32_bf16 v[56:59], v[172:175], v[180:183], v[56:59]
	v_mfma_f32_16x16x32_bf16 v[52:55], v[164:167], v[188:191], v[52:55]
	v_mfma_f32_16x16x32_bf16 v[48:51], v[172:175], v[188:191], v[48:51]
	v_mfma_f32_16x16x32_bf16 v[44:47], v[164:167], v[196:199], v[44:47]
	v_mfma_f32_16x16x32_bf16 v[40:43], v[172:175], v[196:199], v[40:43]
	v_mfma_f32_16x16x32_bf16 v[36:39], v[164:167], v[204:207], v[36:39]
	v_mfma_f32_16x16x32_bf16 v[32:35], v[172:175], v[204:207], v[32:35]
	s_setprio 0
	s_barrier
	s_add_i32 s69, s69, s54
	v_lshl_add_u64 v[214:215], s[22:23], 0, v[208:209]
	s_mov_b32 m0, s69
	ds_read_b128 v[176:179], v154 offset:16384
	ds_read_b128 v[180:183], v154 offset:17408
	ds_read_b128 v[184:187], v154 offset:18432
	ds_read_b128 v[188:191], v154 offset:19456
	ds_read_b128 v[192:195], v154 offset:20480
	ds_read_b128 v[196:199], v154 offset:21504
	ds_read_b128 v[200:203], v154 offset:22528
	ds_read_b128 v[204:207], v154 offset:23552
	global_load_lds_dwordx4 v[214:215], off
	s_add_i32 m0, s69, 0x2000
	s_add_u32 s74, s22, 0x40000
	v_lshl_add_u64 v[216:217], s[22:23], 0, v[136:137]
	s_addc_u32 s75, s23, 0
	s_add_i32 s69, s73, s54
	global_load_lds_dwordx4 v[216:217], off
	s_mov_b32 m0, s69
	v_lshl_add_u64 v[226:227], s[50:51], 0, v[138:139]
	global_load_lds_dwordx4 v208, s[74:75]
	s_add_i32 m0, s69, 0x2000
	s_nop 0
	global_load_lds_dwordx4 v136, s[74:75]
	v_lshl_add_u64 v[224:225], s[50:51], 0, v[140:141]
	s_mov_b32 m0, s55
	s_nop 0
	global_load_lds_dwordx4 v[224:225], off
	s_mov_b32 m0, s60
	s_nop 0
	global_load_lds_dwordx4 v[226:227], off
	s_waitcnt vmcnt(8)
	s_waitcnt lgkmcnt(0)
	s_barrier
	s_setprio 1
	s_waitcnt lgkmcnt(0)
	v_mfma_f32_16x16x32_bf16 v[92:95], v[104:107], v[176:179], v[92:95]
	v_mfma_f32_16x16x32_bf16 v[88:91], v[146:149], v[176:179], v[88:91]
	v_mfma_f32_16x16x32_bf16 v[84:87], v[104:107], v[184:187], v[84:87]
	v_mfma_f32_16x16x32_bf16 v[80:83], v[146:149], v[184:187], v[80:83]
	v_mfma_f32_16x16x32_bf16 v[76:79], v[104:107], v[192:195], v[76:79]
	v_mfma_f32_16x16x32_bf16 v[72:75], v[146:149], v[192:195], v[72:75]
	v_mfma_f32_16x16x32_bf16 v[68:71], v[104:107], v[200:203], v[68:71]
	v_mfma_f32_16x16x32_bf16 v[64:67], v[146:149], v[200:203], v[64:67]
	v_mfma_f32_16x16x32_bf16 v[92:95], v[108:111], v[180:183], v[92:95]
	v_mfma_f32_16x16x32_bf16 v[88:91], v[156:159], v[180:183], v[88:91]
	v_mfma_f32_16x16x32_bf16 v[84:87], v[108:111], v[188:191], v[84:87]
	v_mfma_f32_16x16x32_bf16 v[80:83], v[156:159], v[188:191], v[80:83]
	v_mfma_f32_16x16x32_bf16 v[76:79], v[108:111], v[196:199], v[76:79]
	v_mfma_f32_16x16x32_bf16 v[72:75], v[156:159], v[196:199], v[72:75]
	v_mfma_f32_16x16x32_bf16 v[68:71], v[108:111], v[204:207], v[68:71]
	v_mfma_f32_16x16x32_bf16 v[64:67], v[156:159], v[204:207], v[64:67]
	s_setprio 0
	s_setprio 1
	v_mfma_f32_16x16x32_bf16 v[28:31], v[160:163], v[176:179], v[28:31]
	v_mfma_f32_16x16x32_bf16 v[24:27], v[168:171], v[176:179], v[24:27]
	v_mfma_f32_16x16x32_bf16 v[20:23], v[160:163], v[184:187], v[20:23]
	v_mfma_f32_16x16x32_bf16 v[16:19], v[168:171], v[184:187], v[16:19]
	v_mfma_f32_16x16x32_bf16 v[12:15], v[160:163], v[192:195], v[12:15]
	v_mfma_f32_16x16x32_bf16 v[8:11], v[168:171], v[192:195], v[8:11]
	v_mfma_f32_16x16x32_bf16 v[4:7], v[160:163], v[200:203], v[4:7]
	v_mfma_f32_16x16x32_bf16 v[0:3], v[168:171], v[200:203], v[0:3]
	v_mfma_f32_16x16x32_bf16 v[28:31], v[164:167], v[180:183], v[28:31]
	v_mfma_f32_16x16x32_bf16 v[24:27], v[172:175], v[180:183], v[24:27]
	v_mfma_f32_16x16x32_bf16 v[20:23], v[164:167], v[188:191], v[20:23]
	v_mfma_f32_16x16x32_bf16 v[16:19], v[172:175], v[188:191], v[16:19]
	v_mfma_f32_16x16x32_bf16 v[12:15], v[164:167], v[196:199], v[12:15]
	v_mfma_f32_16x16x32_bf16 v[8:11], v[172:175], v[196:199], v[8:11]
	v_mfma_f32_16x16x32_bf16 v[4:7], v[164:167], v[204:207], v[4:7]
	v_mfma_f32_16x16x32_bf16 v[0:3], v[172:175], v[204:207], v[0:3]
	s_setprio 0
	s_barrier
	s_add_i32 s69, 0, 0x18000
	v_add_u32_e32 v155, s69, v152
	s_add_i32 s73, 0, 0x1c000
	ds_read_b128 v[104:107], v155
	ds_read_b128 v[108:111], v155 offset:1024
	ds_read_b128 v[146:149], v155 offset:2048
	ds_read_b128 v[156:159], v155 offset:3072
	v_add_u32_e32 v155, s73, v152
	ds_read_b128 v[160:163], v155
	ds_read_b128 v[164:167], v155 offset:1024
	ds_read_b128 v[168:171], v155 offset:2048
	ds_read_b128 v[172:175], v155 offset:3072
	s_add_u32 s50, s50, 0x40000
	s_addc_u32 s51, s51, 0
	s_mov_b32 m0, s61
	ds_read_b128 v[176:179], v154 offset:32768
	ds_read_b128 v[180:183], v154 offset:33792
	ds_read_b128 v[184:187], v154 offset:34816
	ds_read_b128 v[188:191], v154 offset:35840
	ds_read_b128 v[192:195], v154 offset:36864
	ds_read_b128 v[196:199], v154 offset:37888
	ds_read_b128 v[200:203], v154 offset:38912
	ds_read_b128 v[204:207], v154 offset:39936
	global_load_lds_dwordx4 v140, s[50:51]
	s_mov_b32 m0, s67
	s_nop 0
	global_load_lds_dwordx4 v138, s[50:51]
	s_waitcnt vmcnt(8)
	s_waitcnt lgkmcnt(0)
	s_barrier
	s_setprio 1
	s_waitcnt lgkmcnt(0)
	v_mfma_f32_16x16x32_bf16 v[132:135], v[104:107], v[176:179], v[132:135]
	v_mfma_f32_16x16x32_bf16 v[128:131], v[146:149], v[176:179], v[128:131]
	v_mfma_f32_16x16x32_bf16 v[124:127], v[104:107], v[184:187], v[124:127]
	v_mfma_f32_16x16x32_bf16 v[120:123], v[146:149], v[184:187], v[120:123]
	v_mfma_f32_16x16x32_bf16 v[116:119], v[104:107], v[192:195], v[116:119]
	v_mfma_f32_16x16x32_bf16 v[112:115], v[146:149], v[192:195], v[112:115]
	v_mfma_f32_16x16x32_bf16 v[100:103], v[104:107], v[200:203], v[100:103]
	v_mfma_f32_16x16x32_bf16 v[96:99], v[146:149], v[200:203], v[96:99]
	v_mfma_f32_16x16x32_bf16 v[132:135], v[108:111], v[180:183], v[132:135]
	v_mfma_f32_16x16x32_bf16 v[128:131], v[156:159], v[180:183], v[128:131]
	v_mfma_f32_16x16x32_bf16 v[124:127], v[108:111], v[188:191], v[124:127]
	v_mfma_f32_16x16x32_bf16 v[120:123], v[156:159], v[188:191], v[120:123]
	v_mfma_f32_16x16x32_bf16 v[116:119], v[108:111], v[196:199], v[116:119]
	v_mfma_f32_16x16x32_bf16 v[112:115], v[156:159], v[196:199], v[112:115]
	v_mfma_f32_16x16x32_bf16 v[100:103], v[108:111], v[204:207], v[100:103]
	v_mfma_f32_16x16x32_bf16 v[96:99], v[156:159], v[204:207], v[96:99]
	s_setprio 0
	s_setprio 1
	v_mfma_f32_16x16x32_bf16 v[60:63], v[160:163], v[176:179], v[60:63]
	v_mfma_f32_16x16x32_bf16 v[56:59], v[168:171], v[176:179], v[56:59]
	v_mfma_f32_16x16x32_bf16 v[52:55], v[160:163], v[184:187], v[52:55]
	v_mfma_f32_16x16x32_bf16 v[48:51], v[168:171], v[184:187], v[48:51]
	v_mfma_f32_16x16x32_bf16 v[44:47], v[160:163], v[192:195], v[44:47]
	v_mfma_f32_16x16x32_bf16 v[40:43], v[168:171], v[192:195], v[40:43]
	v_mfma_f32_16x16x32_bf16 v[36:39], v[160:163], v[200:203], v[36:39]
	v_mfma_f32_16x16x32_bf16 v[32:35], v[168:171], v[200:203], v[32:35]
	v_mfma_f32_16x16x32_bf16 v[60:63], v[164:167], v[180:183], v[60:63]
	v_mfma_f32_16x16x32_bf16 v[56:59], v[172:175], v[180:183], v[56:59]
	v_mfma_f32_16x16x32_bf16 v[52:55], v[164:167], v[188:191], v[52:55]
	v_mfma_f32_16x16x32_bf16 v[48:51], v[172:175], v[188:191], v[48:51]
	v_mfma_f32_16x16x32_bf16 v[44:47], v[164:167], v[196:199], v[44:47]
	v_mfma_f32_16x16x32_bf16 v[40:43], v[172:175], v[196:199], v[40:43]
	v_mfma_f32_16x16x32_bf16 v[36:39], v[164:167], v[204:207], v[36:39]
	v_mfma_f32_16x16x32_bf16 v[32:35], v[172:175], v[204:207], v[32:35]
	s_setprio 0
	s_barrier
	s_add_i32 s50, s69, s54
	v_lshl_add_u64 v[214:215], v[214:215], 0, s[92:93]
	s_mov_b32 m0, s50
	ds_read_b128 v[176:179], v154 offset:49152
	ds_read_b128 v[180:183], v154 offset:50176
	ds_read_b128 v[184:187], v154 offset:51200
	ds_read_b128 v[188:191], v154 offset:52224
	ds_read_b128 v[192:195], v154 offset:53248
	ds_read_b128 v[196:199], v154 offset:54272
	ds_read_b128 v[200:203], v154 offset:55296
	ds_read_b128 v[204:207], v154 offset:56320
	global_load_lds_dwordx4 v[214:215], off
	s_add_i32 m0, s50, 0x2000
	s_add_u32 s22, s22, 0x40080
	v_lshl_add_u64 v[214:215], v[216:217], 0, s[92:93]
	s_addc_u32 s23, s23, 0
	s_add_i32 s50, s73, s54
	global_load_lds_dwordx4 v[214:215], off
	s_mov_b32 m0, s50
	s_nop 0
	global_load_lds_dwordx4 v208, s[22:23]
	s_add_i32 m0, s50, 0x2000
	s_nop 0
	global_load_lds_dwordx4 v136, s[22:23]
	v_lshl_add_u64 v[214:215], v[224:225], 0, s[92:93]
	s_mov_b32 m0, s70
	s_nop 0
	global_load_lds_dwordx4 v[214:215], off
	v_lshl_add_u64 v[214:215], v[226:227], 0, s[92:93]
	s_mov_b32 m0, s71
	s_nop 0
	global_load_lds_dwordx4 v[214:215], off
	s_waitcnt vmcnt(8)
	s_waitcnt lgkmcnt(0)
	s_barrier
	s_setprio 1
	s_waitcnt lgkmcnt(0)
	v_mfma_f32_16x16x32_bf16 v[92:95], v[104:107], v[176:179], v[92:95]
	v_mfma_f32_16x16x32_bf16 v[88:91], v[146:149], v[176:179], v[88:91]
	v_mfma_f32_16x16x32_bf16 v[84:87], v[104:107], v[184:187], v[84:87]
	v_mfma_f32_16x16x32_bf16 v[80:83], v[146:149], v[184:187], v[80:83]
	v_mfma_f32_16x16x32_bf16 v[76:79], v[104:107], v[192:195], v[76:79]
	v_mfma_f32_16x16x32_bf16 v[72:75], v[146:149], v[192:195], v[72:75]
	v_mfma_f32_16x16x32_bf16 v[68:71], v[104:107], v[200:203], v[68:71]
	v_mfma_f32_16x16x32_bf16 v[64:67], v[146:149], v[200:203], v[64:67]
	v_mfma_f32_16x16x32_bf16 v[92:95], v[108:111], v[180:183], v[92:95]
	v_mfma_f32_16x16x32_bf16 v[88:91], v[156:159], v[180:183], v[88:91]
	v_mfma_f32_16x16x32_bf16 v[84:87], v[108:111], v[188:191], v[84:87]
	v_mfma_f32_16x16x32_bf16 v[80:83], v[156:159], v[188:191], v[80:83]
	v_mfma_f32_16x16x32_bf16 v[76:79], v[108:111], v[196:199], v[76:79]
	v_mfma_f32_16x16x32_bf16 v[72:75], v[156:159], v[196:199], v[72:75]
	v_mfma_f32_16x16x32_bf16 v[68:71], v[108:111], v[204:207], v[68:71]
	v_mfma_f32_16x16x32_bf16 v[64:67], v[156:159], v[204:207], v[64:67]
	s_setprio 0
	s_setprio 1
	v_mfma_f32_16x16x32_bf16 v[28:31], v[160:163], v[176:179], v[28:31]
	v_mfma_f32_16x16x32_bf16 v[24:27], v[168:171], v[176:179], v[24:27]
	v_mfma_f32_16x16x32_bf16 v[20:23], v[160:163], v[184:187], v[20:23]
	v_mfma_f32_16x16x32_bf16 v[16:19], v[168:171], v[184:187], v[16:19]
	v_mfma_f32_16x16x32_bf16 v[12:15], v[160:163], v[192:195], v[12:15]
	v_mfma_f32_16x16x32_bf16 v[8:11], v[168:171], v[192:195], v[8:11]
	v_mfma_f32_16x16x32_bf16 v[4:7], v[160:163], v[200:203], v[4:7]
	v_mfma_f32_16x16x32_bf16 v[0:3], v[168:171], v[200:203], v[0:3]
	v_mfma_f32_16x16x32_bf16 v[28:31], v[164:167], v[180:183], v[28:31]
	v_mfma_f32_16x16x32_bf16 v[24:27], v[172:175], v[180:183], v[24:27]
	v_mfma_f32_16x16x32_bf16 v[20:23], v[164:167], v[188:191], v[20:23]
	v_mfma_f32_16x16x32_bf16 v[16:19], v[172:175], v[188:191], v[16:19]
	v_mfma_f32_16x16x32_bf16 v[12:15], v[164:167], v[196:199], v[12:15]
	v_mfma_f32_16x16x32_bf16 v[8:11], v[172:175], v[196:199], v[8:11]
	v_mfma_f32_16x16x32_bf16 v[4:7], v[164:167], v[204:207], v[4:7]
	v_mfma_f32_16x16x32_bf16 v[0:3], v[172:175], v[204:207], v[0:3]
	s_setprio 0
	s_barrier
	s_add_i32 s68, s68, 2
	s_add_u32 s0, s0, 0x100
	s_addc_u32 s1, s1, 0
	s_add_u32 s45, s45, 0x100
	s_addc_u32 s66, s66, 0
	s_cmp_gt_u32 s68, 13
	s_cbranch_scc0 .LBB0_993
	s_and_b64 vcc, exec, s[40:41]
	s_cbranch_vccz .LBB0_996
	s_barrier

.LBB0_1016:
	v_bfe_u32 v15, v14, 4, 2
	v_and_b32_e32 v143, 15, v14
	v_lshlrev_b32_e32 v16, 4, v15
	v_lshlrev_b32_e32 v14, 2, v14
	s_and_b32 s11, s4, 3
	s_lshl_b32 s4, s5, 6
	v_lshl_or_b32 v16, v143, 6, v16
	s_lshl_b32 s5, s5, 13
	v_and_b32_e32 v14, 32, v14
	v_bitop3_b32 v17, v16, s5, v14 bitop3:0xde
	s_lshl_b32 s5, s11, 12
	s_add_u32 s38, s14, 0x9600000
	s_addc_u32 s39, s15, 0
	s_add_i32 m0, s50, 0x18000
	v_lshl_add_u64 v[6:7], v[6:7], 0, s[92:93]
	v_bitop3_b32 v144, v16, s5, v14 bitop3:0xde
	s_waitcnt vmcnt(2)
	s_barrier
	global_load_lds_dwordx4 v[6:7], off
	v_lshl_add_u64 v[4:5], v[4:5], 0, s[92:93]
	s_add_i32 m0, s50, 0x1a000
	s_add_i32 s5, s50, 0x8000
	s_add_i32 s60, s50, 0xa000
	global_load_lds_dwordx4 v[4:5], off
	v_lshl_add_u64 v[0:1], v[0:1], 0, s[92:93]
	s_mov_b32 m0, s5
	s_add_u32 s22, s12, 0x20080
	global_load_lds_dwordx4 v[0:1], off
	v_lshl_add_u64 v[0:1], v[2:3], 0, s[92:93]
	s_mov_b32 m0, s60
	s_addc_u32 s23, s13, 0
	global_load_lds_dwordx4 v[0:1], off
	s_add_i32 m0, s50, 0x1c000
	s_nop 0
	global_load_lds_dwordx4 v130, s[22:23]
	s_add_i32 m0, s50, 0x1e000
	s_cmpk_lt_u32 s10, 0x100
	global_load_lds_dwordx4 v128, s[22:23]
	v_lshlrev_b32_e32 v0, 13, v11
	v_and_b32_e32 v0, 0xffffc000, v0
	v_lshl_add_u32 v0, v12, 10, v0
	v_and_b32_e32 v1, 1, v11
	v_lshl_or_b32 v0, v1, 6, v0
	v_lshl_add_u32 v132, v13, 1, v0
	v_lshlrev_b32_e32 v0, 13, v8
	v_and_b32_e32 v0, 0xffffc000, v0
	s_waitcnt vmcnt(6)
	v_lshl_add_u32 v0, v9, 10, v0
	v_and_b32_e32 v1, 1, v8
	v_lshl_or_b32 v145, s11, 3, v15
	v_lshl_or_b32 v0, v1, 6, v0
	v_readlane_b32 s10, v252, 53
	s_cselect_b64 s[40:41], -1, 0
	v_mov_b32_e32 v133, v209
	v_lshl_add_u32 v134, v10, 1, v0
	v_mov_b32_e32 v135, v209
	s_mov_b32 s34, 0
	v_add_u32_e32 v146, 0, v17
	v_readlane_b32 s61, v252, 55
	s_mov_b32 s66, s10
	s_barrier
	v_readlane_b32 s11, v252, 54
	s_branch .LBB0_1019

.LBB0_1026:
	s_add_u32 s12, s0, 0xfffe0080
	s_addc_u32 s13, s1, -1
	s_add_i32 s72, 0, 0x10000
	s_cmp_eq_u32 s71, 4
	s_cselect_b32 s23, s45, s13
	s_cselect_b32 s22, s67, s12
	v_add_u32_e32 v140, s72, v144
	s_cselect_b32 s13, s43, s70
	s_cselect_b32 s12, s68, s69
	s_add_i32 s74, 0, 0x14000
	ds_read_b128 v[136:139], v140
	ds_read_b128 v[152:155], v140 offset:1024
	ds_read_b128 v[156:159], v140 offset:2048
	ds_read_b128 v[160:163], v140 offset:3072
	v_add_u32_e32 v140, s74, v144
	ds_read_b128 v[164:167], v140
	ds_read_b128 v[168:171], v140 offset:1024
	ds_read_b128 v[172:175], v140 offset:2048
	ds_read_b128 v[176:179], v140 offset:3072
	s_add_i32 m0, s50, 0xc000
	ds_read_b128 v[180:183], v146
	ds_read_b128 v[184:187], v146 offset:1024
	ds_read_b128 v[188:191], v146 offset:2048
	ds_read_b128 v[192:195], v146 offset:3072
	ds_read_b128 v[196:199], v146 offset:4096
	ds_read_b128 v[200:203], v146 offset:5120
	ds_read_b128 v[204:207], v146 offset:6144
	ds_read_b128 v[214:217], v146 offset:7168
	global_load_lds_dwordx4 v132, s[0:1]
	s_add_i32 m0, s50, 0xe000
	s_nop 0
	global_load_lds_dwordx4 v134, s[0:1]
	s_waitcnt vmcnt(8)
	s_waitcnt lgkmcnt(0)
	s_barrier
	s_setprio 1
	s_waitcnt lgkmcnt(0)
	v_mfma_f32_16x16x32_bf16 v[124:127], v[136:139], v[180:183], v[124:127]
	v_mfma_f32_16x16x32_bf16 v[120:123], v[156:159], v[180:183], v[120:123]
	v_mfma_f32_16x16x32_bf16 v[108:111], v[136:139], v[188:191], v[108:111]
	v_mfma_f32_16x16x32_bf16 v[104:107], v[156:159], v[188:191], v[104:107]
	v_mfma_f32_16x16x32_bf16 v[92:95], v[136:139], v[196:199], v[92:95]
	v_mfma_f32_16x16x32_bf16 v[88:91], v[156:159], v[196:199], v[88:91]
	v_mfma_f32_16x16x32_bf16 v[76:79], v[136:139], v[204:207], v[76:79]
	v_mfma_f32_16x16x32_bf16 v[72:75], v[156:159], v[204:207], v[72:75]
	v_mfma_f32_16x16x32_bf16 v[124:127], v[152:155], v[184:187], v[124:127]
	v_mfma_f32_16x16x32_bf16 v[120:123], v[160:163], v[184:187], v[120:123]
	v_mfma_f32_16x16x32_bf16 v[108:111], v[152:155], v[192:195], v[108:111]
	v_mfma_f32_16x16x32_bf16 v[104:107], v[160:163], v[192:195], v[104:107]
	v_mfma_f32_16x16x32_bf16 v[92:95], v[152:155], v[200:203], v[92:95]
	v_mfma_f32_16x16x32_bf16 v[88:91], v[160:163], v[200:203], v[88:91]
	v_mfma_f32_16x16x32_bf16 v[76:79], v[152:155], v[214:217], v[76:79]
	v_mfma_f32_16x16x32_bf16 v[72:75], v[160:163], v[214:217], v[72:75]
	s_setprio 0
	s_setprio 1
	v_mfma_f32_16x16x32_bf16 v[116:119], v[164:167], v[180:183], v[116:119]
	v_mfma_f32_16x16x32_bf16 v[112:115], v[172:175], v[180:183], v[112:115]
	v_mfma_f32_16x16x32_bf16 v[100:103], v[164:167], v[188:191], v[100:103]
	v_mfma_f32_16x16x32_bf16 v[96:99], v[172:175], v[188:191], v[96:99]
	v_mfma_f32_16x16x32_bf16 v[84:87], v[164:167], v[196:199], v[84:87]
	v_mfma_f32_16x16x32_bf16 v[80:83], v[172:175], v[196:199], v[80:83]
	v_mfma_f32_16x16x32_bf16 v[68:71], v[164:167], v[204:207], v[68:71]
	v_mfma_f32_16x16x32_bf16 v[64:67], v[172:175], v[204:207], v[64:67]
	v_mfma_f32_16x16x32_bf16 v[116:119], v[168:171], v[184:187], v[116:119]
	v_mfma_f32_16x16x32_bf16 v[112:115], v[176:179], v[184:187], v[112:115]
	v_mfma_f32_16x16x32_bf16 v[100:103], v[168:171], v[192:195], v[100:103]
	v_mfma_f32_16x16x32_bf16 v[96:99], v[176:179], v[192:195], v[96:99]
	v_mfma_f32_16x16x32_bf16 v[84:87], v[168:171], v[200:203], v[84:87]
	v_mfma_f32_16x16x32_bf16 v[80:83], v[176:179], v[200:203], v[80:83]
	v_mfma_f32_16x16x32_bf16 v[68:71], v[168:171], v[214:217], v[68:71]
	v_mfma_f32_16x16x32_bf16 v[64:67], v[176:179], v[214:217], v[64:67]
	s_setprio 0
	s_barrier
	s_add_i32 s72, s72, s27
	v_lshl_add_u64 v[140:141], s[12:13], 0, v[130:131]
	s_mov_b32 m0, s72
	ds_read_b128 v[180:183], v146 offset:16384
	ds_read_b128 v[184:187], v146 offset:17408
	ds_read_b128 v[188:191], v146 offset:18432
	ds_read_b128 v[192:195], v146 offset:19456
	ds_read_b128 v[196:199], v146 offset:20480
	ds_read_b128 v[200:203], v146 offset:21504
	ds_read_b128 v[204:207], v146 offset:22528
	ds_read_b128 v[214:217], v146 offset:23552
	global_load_lds_dwordx4 v[140:141], off
	s_add_i32 m0, s72, 0x2000
	s_add_u32 s72, s12, 0x20000
	v_lshl_add_u64 v[148:149], s[12:13], 0, v[128:129]
	s_addc_u32 s73, s13, 0
	s_add_i32 s74, s74, s27
	global_load_lds_dwordx4 v[148:149], off
	s_mov_b32 m0, s74
	v_lshl_add_u64 v[226:227], s[22:23], 0, v[128:129]
	global_load_lds_dwordx4 v130, s[72:73]
	s_add_i32 m0, s74, 0x2000
	s_nop 0
	global_load_lds_dwordx4 v128, s[72:73]
	v_lshl_add_u64 v[224:225], s[22:23], 0, v[130:131]
	s_mov_b32 m0, s50
	s_nop 0
	global_load_lds_dwordx4 v[224:225], off
	s_mov_b32 m0, s51
	s_nop 0
	global_load_lds_dwordx4 v[226:227], off
	s_waitcnt vmcnt(8)
	s_waitcnt lgkmcnt(0)
	s_barrier
	s_setprio 1
	s_waitcnt lgkmcnt(0)
	v_mfma_f32_16x16x32_bf16 v[60:63], v[136:139], v[180:183], v[60:63]
	v_mfma_f32_16x16x32_bf16 v[56:59], v[156:159], v[180:183], v[56:59]
	v_mfma_f32_16x16x32_bf16 v[44:47], v[136:139], v[188:191], v[44:47]
	v_mfma_f32_16x16x32_bf16 v[40:43], v[156:159], v[188:191], v[40:43]
	v_mfma_f32_16x16x32_bf16 v[28:31], v[136:139], v[196:199], v[28:31]
	v_mfma_f32_16x16x32_bf16 v[24:27], v[156:159], v[196:199], v[24:27]
	v_mfma_f32_16x16x32_bf16 v[12:15], v[136:139], v[204:207], v[12:15]
	v_mfma_f32_16x16x32_bf16 v[8:11], v[156:159], v[204:207], v[8:11]
	v_mfma_f32_16x16x32_bf16 v[60:63], v[152:155], v[184:187], v[60:63]
	v_mfma_f32_16x16x32_bf16 v[56:59], v[160:163], v[184:187], v[56:59]
	v_mfma_f32_16x16x32_bf16 v[44:47], v[152:155], v[192:195], v[44:47]
	v_mfma_f32_16x16x32_bf16 v[40:43], v[160:163], v[192:195], v[40:43]
	v_mfma_f32_16x16x32_bf16 v[28:31], v[152:155], v[200:203], v[28:31]
	v_mfma_f32_16x16x32_bf16 v[24:27], v[160:163], v[200:203], v[24:27]
	v_mfma_f32_16x16x32_bf16 v[12:15], v[152:155], v[214:217], v[12:15]
	v_mfma_f32_16x16x32_bf16 v[8:11], v[160:163], v[214:217], v[8:11]
	s_setprio 0
	s_setprio 1
	v_mfma_f32_16x16x32_bf16 v[52:55], v[164:167], v[180:183], v[52:55]
	v_mfma_f32_16x16x32_bf16 v[48:51], v[172:175], v[180:183], v[48:51]
	v_mfma_f32_16x16x32_bf16 v[36:39], v[164:167], v[188:191], v[36:39]
	v_mfma_f32_16x16x32_bf16 v[32:35], v[172:175], v[188:191], v[32:35]
	v_mfma_f32_16x16x32_bf16 v[20:23], v[164:167], v[196:199], v[20:23]
	v_mfma_f32_16x16x32_bf16 v[16:19], v[172:175], v[196:199], v[16:19]
	v_mfma_f32_16x16x32_bf16 v[4:7], v[164:167], v[204:207], v[4:7]
	v_mfma_f32_16x16x32_bf16 v[0:3], v[172:175], v[204:207], v[0:3]
	v_mfma_f32_16x16x32_bf16 v[52:55], v[168:171], v[184:187], v[52:55]
	v_mfma_f32_16x16x32_bf16 v[48:51], v[176:179], v[184:187], v[48:51]
	v_mfma_f32_16x16x32_bf16 v[36:39], v[168:171], v[192:195], v[36:39]
	v_mfma_f32_16x16x32_bf16 v[32:35], v[176:179], v[192:195], v[32:35]
	v_mfma_f32_16x16x32_bf16 v[20:23], v[168:171], v[200:203], v[20:23]
	v_mfma_f32_16x16x32_bf16 v[16:19], v[176:179], v[200:203], v[16:19]
	v_mfma_f32_16x16x32_bf16 v[4:7], v[168:171], v[214:217], v[4:7]
	v_mfma_f32_16x16x32_bf16 v[0:3], v[176:179], v[214:217], v[0:3]
	s_setprio 0
	s_barrier
	s_add_i32 s72, 0, 0x18000
	v_add_u32_e32 v147, s72, v144
	s_add_i32 s73, 0, 0x1c000
	ds_read_b128 v[136:139], v147
	ds_read_b128 v[152:155], v147 offset:1024
	ds_read_b128 v[156:159], v147 offset:2048
	ds_read_b128 v[160:163], v147 offset:3072
	v_add_u32_e32 v147, s73, v144
	ds_read_b128 v[164:167], v147
	ds_read_b128 v[168:171], v147 offset:1024
	ds_read_b128 v[172:175], v147 offset:2048
	ds_read_b128 v[176:179], v147 offset:3072
	s_add_u32 s22, s22, 0x20000
	s_addc_u32 s23, s23, 0
	s_mov_b32 m0, s54
	ds_read_b128 v[180:183], v146 offset:32768
	ds_read_b128 v[184:187], v146 offset:33792
	ds_read_b128 v[188:191], v146 offset:34816
	ds_read_b128 v[192:195], v146 offset:35840
	ds_read_b128 v[196:199], v146 offset:36864
	ds_read_b128 v[200:203], v146 offset:37888
	ds_read_b128 v[204:207], v146 offset:38912
	ds_read_b128 v[214:217], v146 offset:39936
	global_load_lds_dwordx4 v130, s[22:23]
	s_mov_b32 m0, s55
	s_nop 0
	global_load_lds_dwordx4 v128, s[22:23]
	s_waitcnt vmcnt(8)
	s_waitcnt lgkmcnt(0)
	s_barrier
	s_setprio 1
	s_waitcnt lgkmcnt(0)
	v_mfma_f32_16x16x32_bf16 v[124:127], v[136:139], v[180:183], v[124:127]
	v_mfma_f32_16x16x32_bf16 v[120:123], v[156:159], v[180:183], v[120:123]
	v_mfma_f32_16x16x32_bf16 v[108:111], v[136:139], v[188:191], v[108:111]
	v_mfma_f32_16x16x32_bf16 v[104:107], v[156:159], v[188:191], v[104:107]
	v_mfma_f32_16x16x32_bf16 v[92:95], v[136:139], v[196:199], v[92:95]
	v_mfma_f32_16x16x32_bf16 v[88:91], v[156:159], v[196:199], v[88:91]
	v_mfma_f32_16x16x32_bf16 v[76:79], v[136:139], v[204:207], v[76:79]
	v_mfma_f32_16x16x32_bf16 v[72:75], v[156:159], v[204:207], v[72:75]
	v_mfma_f32_16x16x32_bf16 v[124:127], v[152:155], v[184:187], v[124:127]
	v_mfma_f32_16x16x32_bf16 v[120:123], v[160:163], v[184:187], v[120:123]
	v_mfma_f32_16x16x32_bf16 v[108:111], v[152:155], v[192:195], v[108:111]
	v_mfma_f32_16x16x32_bf16 v[104:107], v[160:163], v[192:195], v[104:107]
	v_mfma_f32_16x16x32_bf16 v[92:95], v[152:155], v[200:203], v[92:95]
	v_mfma_f32_16x16x32_bf16 v[88:91], v[160:163], v[200:203], v[88:91]
	v_mfma_f32_16x16x32_bf16 v[76:79], v[152:155], v[214:217], v[76:79]
	v_mfma_f32_16x16x32_bf16 v[72:75], v[160:163], v[214:217], v[72:75]
	s_setprio 0
	s_setprio 1
	v_mfma_f32_16x16x32_bf16 v[116:119], v[164:167], v[180:183], v[116:119]
	v_mfma_f32_16x16x32_bf16 v[112:115], v[172:175], v[180:183], v[112:115]
	v_mfma_f32_16x16x32_bf16 v[100:103], v[164:167], v[188:191], v[100:103]
	v_mfma_f32_16x16x32_bf16 v[96:99], v[172:175], v[188:191], v[96:99]
	v_mfma_f32_16x16x32_bf16 v[84:87], v[164:167], v[196:199], v[84:87]
	v_mfma_f32_16x16x32_bf16 v[80:83], v[172:175], v[196:199], v[80:83]
	v_mfma_f32_16x16x32_bf16 v[68:71], v[164:167], v[204:207], v[68:71]
	v_mfma_f32_16x16x32_bf16 v[64:67], v[172:175], v[204:207], v[64:67]
	v_mfma_f32_16x16x32_bf16 v[116:119], v[168:171], v[184:187], v[116:119]
	v_mfma_f32_16x16x32_bf16 v[112:115], v[176:179], v[184:187], v[112:115]
	v_mfma_f32_16x16x32_bf16 v[100:103], v[168:171], v[192:195], v[100:103]
	v_mfma_f32_16x16x32_bf16 v[96:99], v[176:179], v[192:195], v[96:99]
	v_mfma_f32_16x16x32_bf16 v[84:87], v[168:171], v[200:203], v[84:87]
	v_mfma_f32_16x16x32_bf16 v[80:83], v[176:179], v[200:203], v[80:83]
	v_mfma_f32_16x16x32_bf16 v[68:71], v[168:171], v[214:217], v[68:71]
	v_mfma_f32_16x16x32_bf16 v[64:67], v[176:179], v[214:217], v[64:67]
	s_setprio 0
	s_barrier
	s_add_i32 s22, s72, s27
	v_lshl_add_u64 v[140:141], v[140:141], 0, s[92:93]
	s_mov_b32 m0, s22
	ds_read_b128 v[180:183], v146 offset:49152
	ds_read_b128 v[184:187], v146 offset:50176
	ds_read_b128 v[188:191], v146 offset:51200
	ds_read_b128 v[192:195], v146 offset:52224
	ds_read_b128 v[196:199], v146 offset:53248
	ds_read_b128 v[200:203], v146 offset:54272
	ds_read_b128 v[204:207], v146 offset:55296
	ds_read_b128 v[214:217], v146 offset:56320
	global_load_lds_dwordx4 v[140:141], off
	s_add_i32 m0, s22, 0x2000
	s_add_u32 s12, s12, 0x20080
	v_lshl_add_u64 v[140:141], v[148:149], 0, s[92:93]
	s_addc_u32 s13, s13, 0
	s_add_i32 s22, s73, s27
	global_load_lds_dwordx4 v[140:141], off
	s_mov_b32 m0, s22
	s_nop 0
	global_load_lds_dwordx4 v130, s[12:13]
	s_add_i32 m0, s22, 0x2000
	s_nop 0
	global_load_lds_dwordx4 v128, s[12:13]
	v_lshl_add_u64 v[140:141], v[224:225], 0, s[92:93]
	s_mov_b32 m0, s5
	s_nop 0
	global_load_lds_dwordx4 v[140:141], off
	v_lshl_add_u64 v[140:141], v[226:227], 0, s[92:93]
	s_mov_b32 m0, s60
	s_nop 0
	global_load_lds_dwordx4 v[140:141], off
	s_waitcnt vmcnt(8)
	s_waitcnt lgkmcnt(0)
	s_barrier
	s_setprio 1
	s_waitcnt lgkmcnt(0)
	v_mfma_f32_16x16x32_bf16 v[60:63], v[136:139], v[180:183], v[60:63]
	v_mfma_f32_16x16x32_bf16 v[56:59], v[156:159], v[180:183], v[56:59]
	v_mfma_f32_16x16x32_bf16 v[44:47], v[136:139], v[188:191], v[44:47]
	v_mfma_f32_16x16x32_bf16 v[40:43], v[156:159], v[188:191], v[40:43]
	v_mfma_f32_16x16x32_bf16 v[28:31], v[136:139], v[196:199], v[28:31]
	v_mfma_f32_16x16x32_bf16 v[24:27], v[156:159], v[196:199], v[24:27]
	v_mfma_f32_16x16x32_bf16 v[12:15], v[136:139], v[204:207], v[12:15]
	v_mfma_f32_16x16x32_bf16 v[8:11], v[156:159], v[204:207], v[8:11]
	v_mfma_f32_16x16x32_bf16 v[60:63], v[152:155], v[184:187], v[60:63]
	v_mfma_f32_16x16x32_bf16 v[56:59], v[160:163], v[184:187], v[56:59]
	v_mfma_f32_16x16x32_bf16 v[44:47], v[152:155], v[192:195], v[44:47]
	v_mfma_f32_16x16x32_bf16 v[40:43], v[160:163], v[192:195], v[40:43]
	v_mfma_f32_16x16x32_bf16 v[28:31], v[152:155], v[200:203], v[28:31]
	v_mfma_f32_16x16x32_bf16 v[24:27], v[160:163], v[200:203], v[24:27]
	v_mfma_f32_16x16x32_bf16 v[12:15], v[152:155], v[214:217], v[12:15]
	v_mfma_f32_16x16x32_bf16 v[8:11], v[160:163], v[214:217], v[8:11]
	s_setprio 0
	s_setprio 1
	v_mfma_f32_16x16x32_bf16 v[52:55], v[164:167], v[180:183], v[52:55]
	v_mfma_f32_16x16x32_bf16 v[48:51], v[172:175], v[180:183], v[48:51]
	v_mfma_f32_16x16x32_bf16 v[36:39], v[164:167], v[188:191], v[36:39]
	v_mfma_f32_16x16x32_bf16 v[32:35], v[172:175], v[188:191], v[32:35]
	v_mfma_f32_16x16x32_bf16 v[20:23], v[164:167], v[196:199], v[20:23]
	v_mfma_f32_16x16x32_bf16 v[16:19], v[172:175], v[196:199], v[16:19]
	v_mfma_f32_16x16x32_bf16 v[4:7], v[164:167], v[204:207], v[4:7]
	v_mfma_f32_16x16x32_bf16 v[0:3], v[172:175], v[204:207], v[0:3]
	v_mfma_f32_16x16x32_bf16 v[52:55], v[168:171], v[184:187], v[52:55]
	v_mfma_f32_16x16x32_bf16 v[48:51], v[176:179], v[184:187], v[48:51]
	v_mfma_f32_16x16x32_bf16 v[36:39], v[168:171], v[192:195], v[36:39]
	v_mfma_f32_16x16x32_bf16 v[32:35], v[176:179], v[192:195], v[32:35]
	v_mfma_f32_16x16x32_bf16 v[20:23], v[168:171], v[200:203], v[20:23]
	v_mfma_f32_16x16x32_bf16 v[16:19], v[176:179], v[200:203], v[16:19]
	v_mfma_f32_16x16x32_bf16 v[4:7], v[168:171], v[214:217], v[4:7]
	v_mfma_f32_16x16x32_bf16 v[0:3], v[176:179], v[214:217], v[0:3]
	s_setprio 0
	s_barrier
	s_add_i32 s71, s71, 2
	s_add_u32 s0, s0, 0x100
	s_addc_u32 s1, s1, 0
	s_add_u32 s69, s69, 0x100
	s_addc_u32 s70, s70, 0
	s_cmp_gt_u32 s71, 5
	s_cbranch_scc0 .LBB0_1026
	s_and_b64 vcc, exec, s[40:41]
	s_cbranch_vccz .LBB0_1029
	s_barrier

.LBB0_1299:
	v_lshrrev_b32_e32 v16, 1, v6
	v_and_b32_e32 v16, 24, v16
	v_and_b32_e32 v7, 15, v6
	v_lshlrev_b32_e32 v17, 1, v16
	v_lshlrev_b32_e32 v6, 2, v6
	s_lshl_b32 s5, s5, 5
	v_lshl_or_b32 v143, s6, 6, v7
	v_lshl_or_b32 v7, v7, 6, v17
	s_lshl_b32 s6, s6, 13
	v_and_b32_e32 v6, 32, v6
	s_and_b32 s5, s5, 0x60
	v_lshl_add_u64 v[8:9], s[22:23], 0, v[208:209]
	v_mov_b32_e32 v129, v209
	v_bitop3_b32 v17, v7, s6, v6 bitop3:0xde
	s_lshl_b32 s6, s5, 7
	v_lshl_add_u64 v[10:11], s[22:23], 0, v[128:129]
	v_mov_b32_e32 v133, v209
	v_bitop3_b32 v144, v7, s6, v6 bitop3:0xde
	s_add_i32 m0, s49, 0x18000
	v_lshl_add_u64 v[6:7], v[8:9], 0, s[92:93]
	v_lshl_add_u64 v[12:13], s[0:1], 0, v[132:133]
	v_mov_b32_e32 v131, v209
	s_waitcnt vmcnt(2)
	s_barrier
	global_load_lds_dwordx4 v[6:7], off
	v_lshl_add_u64 v[6:7], v[10:11], 0, s[92:93]
	s_add_i32 m0, s49, 0x1a000
	s_add_i32 s55, s49, 0x8000
	s_add_i32 s60, s49, 0xa000
	v_lshl_add_u64 v[14:15], s[0:1], 0, v[130:131]
	global_load_lds_dwordx4 v[6:7], off
	v_lshl_add_u64 v[6:7], v[12:13], 0, s[92:93]
	s_mov_b32 m0, s55
	s_add_u32 s6, s22, 0x40080
	global_load_lds_dwordx4 v[6:7], off
	v_lshl_add_u64 v[6:7], v[14:15], 0, s[92:93]
	s_mov_b32 m0, s60
	s_addc_u32 s7, s23, 0
	global_load_lds_dwordx4 v[6:7], off
	s_add_i32 m0, s49, 0x1c000
	s_nop 0
	global_load_lds_dwordx4 v208, s[6:7]
	s_add_i32 m0, s49, 0x1e000
	s_cmpk_lt_u32 s4, 0x100
	global_load_lds_dwordx4 v128, s[6:7]
	v_lshlrev_b32_e32 v6, 14, v4
	v_and_b32_e32 v6, 0xffff8000, v6
	v_lshl_add_u32 v3, v3, 11, v6
	v_and_b32_e32 v4, 1, v4
	v_lshl_or_b32 v3, v4, 6, v3
	v_lshl_add_u32 v134, v5, 1, v3
	v_lshlrev_b32_e32 v3, 14, v0
	v_and_b32_e32 v3, 0xffff8000, v3
	s_waitcnt vmcnt(6)
	v_lshl_add_u32 v1, v1, 11, v3
	v_and_b32_e32 v0, 1, v0
	v_lshl_or_b32 v0, v0, 6, v1
	v_readlane_b32 s6, v252, 53
	s_cselect_b64 s[36:37], -1, 0
	v_or_b32_e32 v145, s5, v16
	v_mov_b32_e32 v135, v209
	v_lshl_add_u32 v136, v2, 1, v0
	v_mov_b32_e32 v137, v209
	s_mov_b32 s61, 0
	v_add_u32_e32 v146, 0, v17
	v_readlane_b32 s4, v252, 55
	s_mov_b32 s5, s6
	s_barrier
	v_readlane_b32 s7, v252, 54
	s_branch .LBB0_1302

.LBB0_1309:
	s_add_u32 s22, s0, 0xfffc0080
	s_addc_u32 s23, s1, -1
	s_add_i32 s68, 0, 0x10000
	s_cmp_eq_u32 s67, 12
	s_cselect_b32 s47, s24, s23
	s_cselect_b32 s46, s25, s22
	v_add_u32_e32 v147, s68, v144
	s_cselect_b32 s23, s34, s66
	s_cselect_b32 s22, s39, s41
	s_add_i32 s70, 0, 0x14000
	ds_read_b128 v[138:141], v147
	ds_read_b128 v[148:151], v147 offset:1024
	ds_read_b128 v[152:155], v147 offset:2048
	ds_read_b128 v[156:159], v147 offset:3072
	v_add_u32_e32 v147, s70, v144
	ds_read_b128 v[160:163], v147
	ds_read_b128 v[164:167], v147 offset:1024
	ds_read_b128 v[168:171], v147 offset:2048
	ds_read_b128 v[172:175], v147 offset:3072
	s_add_i32 m0, s49, 0xc000
	ds_read_b128 v[176:179], v146
	ds_read_b128 v[180:183], v146 offset:1024
	ds_read_b128 v[184:187], v146 offset:2048
	ds_read_b128 v[188:191], v146 offset:3072
	ds_read_b128 v[192:195], v146 offset:4096
	ds_read_b128 v[196:199], v146 offset:5120
	ds_read_b128 v[200:203], v146 offset:6144
	ds_read_b128 v[204:207], v146 offset:7168
	global_load_lds_dwordx4 v134, s[0:1]
	s_add_i32 m0, s49, 0xe000
	s_nop 0
	global_load_lds_dwordx4 v136, s[0:1]
	s_waitcnt vmcnt(8)
	s_waitcnt lgkmcnt(0)
	s_barrier
	s_setprio 1
	s_waitcnt lgkmcnt(0)
	v_mfma_f32_16x16x32_bf16 v[124:127], v[138:141], v[176:179], v[124:127]
	v_mfma_f32_16x16x32_bf16 v[120:123], v[152:155], v[176:179], v[120:123]
	v_mfma_f32_16x16x32_bf16 v[108:111], v[138:141], v[184:187], v[108:111]
	v_mfma_f32_16x16x32_bf16 v[104:107], v[152:155], v[184:187], v[104:107]
	v_mfma_f32_16x16x32_bf16 v[92:95], v[138:141], v[192:195], v[92:95]
	v_mfma_f32_16x16x32_bf16 v[88:91], v[152:155], v[192:195], v[88:91]
	v_mfma_f32_16x16x32_bf16 v[76:79], v[138:141], v[200:203], v[76:79]
	v_mfma_f32_16x16x32_bf16 v[72:75], v[152:155], v[200:203], v[72:75]
	v_mfma_f32_16x16x32_bf16 v[124:127], v[148:151], v[180:183], v[124:127]
	v_mfma_f32_16x16x32_bf16 v[120:123], v[156:159], v[180:183], v[120:123]
	v_mfma_f32_16x16x32_bf16 v[108:111], v[148:151], v[188:191], v[108:111]
	v_mfma_f32_16x16x32_bf16 v[104:107], v[156:159], v[188:191], v[104:107]
	v_mfma_f32_16x16x32_bf16 v[92:95], v[148:151], v[196:199], v[92:95]
	v_mfma_f32_16x16x32_bf16 v[88:91], v[156:159], v[196:199], v[88:91]
	v_mfma_f32_16x16x32_bf16 v[76:79], v[148:151], v[204:207], v[76:79]
	v_mfma_f32_16x16x32_bf16 v[72:75], v[156:159], v[204:207], v[72:75]
	s_setprio 0
	s_setprio 1
	v_mfma_f32_16x16x32_bf16 v[116:119], v[160:163], v[176:179], v[116:119]
	v_mfma_f32_16x16x32_bf16 v[112:115], v[168:171], v[176:179], v[112:115]
	v_mfma_f32_16x16x32_bf16 v[100:103], v[160:163], v[184:187], v[100:103]
	v_mfma_f32_16x16x32_bf16 v[96:99], v[168:171], v[184:187], v[96:99]
	v_mfma_f32_16x16x32_bf16 v[84:87], v[160:163], v[192:195], v[84:87]
	v_mfma_f32_16x16x32_bf16 v[80:83], v[168:171], v[192:195], v[80:83]
	v_mfma_f32_16x16x32_bf16 v[68:71], v[160:163], v[200:203], v[68:71]
	v_mfma_f32_16x16x32_bf16 v[64:67], v[168:171], v[200:203], v[64:67]
	v_mfma_f32_16x16x32_bf16 v[116:119], v[164:167], v[180:183], v[116:119]
	v_mfma_f32_16x16x32_bf16 v[112:115], v[172:175], v[180:183], v[112:115]
	v_mfma_f32_16x16x32_bf16 v[100:103], v[164:167], v[188:191], v[100:103]
	v_mfma_f32_16x16x32_bf16 v[96:99], v[172:175], v[188:191], v[96:99]
	v_mfma_f32_16x16x32_bf16 v[84:87], v[164:167], v[196:199], v[84:87]
	v_mfma_f32_16x16x32_bf16 v[80:83], v[172:175], v[196:199], v[80:83]
	v_mfma_f32_16x16x32_bf16 v[68:71], v[164:167], v[204:207], v[68:71]
	v_mfma_f32_16x16x32_bf16 v[64:67], v[172:175], v[204:207], v[64:67]
	s_setprio 0
	s_barrier
	s_add_i32 s68, s68, s48
	v_lshl_add_u64 v[214:215], s[22:23], 0, v[208:209]
	s_mov_b32 m0, s68
	ds_read_b128 v[176:179], v146 offset:16384
	ds_read_b128 v[180:183], v146 offset:17408
	ds_read_b128 v[184:187], v146 offset:18432
	ds_read_b128 v[188:191], v146 offset:19456
	ds_read_b128 v[192:195], v146 offset:20480
	ds_read_b128 v[196:199], v146 offset:21504
	ds_read_b128 v[200:203], v146 offset:22528
	ds_read_b128 v[204:207], v146 offset:23552
	global_load_lds_dwordx4 v[214:215], off
	s_add_i32 m0, s68, 0x2000
	s_add_u32 s68, s22, 0x40000
	v_lshl_add_u64 v[216:217], s[22:23], 0, v[128:129]
	s_addc_u32 s69, s23, 0
	s_add_i32 s70, s70, s48
	global_load_lds_dwordx4 v[216:217], off
	s_mov_b32 m0, s70
	v_lshl_add_u64 v[226:227], s[46:47], 0, v[130:131]
	global_load_lds_dwordx4 v208, s[68:69]
	s_add_i32 m0, s70, 0x2000
	s_nop 0
	global_load_lds_dwordx4 v128, s[68:69]
	v_lshl_add_u64 v[224:225], s[46:47], 0, v[132:133]
	s_mov_b32 m0, s49
	s_nop 0
	global_load_lds_dwordx4 v[224:225], off
	s_mov_b32 m0, s50
	s_nop 0
	global_load_lds_dwordx4 v[226:227], off
	s_waitcnt vmcnt(8)
	s_waitcnt lgkmcnt(0)
	s_barrier
	s_setprio 1
	s_waitcnt lgkmcnt(0)
	v_mfma_f32_16x16x32_bf16 v[60:63], v[138:141], v[176:179], v[60:63]
	v_mfma_f32_16x16x32_bf16 v[56:59], v[152:155], v[176:179], v[56:59]
	v_mfma_f32_16x16x32_bf16 v[44:47], v[138:141], v[184:187], v[44:47]
	v_mfma_f32_16x16x32_bf16 v[40:43], v[152:155], v[184:187], v[40:43]
	v_mfma_f32_16x16x32_bf16 v[28:31], v[138:141], v[192:195], v[28:31]
	v_mfma_f32_16x16x32_bf16 v[24:27], v[152:155], v[192:195], v[24:27]
	v_mfma_f32_16x16x32_bf16 v[12:15], v[138:141], v[200:203], v[12:15]
	v_mfma_f32_16x16x32_bf16 v[8:11], v[152:155], v[200:203], v[8:11]
	v_mfma_f32_16x16x32_bf16 v[60:63], v[148:151], v[180:183], v[60:63]
	v_mfma_f32_16x16x32_bf16 v[56:59], v[156:159], v[180:183], v[56:59]
	v_mfma_f32_16x16x32_bf16 v[44:47], v[148:151], v[188:191], v[44:47]
	v_mfma_f32_16x16x32_bf16 v[40:43], v[156:159], v[188:191], v[40:43]
	v_mfma_f32_16x16x32_bf16 v[28:31], v[148:151], v[196:199], v[28:31]
	v_mfma_f32_16x16x32_bf16 v[24:27], v[156:159], v[196:199], v[24:27]
	v_mfma_f32_16x16x32_bf16 v[12:15], v[148:151], v[204:207], v[12:15]
	v_mfma_f32_16x16x32_bf16 v[8:11], v[156:159], v[204:207], v[8:11]
	s_setprio 0
	s_setprio 1
	v_mfma_f32_16x16x32_bf16 v[52:55], v[160:163], v[176:179], v[52:55]
	v_mfma_f32_16x16x32_bf16 v[48:51], v[168:171], v[176:179], v[48:51]
	v_mfma_f32_16x16x32_bf16 v[36:39], v[160:163], v[184:187], v[36:39]
	v_mfma_f32_16x16x32_bf16 v[32:35], v[168:171], v[184:187], v[32:35]
	v_mfma_f32_16x16x32_bf16 v[20:23], v[160:163], v[192:195], v[20:23]
	v_mfma_f32_16x16x32_bf16 v[16:19], v[168:171], v[192:195], v[16:19]
	v_mfma_f32_16x16x32_bf16 v[4:7], v[160:163], v[200:203], v[4:7]
	v_mfma_f32_16x16x32_bf16 v[0:3], v[168:171], v[200:203], v[0:3]
	v_mfma_f32_16x16x32_bf16 v[52:55], v[164:167], v[180:183], v[52:55]
	v_mfma_f32_16x16x32_bf16 v[48:51], v[172:175], v[180:183], v[48:51]
	v_mfma_f32_16x16x32_bf16 v[36:39], v[164:167], v[188:191], v[36:39]
	v_mfma_f32_16x16x32_bf16 v[32:35], v[172:175], v[188:191], v[32:35]
	v_mfma_f32_16x16x32_bf16 v[20:23], v[164:167], v[196:199], v[20:23]
	v_mfma_f32_16x16x32_bf16 v[16:19], v[172:175], v[196:199], v[16:19]
	v_mfma_f32_16x16x32_bf16 v[4:7], v[164:167], v[204:207], v[4:7]
	v_mfma_f32_16x16x32_bf16 v[0:3], v[172:175], v[204:207], v[0:3]
	s_setprio 0
	s_barrier
	s_add_i32 s68, 0, 0x18000
	v_add_u32_e32 v147, s68, v144
	s_add_i32 s69, 0, 0x1c000
	ds_read_b128 v[138:141], v147
	ds_read_b128 v[148:151], v147 offset:1024
	ds_read_b128 v[152:155], v147 offset:2048
	ds_read_b128 v[156:159], v147 offset:3072
	v_add_u32_e32 v147, s69, v144
	ds_read_b128 v[160:163], v147
	ds_read_b128 v[164:167], v147 offset:1024
	ds_read_b128 v[168:171], v147 offset:2048
	ds_read_b128 v[172:175], v147 offset:3072
	s_add_u32 s46, s46, 0x40000
	s_addc_u32 s47, s47, 0
	s_mov_b32 m0, s51
	ds_read_b128 v[176:179], v146 offset:32768
	ds_read_b128 v[180:183], v146 offset:33792
	ds_read_b128 v[184:187], v146 offset:34816
	ds_read_b128 v[188:191], v146 offset:35840
	ds_read_b128 v[192:195], v146 offset:36864
	ds_read_b128 v[196:199], v146 offset:37888
	ds_read_b128 v[200:203], v146 offset:38912
	ds_read_b128 v[204:207], v146 offset:39936
	global_load_lds_dwordx4 v132, s[46:47]
	s_mov_b32 m0, s54
	s_nop 0
	global_load_lds_dwordx4 v130, s[46:47]
	s_waitcnt vmcnt(8)
	s_waitcnt lgkmcnt(0)
	s_barrier
	s_setprio 1
	s_waitcnt lgkmcnt(0)
	v_mfma_f32_16x16x32_bf16 v[124:127], v[138:141], v[176:179], v[124:127]
	v_mfma_f32_16x16x32_bf16 v[120:123], v[152:155], v[176:179], v[120:123]
	v_mfma_f32_16x16x32_bf16 v[108:111], v[138:141], v[184:187], v[108:111]
	v_mfma_f32_16x16x32_bf16 v[104:107], v[152:155], v[184:187], v[104:107]
	v_mfma_f32_16x16x32_bf16 v[92:95], v[138:141], v[192:195], v[92:95]
	v_mfma_f32_16x16x32_bf16 v[88:91], v[152:155], v[192:195], v[88:91]
	v_mfma_f32_16x16x32_bf16 v[76:79], v[138:141], v[200:203], v[76:79]
	v_mfma_f32_16x16x32_bf16 v[72:75], v[152:155], v[200:203], v[72:75]
	v_mfma_f32_16x16x32_bf16 v[124:127], v[148:151], v[180:183], v[124:127]
	v_mfma_f32_16x16x32_bf16 v[120:123], v[156:159], v[180:183], v[120:123]
	v_mfma_f32_16x16x32_bf16 v[108:111], v[148:151], v[188:191], v[108:111]
	v_mfma_f32_16x16x32_bf16 v[104:107], v[156:159], v[188:191], v[104:107]
	v_mfma_f32_16x16x32_bf16 v[92:95], v[148:151], v[196:199], v[92:95]
	v_mfma_f32_16x16x32_bf16 v[88:91], v[156:159], v[196:199], v[88:91]
	v_mfma_f32_16x16x32_bf16 v[76:79], v[148:151], v[204:207], v[76:79]
	v_mfma_f32_16x16x32_bf16 v[72:75], v[156:159], v[204:207], v[72:75]
	s_setprio 0
	s_setprio 1
	v_mfma_f32_16x16x32_bf16 v[116:119], v[160:163], v[176:179], v[116:119]
	v_mfma_f32_16x16x32_bf16 v[112:115], v[168:171], v[176:179], v[112:115]
	v_mfma_f32_16x16x32_bf16 v[100:103], v[160:163], v[184:187], v[100:103]
	v_mfma_f32_16x16x32_bf16 v[96:99], v[168:171], v[184:187], v[96:99]
	v_mfma_f32_16x16x32_bf16 v[84:87], v[160:163], v[192:195], v[84:87]
	v_mfma_f32_16x16x32_bf16 v[80:83], v[168:171], v[192:195], v[80:83]
	v_mfma_f32_16x16x32_bf16 v[68:71], v[160:163], v[200:203], v[68:71]
	v_mfma_f32_16x16x32_bf16 v[64:67], v[168:171], v[200:203], v[64:67]
	v_mfma_f32_16x16x32_bf16 v[116:119], v[164:167], v[180:183], v[116:119]
	v_mfma_f32_16x16x32_bf16 v[112:115], v[172:175], v[180:183], v[112:115]
	v_mfma_f32_16x16x32_bf16 v[100:103], v[164:167], v[188:191], v[100:103]
	v_mfma_f32_16x16x32_bf16 v[96:99], v[172:175], v[188:191], v[96:99]
	v_mfma_f32_16x16x32_bf16 v[84:87], v[164:167], v[196:199], v[84:87]
	v_mfma_f32_16x16x32_bf16 v[80:83], v[172:175], v[196:199], v[80:83]
	v_mfma_f32_16x16x32_bf16 v[68:71], v[164:167], v[204:207], v[68:71]
	v_mfma_f32_16x16x32_bf16 v[64:67], v[172:175], v[204:207], v[64:67]
	s_setprio 0
	s_barrier
	s_add_i32 s46, s68, s48
	v_lshl_add_u64 v[214:215], v[214:215], 0, s[92:93]
	s_mov_b32 m0, s46
	ds_read_b128 v[176:179], v146 offset:49152
	ds_read_b128 v[180:183], v146 offset:50176
	ds_read_b128 v[184:187], v146 offset:51200
	ds_read_b128 v[188:191], v146 offset:52224
	ds_read_b128 v[192:195], v146 offset:53248
	ds_read_b128 v[196:199], v146 offset:54272
	ds_read_b128 v[200:203], v146 offset:55296
	ds_read_b128 v[204:207], v146 offset:56320
	global_load_lds_dwordx4 v[214:215], off
	s_add_i32 m0, s46, 0x2000
	s_add_u32 s22, s22, 0x40080
	v_lshl_add_u64 v[214:215], v[216:217], 0, s[92:93]
	s_addc_u32 s23, s23, 0
	s_add_i32 s46, s69, s48
	global_load_lds_dwordx4 v[214:215], off
	s_mov_b32 m0, s46
	s_nop 0
	global_load_lds_dwordx4 v208, s[22:23]
	s_add_i32 m0, s46, 0x2000
	s_nop 0
	global_load_lds_dwordx4 v128, s[22:23]
	v_lshl_add_u64 v[214:215], v[224:225], 0, s[92:93]
	s_mov_b32 m0, s55
	s_nop 0
	global_load_lds_dwordx4 v[214:215], off
	v_lshl_add_u64 v[214:215], v[226:227], 0, s[92:93]
	s_mov_b32 m0, s60
	s_nop 0
	global_load_lds_dwordx4 v[214:215], off
	s_waitcnt vmcnt(8)
	s_waitcnt lgkmcnt(0)
	s_barrier
	s_setprio 1
	s_waitcnt lgkmcnt(0)
	v_mfma_f32_16x16x32_bf16 v[60:63], v[138:141], v[176:179], v[60:63]
	v_mfma_f32_16x16x32_bf16 v[56:59], v[152:155], v[176:179], v[56:59]
	v_mfma_f32_16x16x32_bf16 v[44:47], v[138:141], v[184:187], v[44:47]
	v_mfma_f32_16x16x32_bf16 v[40:43], v[152:155], v[184:187], v[40:43]
	v_mfma_f32_16x16x32_bf16 v[28:31], v[138:141], v[192:195], v[28:31]
	v_mfma_f32_16x16x32_bf16 v[24:27], v[152:155], v[192:195], v[24:27]
	v_mfma_f32_16x16x32_bf16 v[12:15], v[138:141], v[200:203], v[12:15]
	v_mfma_f32_16x16x32_bf16 v[8:11], v[152:155], v[200:203], v[8:11]
	v_mfma_f32_16x16x32_bf16 v[60:63], v[148:151], v[180:183], v[60:63]
	v_mfma_f32_16x16x32_bf16 v[56:59], v[156:159], v[180:183], v[56:59]
	v_mfma_f32_16x16x32_bf16 v[44:47], v[148:151], v[188:191], v[44:47]
	v_mfma_f32_16x16x32_bf16 v[40:43], v[156:159], v[188:191], v[40:43]
	v_mfma_f32_16x16x32_bf16 v[28:31], v[148:151], v[196:199], v[28:31]
	v_mfma_f32_16x16x32_bf16 v[24:27], v[156:159], v[196:199], v[24:27]
	v_mfma_f32_16x16x32_bf16 v[12:15], v[148:151], v[204:207], v[12:15]
	v_mfma_f32_16x16x32_bf16 v[8:11], v[156:159], v[204:207], v[8:11]
	s_setprio 0
	s_setprio 1
	v_mfma_f32_16x16x32_bf16 v[52:55], v[160:163], v[176:179], v[52:55]
	v_mfma_f32_16x16x32_bf16 v[48:51], v[168:171], v[176:179], v[48:51]
	v_mfma_f32_16x16x32_bf16 v[36:39], v[160:163], v[184:187], v[36:39]
	v_mfma_f32_16x16x32_bf16 v[32:35], v[168:171], v[184:187], v[32:35]
	v_mfma_f32_16x16x32_bf16 v[20:23], v[160:163], v[192:195], v[20:23]
	v_mfma_f32_16x16x32_bf16 v[16:19], v[168:171], v[192:195], v[16:19]
	v_mfma_f32_16x16x32_bf16 v[4:7], v[160:163], v[200:203], v[4:7]
	v_mfma_f32_16x16x32_bf16 v[0:3], v[168:171], v[200:203], v[0:3]
	v_mfma_f32_16x16x32_bf16 v[52:55], v[164:167], v[180:183], v[52:55]
	v_mfma_f32_16x16x32_bf16 v[48:51], v[172:175], v[180:183], v[48:51]
	v_mfma_f32_16x16x32_bf16 v[36:39], v[164:167], v[188:191], v[36:39]
	v_mfma_f32_16x16x32_bf16 v[32:35], v[172:175], v[188:191], v[32:35]
	v_mfma_f32_16x16x32_bf16 v[20:23], v[164:167], v[196:199], v[20:23]
	v_mfma_f32_16x16x32_bf16 v[16:19], v[172:175], v[196:199], v[16:19]
	v_mfma_f32_16x16x32_bf16 v[4:7], v[164:167], v[204:207], v[4:7]
	v_mfma_f32_16x16x32_bf16 v[0:3], v[172:175], v[204:207], v[0:3]
	s_setprio 0
	s_barrier
	s_add_i32 s67, s67, 2
	s_add_u32 s0, s0, 0x100
	s_addc_u32 s1, s1, 0
	s_add_u32 s41, s41, 0x100
	s_addc_u32 s66, s66, 0
	s_cmp_gt_u32 s67, 13
	s_cbranch_scc0 .LBB0_1309
	s_and_b64 vcc, exec, s[36:37]
	s_cbranch_vccz .LBB0_1312
	s_barrier

.LBB0_1319:
	v_lshrrev_b32_e32 v16, 1, v6
	v_and_b32_e32 v16, 24, v16
	v_and_b32_e32 v7, 15, v6
	v_lshlrev_b32_e32 v17, 1, v16
	v_lshlrev_b32_e32 v6, 2, v6
	s_lshl_b32 s5, s5, 5
	v_lshl_or_b32 v143, s6, 6, v7
	v_lshl_or_b32 v7, v7, 6, v17
	s_lshl_b32 s6, s6, 13
	v_and_b32_e32 v6, 32, v6
	s_and_b32 s5, s5, 0x60
	v_lshl_add_u64 v[8:9], s[22:23], 0, v[208:209]
	v_mov_b32_e32 v129, v209
	v_bitop3_b32 v17, v7, s6, v6 bitop3:0xde
	s_lshl_b32 s6, s5, 7
	v_lshl_add_u64 v[10:11], s[22:23], 0, v[128:129]
	v_mov_b32_e32 v133, v209
	v_bitop3_b32 v144, v7, s6, v6 bitop3:0xde
	s_add_i32 m0, s51, 0x18000
	v_lshl_add_u64 v[6:7], v[8:9], 0, s[92:93]
	v_lshl_add_u64 v[12:13], s[0:1], 0, v[132:133]
	v_mov_b32_e32 v131, v209
	s_waitcnt vmcnt(2)
	s_barrier
	global_load_lds_dwordx4 v[6:7], off
	v_lshl_add_u64 v[6:7], v[10:11], 0, s[92:93]
	s_add_i32 m0, s51, 0x1a000
	s_add_i32 s61, s51, 0x8000
	s_add_i32 s67, s51, 0xa000
	v_lshl_add_u64 v[14:15], s[0:1], 0, v[130:131]
	global_load_lds_dwordx4 v[6:7], off
	v_lshl_add_u64 v[6:7], v[12:13], 0, s[92:93]
	s_mov_b32 m0, s61
	s_add_u32 s6, s22, 0x20080
	global_load_lds_dwordx4 v[6:7], off
	v_lshl_add_u64 v[6:7], v[14:15], 0, s[92:93]
	s_mov_b32 m0, s67
	s_addc_u32 s7, s23, 0
	global_load_lds_dwordx4 v[6:7], off
	s_add_i32 m0, s51, 0x1c000
	s_nop 0
	global_load_lds_dwordx4 v208, s[6:7]
	s_add_i32 m0, s51, 0x1e000
	s_cmpk_lt_u32 s4, 0x100
	global_load_lds_dwordx4 v128, s[6:7]
	v_lshlrev_b32_e32 v6, 13, v4
	v_and_b32_e32 v6, 0xffffc000, v6
	v_lshl_add_u32 v3, v3, 10, v6
	v_and_b32_e32 v4, 1, v4
	v_lshl_or_b32 v3, v4, 6, v3
	v_lshl_add_u32 v134, v5, 1, v3
	v_lshlrev_b32_e32 v3, 13, v0
	v_and_b32_e32 v3, 0xffffc000, v3
	s_waitcnt vmcnt(6)
	v_lshl_add_u32 v1, v1, 10, v3
	v_and_b32_e32 v0, 1, v0
	v_lshl_or_b32 v0, v0, 6, v1
	v_readlane_b32 s6, v252, 53
	s_cselect_b64 s[36:37], -1, 0
	v_or_b32_e32 v145, s5, v16
	v_mov_b32_e32 v135, v209
	v_lshl_add_u32 v136, v2, 1, v0
	v_mov_b32_e32 v137, v209
	s_mov_b32 s70, 0
	v_add_u32_e32 v146, 0, v17
	v_readlane_b32 s4, v252, 55
	s_mov_b32 s5, s6
	s_barrier
	v_readlane_b32 s7, v252, 54
	s_branch .LBB0_1322

.LBB0_1329:
	s_add_u32 s22, s0, 0xfffe0080
	s_addc_u32 s23, s1, -1
	s_add_i32 s66, 0, 0x10000
	s_cmp_eq_u32 s41, 4
	s_cselect_b32 s47, s24, s23
	s_cselect_b32 s46, s25, s22
	v_add_u32_e32 v147, s66, v144
	s_cselect_b32 s23, s26, s39
	s_cselect_b32 s22, s27, s34
	s_add_i32 s71, 0, 0x14000
	ds_read_b128 v[138:141], v147
	ds_read_b128 v[148:151], v147 offset:1024
	ds_read_b128 v[152:155], v147 offset:2048
	ds_read_b128 v[156:159], v147 offset:3072
	v_add_u32_e32 v147, s71, v144
	ds_read_b128 v[160:163], v147
	ds_read_b128 v[164:167], v147 offset:1024
	ds_read_b128 v[168:171], v147 offset:2048
	ds_read_b128 v[172:175], v147 offset:3072
	s_add_i32 m0, s51, 0xc000
	ds_read_b128 v[176:179], v146
	ds_read_b128 v[180:183], v146 offset:1024
	ds_read_b128 v[184:187], v146 offset:2048
	ds_read_b128 v[188:191], v146 offset:3072
	ds_read_b128 v[192:195], v146 offset:4096
	ds_read_b128 v[196:199], v146 offset:5120
	ds_read_b128 v[200:203], v146 offset:6144
	ds_read_b128 v[204:207], v146 offset:7168
	global_load_lds_dwordx4 v134, s[0:1]
	s_add_i32 m0, s51, 0xe000
	s_nop 0
	global_load_lds_dwordx4 v136, s[0:1]
	s_waitcnt vmcnt(8)
	s_waitcnt lgkmcnt(0)
	s_barrier
	s_setprio 1
	s_waitcnt lgkmcnt(0)
	v_mfma_f32_16x16x32_bf16 v[124:127], v[138:141], v[176:179], v[124:127]
	v_mfma_f32_16x16x32_bf16 v[120:123], v[152:155], v[176:179], v[120:123]
	v_mfma_f32_16x16x32_bf16 v[108:111], v[138:141], v[184:187], v[108:111]
	v_mfma_f32_16x16x32_bf16 v[104:107], v[152:155], v[184:187], v[104:107]
	v_mfma_f32_16x16x32_bf16 v[92:95], v[138:141], v[192:195], v[92:95]
	v_mfma_f32_16x16x32_bf16 v[88:91], v[152:155], v[192:195], v[88:91]
	v_mfma_f32_16x16x32_bf16 v[76:79], v[138:141], v[200:203], v[76:79]
	v_mfma_f32_16x16x32_bf16 v[72:75], v[152:155], v[200:203], v[72:75]
	v_mfma_f32_16x16x32_bf16 v[124:127], v[148:151], v[180:183], v[124:127]
	v_mfma_f32_16x16x32_bf16 v[120:123], v[156:159], v[180:183], v[120:123]
	v_mfma_f32_16x16x32_bf16 v[108:111], v[148:151], v[188:191], v[108:111]
	v_mfma_f32_16x16x32_bf16 v[104:107], v[156:159], v[188:191], v[104:107]
	v_mfma_f32_16x16x32_bf16 v[92:95], v[148:151], v[196:199], v[92:95]
	v_mfma_f32_16x16x32_bf16 v[88:91], v[156:159], v[196:199], v[88:91]
	v_mfma_f32_16x16x32_bf16 v[76:79], v[148:151], v[204:207], v[76:79]
	v_mfma_f32_16x16x32_bf16 v[72:75], v[156:159], v[204:207], v[72:75]
	s_setprio 0
	s_setprio 1
	v_mfma_f32_16x16x32_bf16 v[116:119], v[160:163], v[176:179], v[116:119]
	v_mfma_f32_16x16x32_bf16 v[112:115], v[168:171], v[176:179], v[112:115]
	v_mfma_f32_16x16x32_bf16 v[100:103], v[160:163], v[184:187], v[100:103]
	v_mfma_f32_16x16x32_bf16 v[96:99], v[168:171], v[184:187], v[96:99]
	v_mfma_f32_16x16x32_bf16 v[84:87], v[160:163], v[192:195], v[84:87]
	v_mfma_f32_16x16x32_bf16 v[80:83], v[168:171], v[192:195], v[80:83]
	v_mfma_f32_16x16x32_bf16 v[68:71], v[160:163], v[200:203], v[68:71]
	v_mfma_f32_16x16x32_bf16 v[64:67], v[168:171], v[200:203], v[64:67]
	v_mfma_f32_16x16x32_bf16 v[116:119], v[164:167], v[180:183], v[116:119]
	v_mfma_f32_16x16x32_bf16 v[112:115], v[172:175], v[180:183], v[112:115]
	v_mfma_f32_16x16x32_bf16 v[100:103], v[164:167], v[188:191], v[100:103]
	v_mfma_f32_16x16x32_bf16 v[96:99], v[172:175], v[188:191], v[96:99]
	v_mfma_f32_16x16x32_bf16 v[84:87], v[164:167], v[196:199], v[84:87]
	v_mfma_f32_16x16x32_bf16 v[80:83], v[172:175], v[196:199], v[80:83]
	v_mfma_f32_16x16x32_bf16 v[68:71], v[164:167], v[204:207], v[68:71]
	v_mfma_f32_16x16x32_bf16 v[64:67], v[172:175], v[204:207], v[64:67]
	s_setprio 0
	s_barrier
	s_add_i32 s66, s66, s48
	v_lshl_add_u64 v[214:215], s[22:23], 0, v[208:209]
	s_mov_b32 m0, s66
	ds_read_b128 v[176:179], v146 offset:16384
	ds_read_b128 v[180:183], v146 offset:17408
	ds_read_b128 v[184:187], v146 offset:18432
	ds_read_b128 v[188:191], v146 offset:19456
	ds_read_b128 v[192:195], v146 offset:20480
	ds_read_b128 v[196:199], v146 offset:21504
	ds_read_b128 v[200:203], v146 offset:22528
	ds_read_b128 v[204:207], v146 offset:23552
	global_load_lds_dwordx4 v[214:215], off
	s_add_i32 m0, s66, 0x2000
	s_add_u32 s68, s22, 0x20000
	v_lshl_add_u64 v[216:217], s[22:23], 0, v[128:129]
	s_addc_u32 s69, s23, 0
	s_add_i32 s66, s71, s48
	global_load_lds_dwordx4 v[216:217], off
	s_mov_b32 m0, s66
	v_lshl_add_u64 v[226:227], s[46:47], 0, v[130:131]
	global_load_lds_dwordx4 v208, s[68:69]
	s_add_i32 m0, s66, 0x2000
	s_nop 0
	global_load_lds_dwordx4 v128, s[68:69]
	v_lshl_add_u64 v[224:225], s[46:47], 0, v[132:133]
	s_mov_b32 m0, s51
	s_nop 0
	global_load_lds_dwordx4 v[224:225], off
	s_mov_b32 m0, s54
	s_nop 0
	global_load_lds_dwordx4 v[226:227], off
	s_waitcnt vmcnt(8)
	s_waitcnt lgkmcnt(0)
	s_barrier
	s_setprio 1
	s_waitcnt lgkmcnt(0)
	v_mfma_f32_16x16x32_bf16 v[60:63], v[138:141], v[176:179], v[60:63]
	v_mfma_f32_16x16x32_bf16 v[56:59], v[152:155], v[176:179], v[56:59]
	v_mfma_f32_16x16x32_bf16 v[44:47], v[138:141], v[184:187], v[44:47]
	v_mfma_f32_16x16x32_bf16 v[40:43], v[152:155], v[184:187], v[40:43]
	v_mfma_f32_16x16x32_bf16 v[28:31], v[138:141], v[192:195], v[28:31]
	v_mfma_f32_16x16x32_bf16 v[24:27], v[152:155], v[192:195], v[24:27]
	v_mfma_f32_16x16x32_bf16 v[12:15], v[138:141], v[200:203], v[12:15]
	v_mfma_f32_16x16x32_bf16 v[8:11], v[152:155], v[200:203], v[8:11]
	v_mfma_f32_16x16x32_bf16 v[60:63], v[148:151], v[180:183], v[60:63]
	v_mfma_f32_16x16x32_bf16 v[56:59], v[156:159], v[180:183], v[56:59]
	v_mfma_f32_16x16x32_bf16 v[44:47], v[148:151], v[188:191], v[44:47]
	v_mfma_f32_16x16x32_bf16 v[40:43], v[156:159], v[188:191], v[40:43]
	v_mfma_f32_16x16x32_bf16 v[28:31], v[148:151], v[196:199], v[28:31]
	v_mfma_f32_16x16x32_bf16 v[24:27], v[156:159], v[196:199], v[24:27]
	v_mfma_f32_16x16x32_bf16 v[12:15], v[148:151], v[204:207], v[12:15]
	v_mfma_f32_16x16x32_bf16 v[8:11], v[156:159], v[204:207], v[8:11]
	s_setprio 0
	s_setprio 1
	v_mfma_f32_16x16x32_bf16 v[52:55], v[160:163], v[176:179], v[52:55]
	v_mfma_f32_16x16x32_bf16 v[48:51], v[168:171], v[176:179], v[48:51]
	v_mfma_f32_16x16x32_bf16 v[36:39], v[160:163], v[184:187], v[36:39]
	v_mfma_f32_16x16x32_bf16 v[32:35], v[168:171], v[184:187], v[32:35]
	v_mfma_f32_16x16x32_bf16 v[20:23], v[160:163], v[192:195], v[20:23]
	v_mfma_f32_16x16x32_bf16 v[16:19], v[168:171], v[192:195], v[16:19]
	v_mfma_f32_16x16x32_bf16 v[4:7], v[160:163], v[200:203], v[4:7]
	v_mfma_f32_16x16x32_bf16 v[0:3], v[168:171], v[200:203], v[0:3]
	v_mfma_f32_16x16x32_bf16 v[52:55], v[164:167], v[180:183], v[52:55]
	v_mfma_f32_16x16x32_bf16 v[48:51], v[172:175], v[180:183], v[48:51]
	v_mfma_f32_16x16x32_bf16 v[36:39], v[164:167], v[188:191], v[36:39]
	v_mfma_f32_16x16x32_bf16 v[32:35], v[172:175], v[188:191], v[32:35]
	v_mfma_f32_16x16x32_bf16 v[20:23], v[164:167], v[196:199], v[20:23]
	v_mfma_f32_16x16x32_bf16 v[16:19], v[172:175], v[196:199], v[16:19]
	v_mfma_f32_16x16x32_bf16 v[4:7], v[164:167], v[204:207], v[4:7]
	v_mfma_f32_16x16x32_bf16 v[0:3], v[172:175], v[204:207], v[0:3]
	s_setprio 0
	s_barrier
	s_add_i32 s66, 0, 0x18000
	v_add_u32_e32 v147, s66, v144
	s_add_i32 s68, 0, 0x1c000
	ds_read_b128 v[138:141], v147
	ds_read_b128 v[148:151], v147 offset:1024
	ds_read_b128 v[152:155], v147 offset:2048
	ds_read_b128 v[156:159], v147 offset:3072
	v_add_u32_e32 v147, s68, v144
	ds_read_b128 v[160:163], v147
	ds_read_b128 v[164:167], v147 offset:1024
	ds_read_b128 v[168:171], v147 offset:2048
	ds_read_b128 v[172:175], v147 offset:3072
	s_add_u32 s46, s46, 0x20000
	s_addc_u32 s47, s47, 0
	s_mov_b32 m0, s55
	ds_read_b128 v[176:179], v146 offset:32768
	ds_read_b128 v[180:183], v146 offset:33792
	ds_read_b128 v[184:187], v146 offset:34816
	ds_read_b128 v[188:191], v146 offset:35840
	ds_read_b128 v[192:195], v146 offset:36864
	ds_read_b128 v[196:199], v146 offset:37888
	ds_read_b128 v[200:203], v146 offset:38912
	ds_read_b128 v[204:207], v146 offset:39936
	global_load_lds_dwordx4 v132, s[46:47]
	s_mov_b32 m0, s60
	s_nop 0
	global_load_lds_dwordx4 v130, s[46:47]
	s_waitcnt vmcnt(8)
	s_waitcnt lgkmcnt(0)
	s_barrier
	s_setprio 1
	s_waitcnt lgkmcnt(0)
	v_mfma_f32_16x16x32_bf16 v[124:127], v[138:141], v[176:179], v[124:127]
	v_mfma_f32_16x16x32_bf16 v[120:123], v[152:155], v[176:179], v[120:123]
	v_mfma_f32_16x16x32_bf16 v[108:111], v[138:141], v[184:187], v[108:111]
	v_mfma_f32_16x16x32_bf16 v[104:107], v[152:155], v[184:187], v[104:107]
	v_mfma_f32_16x16x32_bf16 v[92:95], v[138:141], v[192:195], v[92:95]
	v_mfma_f32_16x16x32_bf16 v[88:91], v[152:155], v[192:195], v[88:91]
	v_mfma_f32_16x16x32_bf16 v[76:79], v[138:141], v[200:203], v[76:79]
	v_mfma_f32_16x16x32_bf16 v[72:75], v[152:155], v[200:203], v[72:75]
	v_mfma_f32_16x16x32_bf16 v[124:127], v[148:151], v[180:183], v[124:127]
	v_mfma_f32_16x16x32_bf16 v[120:123], v[156:159], v[180:183], v[120:123]
	v_mfma_f32_16x16x32_bf16 v[108:111], v[148:151], v[188:191], v[108:111]
	v_mfma_f32_16x16x32_bf16 v[104:107], v[156:159], v[188:191], v[104:107]
	v_mfma_f32_16x16x32_bf16 v[92:95], v[148:151], v[196:199], v[92:95]
	v_mfma_f32_16x16x32_bf16 v[88:91], v[156:159], v[196:199], v[88:91]
	v_mfma_f32_16x16x32_bf16 v[76:79], v[148:151], v[204:207], v[76:79]
	v_mfma_f32_16x16x32_bf16 v[72:75], v[156:159], v[204:207], v[72:75]
	s_setprio 0
	s_setprio 1
	v_mfma_f32_16x16x32_bf16 v[116:119], v[160:163], v[176:179], v[116:119]
	v_mfma_f32_16x16x32_bf16 v[112:115], v[168:171], v[176:179], v[112:115]
	v_mfma_f32_16x16x32_bf16 v[100:103], v[160:163], v[184:187], v[100:103]
	v_mfma_f32_16x16x32_bf16 v[96:99], v[168:171], v[184:187], v[96:99]
	v_mfma_f32_16x16x32_bf16 v[84:87], v[160:163], v[192:195], v[84:87]
	v_mfma_f32_16x16x32_bf16 v[80:83], v[168:171], v[192:195], v[80:83]
	v_mfma_f32_16x16x32_bf16 v[68:71], v[160:163], v[200:203], v[68:71]
	v_mfma_f32_16x16x32_bf16 v[64:67], v[168:171], v[200:203], v[64:67]
	v_mfma_f32_16x16x32_bf16 v[116:119], v[164:167], v[180:183], v[116:119]
	v_mfma_f32_16x16x32_bf16 v[112:115], v[172:175], v[180:183], v[112:115]
	v_mfma_f32_16x16x32_bf16 v[100:103], v[164:167], v[188:191], v[100:103]
	v_mfma_f32_16x16x32_bf16 v[96:99], v[172:175], v[188:191], v[96:99]
	v_mfma_f32_16x16x32_bf16 v[84:87], v[164:167], v[196:199], v[84:87]
	v_mfma_f32_16x16x32_bf16 v[80:83], v[172:175], v[196:199], v[80:83]
	v_mfma_f32_16x16x32_bf16 v[68:71], v[164:167], v[204:207], v[68:71]
	v_mfma_f32_16x16x32_bf16 v[64:67], v[172:175], v[204:207], v[64:67]
	s_setprio 0
	s_barrier
	s_add_i32 s46, s66, s48
	v_lshl_add_u64 v[214:215], v[214:215], 0, s[92:93]
	s_mov_b32 m0, s46
	ds_read_b128 v[176:179], v146 offset:49152
	ds_read_b128 v[180:183], v146 offset:50176
	ds_read_b128 v[184:187], v146 offset:51200
	ds_read_b128 v[188:191], v146 offset:52224
	ds_read_b128 v[192:195], v146 offset:53248
	ds_read_b128 v[196:199], v146 offset:54272
	ds_read_b128 v[200:203], v146 offset:55296
	ds_read_b128 v[204:207], v146 offset:56320
	global_load_lds_dwordx4 v[214:215], off
	s_add_i32 m0, s46, 0x2000
	s_add_u32 s22, s22, 0x20080
	v_lshl_add_u64 v[214:215], v[216:217], 0, s[92:93]
	s_addc_u32 s23, s23, 0
	s_add_i32 s46, s68, s48
	global_load_lds_dwordx4 v[214:215], off
	s_mov_b32 m0, s46
	s_nop 0
	global_load_lds_dwordx4 v208, s[22:23]
	s_add_i32 m0, s46, 0x2000
	s_nop 0
	global_load_lds_dwordx4 v128, s[22:23]
	v_lshl_add_u64 v[214:215], v[224:225], 0, s[92:93]
	s_mov_b32 m0, s61
	s_nop 0
	global_load_lds_dwordx4 v[214:215], off
	v_lshl_add_u64 v[214:215], v[226:227], 0, s[92:93]
	s_mov_b32 m0, s67
	s_nop 0
	global_load_lds_dwordx4 v[214:215], off
	s_waitcnt vmcnt(8)
	s_waitcnt lgkmcnt(0)
	s_barrier
	s_setprio 1
	s_waitcnt lgkmcnt(0)
	v_mfma_f32_16x16x32_bf16 v[60:63], v[138:141], v[176:179], v[60:63]
	v_mfma_f32_16x16x32_bf16 v[56:59], v[152:155], v[176:179], v[56:59]
	v_mfma_f32_16x16x32_bf16 v[44:47], v[138:141], v[184:187], v[44:47]
	v_mfma_f32_16x16x32_bf16 v[40:43], v[152:155], v[184:187], v[40:43]
	v_mfma_f32_16x16x32_bf16 v[28:31], v[138:141], v[192:195], v[28:31]
	v_mfma_f32_16x16x32_bf16 v[24:27], v[152:155], v[192:195], v[24:27]
	v_mfma_f32_16x16x32_bf16 v[12:15], v[138:141], v[200:203], v[12:15]
	v_mfma_f32_16x16x32_bf16 v[8:11], v[152:155], v[200:203], v[8:11]
	v_mfma_f32_16x16x32_bf16 v[60:63], v[148:151], v[180:183], v[60:63]
	v_mfma_f32_16x16x32_bf16 v[56:59], v[156:159], v[180:183], v[56:59]
	v_mfma_f32_16x16x32_bf16 v[44:47], v[148:151], v[188:191], v[44:47]
	v_mfma_f32_16x16x32_bf16 v[40:43], v[156:159], v[188:191], v[40:43]
	v_mfma_f32_16x16x32_bf16 v[28:31], v[148:151], v[196:199], v[28:31]
	v_mfma_f32_16x16x32_bf16 v[24:27], v[156:159], v[196:199], v[24:27]
	v_mfma_f32_16x16x32_bf16 v[12:15], v[148:151], v[204:207], v[12:15]
	v_mfma_f32_16x16x32_bf16 v[8:11], v[156:159], v[204:207], v[8:11]
	s_setprio 0
	s_setprio 1
	v_mfma_f32_16x16x32_bf16 v[52:55], v[160:163], v[176:179], v[52:55]
	v_mfma_f32_16x16x32_bf16 v[48:51], v[168:171], v[176:179], v[48:51]
	v_mfma_f32_16x16x32_bf16 v[36:39], v[160:163], v[184:187], v[36:39]
	v_mfma_f32_16x16x32_bf16 v[32:35], v[168:171], v[184:187], v[32:35]
	v_mfma_f32_16x16x32_bf16 v[20:23], v[160:163], v[192:195], v[20:23]
	v_mfma_f32_16x16x32_bf16 v[16:19], v[168:171], v[192:195], v[16:19]
	v_mfma_f32_16x16x32_bf16 v[4:7], v[160:163], v[200:203], v[4:7]
	v_mfma_f32_16x16x32_bf16 v[0:3], v[168:171], v[200:203], v[0:3]
	v_mfma_f32_16x16x32_bf16 v[52:55], v[164:167], v[180:183], v[52:55]
	v_mfma_f32_16x16x32_bf16 v[48:51], v[172:175], v[180:183], v[48:51]
	v_mfma_f32_16x16x32_bf16 v[36:39], v[164:167], v[188:191], v[36:39]
	v_mfma_f32_16x16x32_bf16 v[32:35], v[172:175], v[188:191], v[32:35]
	v_mfma_f32_16x16x32_bf16 v[20:23], v[164:167], v[196:199], v[20:23]
	v_mfma_f32_16x16x32_bf16 v[16:19], v[172:175], v[196:199], v[16:19]
	v_mfma_f32_16x16x32_bf16 v[4:7], v[164:167], v[204:207], v[4:7]
	v_mfma_f32_16x16x32_bf16 v[0:3], v[172:175], v[204:207], v[0:3]
	s_setprio 0
	s_barrier
	s_add_i32 s41, s41, 2
	s_add_u32 s0, s0, 0x100
	s_addc_u32 s1, s1, 0
	s_add_u32 s34, s34, 0x100
	s_addc_u32 s39, s39, 0
	s_cmp_gt_u32 s41, 5
	s_cbranch_scc0 .LBB0_1329
	s_and_b64 vcc, exec, s[36:37]
	s_cbranch_vccz .LBB0_1332
	s_barrier

.LBB0_1414:
	s_add_u32 s74, s34, 0x5000
	s_addc_u32 s75, s54, 0
	s_lshl_b32 s6, s6, 5
	s_and_b32 s25, s6, 0x60
	s_add_i32 m0, s71, 0x18000
	v_lshl_add_u64 v[6:7], v[6:7], 0, s[92:93]
	v_writelane_b32 v253, s34, 57
	s_lshl_b32 s24, s1, 13
	s_lshl_b32 s30, s25, 7
	s_waitcnt vmcnt(2)
	s_barrier
	global_load_lds_dwordx4 v[6:7], off
	v_lshl_add_u64 v[4:5], v[4:5], 0, s[92:93]
	s_add_i32 m0, s71, 0x1a000
	s_add_i32 s55, s71, 0x8000
	s_add_i32 s34, s71, 0xa000
	global_load_lds_dwordx4 v[4:5], off
	v_lshl_add_u64 v[0:1], v[0:1], 0, s[92:93]
	s_mov_b32 m0, s55
	s_add_u32 s6, s48, 0x40080
	global_load_lds_dwordx4 v[0:1], off
	v_lshl_add_u64 v[0:1], v[2:3], 0, s[92:93]
	s_mov_b32 m0, s34
	s_addc_u32 s7, s49, 0
	global_load_lds_dwordx4 v[0:1], off
	s_add_i32 m0, s71, 0x1c000
	s_nop 0
	global_load_lds_dwordx4 v208, s[6:7]
	s_add_i32 m0, s71, 0x1e000
	v_bfe_u32 v4, v12, 4, 2
	global_load_lds_dwordx4 v144, s[6:7]
	v_and_b32_e32 v1, 15, v12
	v_lshlrev_b32_e32 v2, 4, v4
	v_lshl_or_b32 v0, s1, 6, v1
	v_lshl_or_b32 v1, v1, 6, v2
	v_lshlrev_b32_e32 v2, 2, v12
	v_and_b32_e32 v2, 32, v2
	v_bitop3_b32 v5, v1, s24, v2 bitop3:0xde
	v_bitop3_b32 v170, v1, s30, v2 bitop3:0xde
	v_or_b32_e32 v2, 16, v0
	v_ashrrev_i32_e32 v3, 31, v2
	v_lshlrev_b64 v[148:149], 12, v[2:3]
	v_or_b32_e32 v2, 32, v0
	v_ashrrev_i32_e32 v3, 31, v2
	v_lshlrev_b64 v[150:151], 12, v[2:3]
	v_or_b32_e32 v2, 48, v0
	v_ashrrev_i32_e32 v3, 31, v2
	v_lshlrev_b64 v[152:153], 12, v[2:3]
	v_add_u32_e32 v2, 0x90, v0
	v_ashrrev_i32_e32 v1, 31, v0
	v_ashrrev_i32_e32 v3, 31, v2
	v_lshlrev_b64 v[146:147], 12, v[0:1]
	v_lshlrev_b64 v[156:157], 12, v[2:3]
	v_add_u32_e32 v2, 0xa0, v0
	v_add_u32_e32 v0, 0xb0, v0
	v_ashrrev_i32_e32 v1, 31, v0
	v_lshlrev_b64 v[160:161], 12, v[0:1]
	v_lshlrev_b32_e32 v0, 13, v14
	v_and_b32_e32 v0, 0x7fffc000, v0
	v_lshl_add_u32 v0, v13, 10, v0
	v_or_b32_e32 v0, v0, v15
	s_cmpk_lt_u32 s0, 0x100
	v_add_lshl_u32 v0, v0, v16, 1
	v_mov_b32_e32 v1, v209
	s_mov_b64 s[0:1], 0x40080
	v_lshl_add_u64 v[162:163], v[0:1], 0, s[0:1]
	v_lshlrev_b32_e32 v0, 13, v8
	v_and_b32_e32 v0, 0x7fffc000, v0
	v_lshl_add_u32 v0, v9, 10, v0
	s_waitcnt vmcnt(6)
	v_or_b32_e32 v0, v0, v10
	v_ashrrev_i32_e32 v3, 31, v2
	v_add_lshl_u32 v0, v0, v11, 1
	s_cselect_b64 s[38:39], -1, 0
	v_lshl_add_u64 v[154:155], v[146:147], 0, s[28:29]
	v_lshlrev_b64 v[158:159], 12, v[2:3]
	v_lshl_or_b32 v171, v4, 2, s25
	v_lshl_add_u64 v[164:165], v[0:1], 0, s[0:1]
	s_mov_b32 s66, 0
	v_add_u32_e32 v172, 0, v5
	v_readlane_b32 s35, v252, 55
	v_readlane_b32 s0, v252, 53
	s_barrier
	v_readlane_b32 s1, v252, 54
	s_branch .LBB0_1417

.LBB0_1424:
	s_add_u32 s48, s22, 0x100
	s_addc_u32 s49, s23, 0
	s_add_i32 s80, 0, 0x10000
	s_cmp_eq_u32 s43, 12
	s_cselect_b32 s69, s1, s49
	s_cselect_b32 s68, s24, s48
	s_cselect_b32 s51, s25, s41
	s_cselect_b32 s50, s30, s31
	s_add_i32 vcc_lo, 0, 0x14000
	v_add_u32_e32 v92, s80, v170
	v_add_u32_e32 v173, vcc_lo, v170
	ds_read_b128 v[72:75], v92
	ds_read_b128 v[80:83], v92 offset:1024
	ds_read_b128 v[88:91], v92 offset:2048
	ds_read_b128 v[92:95], v92 offset:3072
	ds_read_b128 v[166:169], v173
	ds_read_b128 v[174:177], v173 offset:1024
	ds_read_b128 v[178:181], v173 offset:2048
	ds_read_b128 v[182:185], v173 offset:3072
	v_lshl_add_u64 v[232:233], s[22:23], 0, v[162:163]
	s_add_i32 m0, s71, 0xc000
	ds_read_b128 v[188:191], v172
	ds_read_b128 v[192:195], v172 offset:1024
	ds_read_b128 v[196:199], v172 offset:2048
	ds_read_b128 v[200:203], v172 offset:3072
	ds_read_b128 v[204:207], v172 offset:4096
	ds_read_b128 v[214:217], v172 offset:5120
	ds_read_b128 v[224:227], v172 offset:6144
	ds_read_b128 v[228:231], v172 offset:7168
	global_load_lds_dwordx4 v[232:233], off
	v_lshl_add_u64 v[232:233], s[22:23], 0, v[164:165]
	s_add_i32 m0, s71, 0xe000
	s_nop 0
	global_load_lds_dwordx4 v[232:233], off
	s_waitcnt vmcnt(8)
	s_waitcnt lgkmcnt(0)
	s_barrier
	s_setprio 1
	s_waitcnt lgkmcnt(0)
	v_mfma_f32_16x16x32_bf16 v[140:143], v[72:75], v[188:191], v[140:143]
	v_mfma_f32_16x16x32_bf16 v[136:139], v[88:91], v[188:191], v[136:139]
	v_mfma_f32_16x16x32_bf16 v[124:127], v[72:75], v[196:199], v[124:127]
	v_mfma_f32_16x16x32_bf16 v[120:123], v[88:91], v[196:199], v[120:123]
	v_mfma_f32_16x16x32_bf16 v[108:111], v[72:75], v[204:207], v[108:111]
	v_mfma_f32_16x16x32_bf16 v[104:107], v[88:91], v[204:207], v[104:107]
	v_mfma_f32_16x16x32_bf16 v[84:87], v[72:75], v[224:227], v[84:87]
	v_mfma_f32_16x16x32_bf16 v[76:79], v[88:91], v[224:227], v[76:79]
	v_mfma_f32_16x16x32_bf16 v[140:143], v[80:83], v[192:195], v[140:143]
	v_mfma_f32_16x16x32_bf16 v[136:139], v[92:95], v[192:195], v[136:139]
	v_mfma_f32_16x16x32_bf16 v[124:127], v[80:83], v[200:203], v[124:127]
	v_mfma_f32_16x16x32_bf16 v[120:123], v[92:95], v[200:203], v[120:123]
	v_mfma_f32_16x16x32_bf16 v[108:111], v[80:83], v[214:217], v[108:111]
	v_mfma_f32_16x16x32_bf16 v[104:107], v[92:95], v[214:217], v[104:107]
	v_mfma_f32_16x16x32_bf16 v[84:87], v[80:83], v[228:231], v[84:87]
	v_mfma_f32_16x16x32_bf16 v[76:79], v[92:95], v[228:231], v[76:79]
	s_setprio 0
	s_setprio 1
	v_mfma_f32_16x16x32_bf16 v[132:135], v[166:169], v[188:191], v[132:135]
	v_mfma_f32_16x16x32_bf16 v[128:131], v[178:181], v[188:191], v[128:131]
	v_mfma_f32_16x16x32_bf16 v[116:119], v[166:169], v[196:199], v[116:119]
	v_mfma_f32_16x16x32_bf16 v[112:115], v[178:181], v[196:199], v[112:115]
	v_mfma_f32_16x16x32_bf16 v[100:103], v[166:169], v[204:207], v[100:103]
	v_mfma_f32_16x16x32_bf16 v[96:99], v[178:181], v[204:207], v[96:99]
	v_mfma_f32_16x16x32_bf16 v[68:71], v[166:169], v[224:227], v[68:71]
	v_mfma_f32_16x16x32_bf16 v[64:67], v[178:181], v[224:227], v[64:67]
	v_mfma_f32_16x16x32_bf16 v[132:135], v[174:177], v[192:195], v[132:135]
	v_mfma_f32_16x16x32_bf16 v[128:131], v[182:185], v[192:195], v[128:131]
	v_mfma_f32_16x16x32_bf16 v[116:119], v[174:177], v[200:203], v[116:119]
	v_mfma_f32_16x16x32_bf16 v[112:115], v[182:185], v[200:203], v[112:115]
	v_mfma_f32_16x16x32_bf16 v[100:103], v[174:177], v[214:217], v[100:103]
	v_mfma_f32_16x16x32_bf16 v[96:99], v[182:185], v[214:217], v[96:99]
	v_mfma_f32_16x16x32_bf16 v[68:71], v[174:177], v[228:231], v[68:71]
	v_mfma_f32_16x16x32_bf16 v[64:67], v[182:185], v[228:231], v[64:67]
	s_setprio 0
	s_barrier
	s_add_i32 s22, s80, s70
	v_lshl_add_u64 v[232:233], s[50:51], 0, v[208:209]
	s_mov_b32 m0, s22
	ds_read_b128 v[188:191], v172 offset:16384
	ds_read_b128 v[192:195], v172 offset:17408
	ds_read_b128 v[196:199], v172 offset:18432
	ds_read_b128 v[200:203], v172 offset:19456
	ds_read_b128 v[204:207], v172 offset:20480
	ds_read_b128 v[214:217], v172 offset:21504
	ds_read_b128 v[224:227], v172 offset:22528
	ds_read_b128 v[228:231], v172 offset:23552
	global_load_lds_dwordx4 v[232:233], off
	s_add_i32 m0, s22, 0x2000
	s_add_u32 s22, s50, 0x40000
	v_lshl_add_u64 v[234:235], s[50:51], 0, v[144:145]
	s_addc_u32 s23, s51, 0
	s_add_i32 s80, vcc_lo, s70
	global_load_lds_dwordx4 v[234:235], off
	s_mov_b32 m0, s80
	v_lshl_add_u64 v[240:241], s[68:69], 0, v[144:145]
	global_load_lds_dwordx4 v208, s[22:23]
	s_add_i32 m0, s80, 0x2000
	s_nop 0
	global_load_lds_dwordx4 v144, s[22:23]
	v_lshl_add_u64 v[238:239], s[68:69], 0, v[208:209]
	s_mov_b32 m0, s71
	s_nop 0
	global_load_lds_dwordx4 v[238:239], off
	s_mov_b32 m0, s4
	s_nop 0
	global_load_lds_dwordx4 v[240:241], off
	s_waitcnt vmcnt(8)
	s_waitcnt lgkmcnt(0)
	s_barrier
	s_setprio 1
	s_waitcnt lgkmcnt(0)
	v_mfma_f32_16x16x32_bf16 v[60:63], v[72:75], v[188:191], v[60:63]
	v_mfma_f32_16x16x32_bf16 v[56:59], v[88:91], v[188:191], v[56:59]
	v_mfma_f32_16x16x32_bf16 v[44:47], v[72:75], v[196:199], v[44:47]
	v_mfma_f32_16x16x32_bf16 v[40:43], v[88:91], v[196:199], v[40:43]
	v_mfma_f32_16x16x32_bf16 v[28:31], v[72:75], v[204:207], v[28:31]
	v_mfma_f32_16x16x32_bf16 v[24:27], v[88:91], v[204:207], v[24:27]
	v_mfma_f32_16x16x32_bf16 v[12:15], v[72:75], v[224:227], v[12:15]
	v_mfma_f32_16x16x32_bf16 v[8:11], v[88:91], v[224:227], v[8:11]
	v_mfma_f32_16x16x32_bf16 v[60:63], v[80:83], v[192:195], v[60:63]
	v_mfma_f32_16x16x32_bf16 v[56:59], v[92:95], v[192:195], v[56:59]
	v_mfma_f32_16x16x32_bf16 v[44:47], v[80:83], v[200:203], v[44:47]
	v_mfma_f32_16x16x32_bf16 v[40:43], v[92:95], v[200:203], v[40:43]
	v_mfma_f32_16x16x32_bf16 v[28:31], v[80:83], v[214:217], v[28:31]
	v_mfma_f32_16x16x32_bf16 v[24:27], v[92:95], v[214:217], v[24:27]
	v_mfma_f32_16x16x32_bf16 v[12:15], v[80:83], v[228:231], v[12:15]
	v_mfma_f32_16x16x32_bf16 v[8:11], v[92:95], v[228:231], v[8:11]
	s_setprio 0
	s_setprio 1
	v_mfma_f32_16x16x32_bf16 v[52:55], v[166:169], v[188:191], v[52:55]
	v_mfma_f32_16x16x32_bf16 v[48:51], v[178:181], v[188:191], v[48:51]
	v_mfma_f32_16x16x32_bf16 v[36:39], v[166:169], v[196:199], v[36:39]
	v_mfma_f32_16x16x32_bf16 v[32:35], v[178:181], v[196:199], v[32:35]
	v_mfma_f32_16x16x32_bf16 v[20:23], v[166:169], v[204:207], v[20:23]
	v_mfma_f32_16x16x32_bf16 v[16:19], v[178:181], v[204:207], v[16:19]
	v_mfma_f32_16x16x32_bf16 v[4:7], v[166:169], v[224:227], v[4:7]
	v_mfma_f32_16x16x32_bf16 v[0:3], v[178:181], v[224:227], v[0:3]
	v_mfma_f32_16x16x32_bf16 v[52:55], v[174:177], v[192:195], v[52:55]
	v_mfma_f32_16x16x32_bf16 v[48:51], v[182:185], v[192:195], v[48:51]
	v_mfma_f32_16x16x32_bf16 v[36:39], v[174:177], v[200:203], v[36:39]
	v_mfma_f32_16x16x32_bf16 v[32:35], v[182:185], v[200:203], v[32:35]
	v_mfma_f32_16x16x32_bf16 v[20:23], v[174:177], v[214:217], v[20:23]
	v_mfma_f32_16x16x32_bf16 v[16:19], v[182:185], v[214:217], v[16:19]
	v_mfma_f32_16x16x32_bf16 v[4:7], v[174:177], v[228:231], v[4:7]
	v_mfma_f32_16x16x32_bf16 v[0:3], v[182:185], v[228:231], v[0:3]
	s_setprio 0
	s_barrier
	s_add_i32 s80, 0, 0x18000
	s_add_i32 vcc_lo, 0, 0x1c000
	v_add_u32_e32 v92, s80, v170
	v_add_u32_e32 v173, vcc_lo, v170
	ds_read_b128 v[72:75], v92
	ds_read_b128 v[80:83], v92 offset:1024
	ds_read_b128 v[88:91], v92 offset:2048
	ds_read_b128 v[92:95], v92 offset:3072
	ds_read_b128 v[166:169], v173
	ds_read_b128 v[174:177], v173 offset:1024
	ds_read_b128 v[178:181], v173 offset:2048
	ds_read_b128 v[182:185], v173 offset:3072
	s_add_u32 s22, s68, 0x40000
	s_addc_u32 s23, s69, 0
	s_mov_b32 m0, s5
	ds_read_b128 v[188:191], v172 offset:32768
	ds_read_b128 v[192:195], v172 offset:33792
	ds_read_b128 v[196:199], v172 offset:34816
	ds_read_b128 v[200:203], v172 offset:35840
	ds_read_b128 v[204:207], v172 offset:36864
	ds_read_b128 v[214:217], v172 offset:37888
	ds_read_b128 v[224:227], v172 offset:38912
	ds_read_b128 v[228:231], v172 offset:39936
	global_load_lds_dwordx4 v208, s[22:23]
	s_mov_b32 m0, s73
	s_nop 0
	global_load_lds_dwordx4 v144, s[22:23]
	s_waitcnt vmcnt(8)
	s_waitcnt lgkmcnt(0)
	s_barrier
	s_setprio 1
	s_waitcnt lgkmcnt(0)
	v_mfma_f32_16x16x32_bf16 v[140:143], v[72:75], v[188:191], v[140:143]
	v_mfma_f32_16x16x32_bf16 v[136:139], v[88:91], v[188:191], v[136:139]
	v_mfma_f32_16x16x32_bf16 v[124:127], v[72:75], v[196:199], v[124:127]
	v_mfma_f32_16x16x32_bf16 v[120:123], v[88:91], v[196:199], v[120:123]
	v_mfma_f32_16x16x32_bf16 v[108:111], v[72:75], v[204:207], v[108:111]
	v_mfma_f32_16x16x32_bf16 v[104:107], v[88:91], v[204:207], v[104:107]
	v_mfma_f32_16x16x32_bf16 v[84:87], v[72:75], v[224:227], v[84:87]
	v_mfma_f32_16x16x32_bf16 v[76:79], v[88:91], v[224:227], v[76:79]
	v_mfma_f32_16x16x32_bf16 v[140:143], v[80:83], v[192:195], v[140:143]
	v_mfma_f32_16x16x32_bf16 v[136:139], v[92:95], v[192:195], v[136:139]
	v_mfma_f32_16x16x32_bf16 v[124:127], v[80:83], v[200:203], v[124:127]
	v_mfma_f32_16x16x32_bf16 v[120:123], v[92:95], v[200:203], v[120:123]
	v_mfma_f32_16x16x32_bf16 v[108:111], v[80:83], v[214:217], v[108:111]
	v_mfma_f32_16x16x32_bf16 v[104:107], v[92:95], v[214:217], v[104:107]
	v_mfma_f32_16x16x32_bf16 v[84:87], v[80:83], v[228:231], v[84:87]
	v_mfma_f32_16x16x32_bf16 v[76:79], v[92:95], v[228:231], v[76:79]
	s_setprio 0
	s_setprio 1
	v_mfma_f32_16x16x32_bf16 v[132:135], v[166:169], v[188:191], v[132:135]
	v_mfma_f32_16x16x32_bf16 v[128:131], v[178:181], v[188:191], v[128:131]
	v_mfma_f32_16x16x32_bf16 v[116:119], v[166:169], v[196:199], v[116:119]
	v_mfma_f32_16x16x32_bf16 v[112:115], v[178:181], v[196:199], v[112:115]
	v_mfma_f32_16x16x32_bf16 v[100:103], v[166:169], v[204:207], v[100:103]
	v_mfma_f32_16x16x32_bf16 v[96:99], v[178:181], v[204:207], v[96:99]
	v_mfma_f32_16x16x32_bf16 v[68:71], v[166:169], v[224:227], v[68:71]
	v_mfma_f32_16x16x32_bf16 v[64:67], v[178:181], v[224:227], v[64:67]
	v_mfma_f32_16x16x32_bf16 v[132:135], v[174:177], v[192:195], v[132:135]
	v_mfma_f32_16x16x32_bf16 v[128:131], v[182:185], v[192:195], v[128:131]
	v_mfma_f32_16x16x32_bf16 v[116:119], v[174:177], v[200:203], v[116:119]
	v_mfma_f32_16x16x32_bf16 v[112:115], v[182:185], v[200:203], v[112:115]
	v_mfma_f32_16x16x32_bf16 v[100:103], v[174:177], v[214:217], v[100:103]
	v_mfma_f32_16x16x32_bf16 v[96:99], v[182:185], v[214:217], v[96:99]
	v_mfma_f32_16x16x32_bf16 v[68:71], v[174:177], v[228:231], v[68:71]
	v_mfma_f32_16x16x32_bf16 v[64:67], v[182:185], v[228:231], v[64:67]
	s_setprio 0
	s_barrier
	s_add_i32 s22, s80, s70
	v_lshl_add_u64 v[232:233], v[232:233], 0, s[92:93]
	s_mov_b32 m0, s22
	ds_read_b128 v[188:191], v172 offset:49152
	ds_read_b128 v[192:195], v172 offset:50176
	ds_read_b128 v[196:199], v172 offset:51200
	ds_read_b128 v[200:203], v172 offset:52224
	ds_read_b128 v[204:207], v172 offset:53248
	ds_read_b128 v[214:217], v172 offset:54272
	ds_read_b128 v[224:227], v172 offset:55296
	ds_read_b128 v[228:231], v172 offset:56320
	global_load_lds_dwordx4 v[232:233], off
	s_add_i32 m0, s22, 0x2000
	s_add_u32 s22, s50, 0x40080
	v_lshl_add_u64 v[232:233], v[234:235], 0, s[92:93]
	s_addc_u32 s23, s51, 0
	s_add_i32 s50, vcc_lo, s70
	global_load_lds_dwordx4 v[232:233], off
	s_mov_b32 m0, s50
	s_nop 0
	global_load_lds_dwordx4 v208, s[22:23]
	s_add_i32 m0, s50, 0x2000
	s_nop 0
	global_load_lds_dwordx4 v144, s[22:23]
	v_lshl_add_u64 v[232:233], v[238:239], 0, s[92:93]
	s_mov_b32 m0, s55
	s_nop 0
	global_load_lds_dwordx4 v[232:233], off
	v_lshl_add_u64 v[232:233], v[240:241], 0, s[92:93]
	s_mov_b32 m0, s34
	s_nop 0
	global_load_lds_dwordx4 v[232:233], off
	s_waitcnt vmcnt(8)
	s_waitcnt lgkmcnt(0)
	s_barrier
	s_setprio 1
	s_waitcnt lgkmcnt(0)
	v_mfma_f32_16x16x32_bf16 v[60:63], v[72:75], v[188:191], v[60:63]
	v_mfma_f32_16x16x32_bf16 v[56:59], v[88:91], v[188:191], v[56:59]
	v_mfma_f32_16x16x32_bf16 v[44:47], v[72:75], v[196:199], v[44:47]
	v_mfma_f32_16x16x32_bf16 v[40:43], v[88:91], v[196:199], v[40:43]
	v_mfma_f32_16x16x32_bf16 v[28:31], v[72:75], v[204:207], v[28:31]
	v_mfma_f32_16x16x32_bf16 v[24:27], v[88:91], v[204:207], v[24:27]
	v_mfma_f32_16x16x32_bf16 v[12:15], v[72:75], v[224:227], v[12:15]
	v_mfma_f32_16x16x32_bf16 v[8:11], v[88:91], v[224:227], v[8:11]
	v_mfma_f32_16x16x32_bf16 v[60:63], v[80:83], v[192:195], v[60:63]
	v_mfma_f32_16x16x32_bf16 v[56:59], v[92:95], v[192:195], v[56:59]
	v_mfma_f32_16x16x32_bf16 v[44:47], v[80:83], v[200:203], v[44:47]
	v_mfma_f32_16x16x32_bf16 v[40:43], v[92:95], v[200:203], v[40:43]
	v_mfma_f32_16x16x32_bf16 v[28:31], v[80:83], v[214:217], v[28:31]
	v_mfma_f32_16x16x32_bf16 v[24:27], v[92:95], v[214:217], v[24:27]
	v_mfma_f32_16x16x32_bf16 v[12:15], v[80:83], v[228:231], v[12:15]
	v_mfma_f32_16x16x32_bf16 v[8:11], v[92:95], v[228:231], v[8:11]
	s_setprio 0
	s_setprio 1
	v_mfma_f32_16x16x32_bf16 v[52:55], v[166:169], v[188:191], v[52:55]
	v_mfma_f32_16x16x32_bf16 v[48:51], v[178:181], v[188:191], v[48:51]
	v_mfma_f32_16x16x32_bf16 v[36:39], v[166:169], v[196:199], v[36:39]
	v_mfma_f32_16x16x32_bf16 v[32:35], v[178:181], v[196:199], v[32:35]
	v_mfma_f32_16x16x32_bf16 v[20:23], v[166:169], v[204:207], v[20:23]
	v_mfma_f32_16x16x32_bf16 v[16:19], v[178:181], v[204:207], v[16:19]
	v_mfma_f32_16x16x32_bf16 v[4:7], v[166:169], v[224:227], v[4:7]
	v_mfma_f32_16x16x32_bf16 v[0:3], v[178:181], v[224:227], v[0:3]
	v_mfma_f32_16x16x32_bf16 v[52:55], v[174:177], v[192:195], v[52:55]
	v_mfma_f32_16x16x32_bf16 v[48:51], v[182:185], v[192:195], v[48:51]
	v_mfma_f32_16x16x32_bf16 v[36:39], v[174:177], v[200:203], v[36:39]
	v_mfma_f32_16x16x32_bf16 v[32:35], v[182:185], v[200:203], v[32:35]
	v_mfma_f32_16x16x32_bf16 v[20:23], v[174:177], v[214:217], v[20:23]
	v_mfma_f32_16x16x32_bf16 v[16:19], v[182:185], v[214:217], v[16:19]
	v_mfma_f32_16x16x32_bf16 v[4:7], v[174:177], v[228:231], v[4:7]
	v_mfma_f32_16x16x32_bf16 v[0:3], v[182:185], v[228:231], v[0:3]
	s_setprio 0
	s_barrier
	s_add_i32 s43, s43, 2
	s_add_u32 s31, s31, 0x100
	s_addc_u32 s41, s41, 0
	s_cmp_gt_u32 s43, 13
	s_mov_b64 s[22:23], s[48:49]
	s_cbranch_scc0 .LBB0_1424
	s_and_b64 vcc, exec, s[38:39]
	s_cbranch_vccz .LBB0_1427
	s_barrier

.LBB0_1440:
	v_and_b32_e32 v14, 15, v187
	v_lshl_add_u64 v[6:7], s[50:51], 0, v[208:209]
	v_mov_b32_e32 v113, v209
	v_lshlrev_b32_e32 v188, 6, v14
	v_lshlrev_b32_e32 v15, 2, v187
	v_lshl_add_u64 v[8:9], s[50:51], 0, v[112:113]
	s_and_b32 s27, s22, 3
	v_lshl_or_b32 v148, s26, 6, v14
	s_lshl_b32 s6, s26, 13
	v_and_or_b32 v14, v187, 48, v188
	v_and_b32_e32 v15, 32, v15
	s_add_i32 m0, s39, 0x18000
	v_lshl_add_u64 v[6:7], v[6:7], 0, s[92:93]
	v_lshl_add_u64 v[10:11], s[0:1], 0, v[208:209]
	v_bitop3_b32 v16, v14, s6, v15 bitop3:0xde
	s_lshl_b32 s6, s27, 12
	s_waitcnt vmcnt(2)
	s_barrier
	global_load_lds_dwordx4 v[6:7], off
	v_lshl_add_u64 v[6:7], v[8:9], 0, s[92:93]
	s_add_i32 m0, s39, 0x1a000
	s_add_i32 s73, s39, 0x8000
	s_add_i32 s74, s39, 0xa000
	v_lshl_add_u64 v[12:13], s[0:1], 0, v[112:113]
	v_bitop3_b32 v122, v14, s6, v15 bitop3:0xde
	global_load_lds_dwordx4 v[6:7], off
	v_lshl_add_u64 v[6:7], v[10:11], 0, s[92:93]
	s_mov_b32 m0, s73
	s_add_u32 s6, s50, 0x40080
	global_load_lds_dwordx4 v[6:7], off
	v_lshl_add_u64 v[6:7], v[12:13], 0, s[92:93]
	s_mov_b32 m0, s74
	s_addc_u32 s7, s51, 0
	global_load_lds_dwordx4 v[6:7], off
	s_add_i32 m0, s39, 0x1c000
	s_nop 0
	global_load_lds_dwordx4 v208, s[6:7]
	v_lshl_add_u64 v[6:7], s[6:7], 0, v[112:113]
	s_add_i32 m0, s39, 0x1e000
	v_readlane_b32 s6, v252, 55
	global_load_lds_dwordx4 v[6:7], off
	v_lshlrev_b32_e32 v6, 14, v3
	v_and_b32_e32 v6, 0xffff8000, v6
	v_lshl_add_u32 v4, v4, 11, v6
	v_and_b32_e32 v3, 1, v3
	v_lshl_or_b32 v3, v3, 6, v4
	v_lshl_add_u32 v114, v5, 1, v3
	v_lshlrev_b32_e32 v3, 14, v0
	v_and_b32_e32 v3, 0xffff8000, v3
	v_lshl_add_u32 v1, v1, 11, v3
	v_and_b32_e32 v0, 1, v0
	s_waitcnt vmcnt(6)
	v_lshl_or_b32 v0, v0, 6, v1
	v_lshl_add_u32 v116, v2, 1, v0
	v_mov_b32_e32 v0, 0
	s_mov_b32 s40, s6
	v_readlane_b32 s6, v252, 53
	v_writelane_b32 v253, s22, 59
	v_mov_b32_e32 v115, v209
	v_mov_b32_e32 v117, v209
	s_mov_b32 s75, 0
	v_add_u32_e32 v123, 0, v16
	s_mov_b32 s38, s6
	v_mov_b32_e32 v1, v0
	v_mov_b32_e32 v2, v0
	v_mov_b32_e32 v3, v0
	v_mov_b32_e32 v12, v0
	v_mov_b32_e32 v13, v0
	v_mov_b32_e32 v14, v0
	v_mov_b32_e32 v15, v0
	v_mov_b32_e32 v4, v0
	v_mov_b32_e32 v5, v0
	v_mov_b32_e32 v6, v0
	v_mov_b32_e32 v7, v0
	v_mov_b32_e32 v16, v0
	v_mov_b32_e32 v17, v0
	v_mov_b32_e32 v18, v0
	v_mov_b32_e32 v19, v0
	v_mov_b32_e32 v8, v0
	v_mov_b32_e32 v9, v0
	v_mov_b32_e32 v10, v0
	v_mov_b32_e32 v11, v0
	v_mov_b32_e32 v20, v0
	v_mov_b32_e32 v21, v0
	v_mov_b32_e32 v22, v0
	v_mov_b32_e32 v23, v0
	v_mov_b32_e32 v128, v0
	v_mov_b32_e32 v129, v0
	v_mov_b32_e32 v130, v0
	v_mov_b32_e32 v131, v0
	v_mov_b32_e32 v24, v0
	v_mov_b32_e32 v25, v0
	v_mov_b32_e32 v26, v0
	v_mov_b32_e32 v27, v0
	v_mov_b32_e32 v40, v0
	v_mov_b32_e32 v41, v0
	v_mov_b32_e32 v42, v0
	v_mov_b32_e32 v43, v0
	v_mov_b32_e32 v64, v0
	v_mov_b32_e32 v65, v0
	v_mov_b32_e32 v66, v0
	v_mov_b32_e32 v67, v0
	v_mov_b32_e32 v52, v0
	v_mov_b32_e32 v53, v0
	v_mov_b32_e32 v54, v0
	v_mov_b32_e32 v55, v0
	v_mov_b32_e32 v80, v0
	v_mov_b32_e32 v81, v0
	v_mov_b32_e32 v82, v0
	v_mov_b32_e32 v83, v0
	v_mov_b32_e32 v56, v0
	v_mov_b32_e32 v57, v0
	v_mov_b32_e32 v58, v0
	v_mov_b32_e32 v59, v0
	v_mov_b32_e32 v88, v0
	v_mov_b32_e32 v89, v0
	v_mov_b32_e32 v90, v0
	v_mov_b32_e32 v91, v0
	v_mov_b32_e32 v60, v0
	v_mov_b32_e32 v61, v0
	v_mov_b32_e32 v62, v0
	v_mov_b32_e32 v63, v0
	v_mov_b32_e32 v92, v0
	v_mov_b32_e32 v93, v0
	v_mov_b32_e32 v94, v0
	v_mov_b32_e32 v95, v0
	v_mov_b32_e32 v132, v0
	v_mov_b32_e32 v133, v0
	v_mov_b32_e32 v134, v0
	v_mov_b32_e32 v135, v0
	v_mov_b32_e32 v32, v0
	v_mov_b32_e32 v33, v0
	v_mov_b32_e32 v34, v0
	v_mov_b32_e32 v35, v0
	v_mov_b32_e32 v136, v0
	v_mov_b32_e32 v137, v0
	v_mov_b32_e32 v138, v0
	v_mov_b32_e32 v139, v0
	v_mov_b32_e32 v36, v0
	v_mov_b32_e32 v37, v0
	v_mov_b32_e32 v38, v0
	v_mov_b32_e32 v39, v0
	v_mov_b32_e32 v140, v0
	v_mov_b32_e32 v141, v0
	v_mov_b32_e32 v142, v0
	v_mov_b32_e32 v143, v0
	v_mov_b32_e32 v44, v0
	v_mov_b32_e32 v45, v0
	v_mov_b32_e32 v46, v0
	v_mov_b32_e32 v47, v0
	v_mov_b32_e32 v28, v0
	v_mov_b32_e32 v29, v0
	v_mov_b32_e32 v30, v0
	v_mov_b32_e32 v31, v0
	v_mov_b32_e32 v48, v0
	v_mov_b32_e32 v49, v0
	v_mov_b32_e32 v50, v0
	v_mov_b32_e32 v51, v0
	v_mov_b32_e32 v68, v0
	v_mov_b32_e32 v69, v0
	v_mov_b32_e32 v70, v0
	v_mov_b32_e32 v71, v0
	v_mov_b32_e32 v96, v0
	v_mov_b32_e32 v97, v0
	v_mov_b32_e32 v98, v0
	v_mov_b32_e32 v99, v0
	v_mov_b32_e32 v72, v0
	v_mov_b32_e32 v73, v0
	v_mov_b32_e32 v74, v0
	v_mov_b32_e32 v75, v0
	v_mov_b32_e32 v100, v0
	v_mov_b32_e32 v101, v0
	v_mov_b32_e32 v102, v0
	v_mov_b32_e32 v103, v0
	v_mov_b32_e32 v76, v0
	v_mov_b32_e32 v77, v0
	v_mov_b32_e32 v78, v0
	v_mov_b32_e32 v79, v0
	v_mov_b32_e32 v104, v0
	v_mov_b32_e32 v105, v0
	v_mov_b32_e32 v106, v0
	v_mov_b32_e32 v107, v0
	v_mov_b32_e32 v84, v0
	v_mov_b32_e32 v85, v0
	v_mov_b32_e32 v86, v0
	v_mov_b32_e32 v87, v0
	v_mov_b32_e32 v108, v0
	v_mov_b32_e32 v109, v0
	v_mov_b32_e32 v110, v0
	v_mov_b32_e32 v111, v0
	s_barrier
	v_readlane_b32 s7, v252, 54
	s_branch .LBB0_1443

.LBB0_1450:
	s_add_u32 s68, s0, s50
	s_addc_u32 s69, s1, s51
	s_add_u32 s68, s68, 0x100
	s_addc_u32 s69, s69, 0
	s_add_u32 vcc_lo, s24, s50
	s_addc_u32 vcc_hi, s25, s51
	s_add_i32 s36, 0, 0x10000
	s_cmpk_eq_i32 s50, 0x700
	s_cselect_b32 s71, s35, s69
	s_cselect_b32 s70, s43, s68
	v_add_u32_e32 v149, s36, v122
	s_cselect_b32 s69, s23, vcc_hi
	s_cselect_b32 s68, s47, vcc_lo
	s_add_i32 s37, 0, 0x14000
	ds_read_b128 v[124:127], v149
	ds_read_b128 v[144:147], v149 offset:1024
	ds_read_b128 v[150:153], v149 offset:2048
	ds_read_b128 v[154:157], v149 offset:3072
	v_add_u32_e32 v149, s37, v122
	ds_read_b128 v[158:161], v149
	ds_read_b128 v[162:165], v149 offset:1024
	ds_read_b128 v[166:169], v149 offset:2048
	ds_read_b128 v[170:173], v149 offset:3072
	v_lshl_add_u64 v[206:207], v[118:119], 0, s[50:51]
	s_add_i32 m0, s39, 0xc000
	ds_read_b128 v[174:177], v123
	ds_read_b128 v[178:181], v123 offset:1024
	ds_read_b128 v[182:185], v123 offset:2048
	ds_read_b128 v[190:193], v123 offset:3072
	ds_read_b128 v[194:197], v123 offset:4096
	ds_read_b128 v[198:201], v123 offset:5120
	ds_read_b128 v[202:205], v123 offset:6144
	ds_read_b128 v[214:217], v123 offset:7168
	global_load_lds_dwordx4 v[206:207], off
	v_lshl_add_u64 v[206:207], v[120:121], 0, s[50:51]
	s_add_i32 m0, s39, 0xe000
	s_nop 0
	global_load_lds_dwordx4 v[206:207], off
	s_waitcnt vmcnt(8)
	s_waitcnt lgkmcnt(0)
	s_barrier
	s_setprio 1
	s_waitcnt lgkmcnt(0)
	v_mfma_f32_16x16x32_bf16 v[108:111], v[124:127], v[174:177], v[108:111]
	v_mfma_f32_16x16x32_bf16 v[84:87], v[150:153], v[174:177], v[84:87]
	v_mfma_f32_16x16x32_bf16 v[104:107], v[124:127], v[182:185], v[104:107]
	v_mfma_f32_16x16x32_bf16 v[76:79], v[150:153], v[182:185], v[76:79]
	v_mfma_f32_16x16x32_bf16 v[100:103], v[124:127], v[194:197], v[100:103]
	v_mfma_f32_16x16x32_bf16 v[72:75], v[150:153], v[194:197], v[72:75]
	v_mfma_f32_16x16x32_bf16 v[96:99], v[124:127], v[202:205], v[96:99]
	v_mfma_f32_16x16x32_bf16 v[68:71], v[150:153], v[202:205], v[68:71]
	v_mfma_f32_16x16x32_bf16 v[108:111], v[144:147], v[178:181], v[108:111]
	v_mfma_f32_16x16x32_bf16 v[84:87], v[154:157], v[178:181], v[84:87]
	v_mfma_f32_16x16x32_bf16 v[104:107], v[144:147], v[190:193], v[104:107]
	v_mfma_f32_16x16x32_bf16 v[76:79], v[154:157], v[190:193], v[76:79]
	v_mfma_f32_16x16x32_bf16 v[100:103], v[144:147], v[198:201], v[100:103]
	v_mfma_f32_16x16x32_bf16 v[72:75], v[154:157], v[198:201], v[72:75]
	v_mfma_f32_16x16x32_bf16 v[96:99], v[144:147], v[214:217], v[96:99]
	v_mfma_f32_16x16x32_bf16 v[68:71], v[154:157], v[214:217], v[68:71]
	s_setprio 0
	s_setprio 1
	v_mfma_f32_16x16x32_bf16 v[48:51], v[158:161], v[174:177], v[48:51]
	v_mfma_f32_16x16x32_bf16 v[28:31], v[166:169], v[174:177], v[28:31]
	v_mfma_f32_16x16x32_bf16 v[44:47], v[158:161], v[182:185], v[44:47]
	v_mfma_f32_16x16x32_bf16 v[140:143], v[166:169], v[182:185], v[140:143]
	v_mfma_f32_16x16x32_bf16 v[36:39], v[158:161], v[194:197], v[36:39]
	v_mfma_f32_16x16x32_bf16 v[136:139], v[166:169], v[194:197], v[136:139]
	v_mfma_f32_16x16x32_bf16 v[32:35], v[158:161], v[202:205], v[32:35]
	v_mfma_f32_16x16x32_bf16 v[132:135], v[166:169], v[202:205], v[132:135]
	v_mfma_f32_16x16x32_bf16 v[48:51], v[162:165], v[178:181], v[48:51]
	v_mfma_f32_16x16x32_bf16 v[28:31], v[170:173], v[178:181], v[28:31]
	v_mfma_f32_16x16x32_bf16 v[44:47], v[162:165], v[190:193], v[44:47]
	v_mfma_f32_16x16x32_bf16 v[140:143], v[170:173], v[190:193], v[140:143]
	v_mfma_f32_16x16x32_bf16 v[36:39], v[162:165], v[198:201], v[36:39]
	v_mfma_f32_16x16x32_bf16 v[136:139], v[170:173], v[198:201], v[136:139]
	v_mfma_f32_16x16x32_bf16 v[32:35], v[162:165], v[214:217], v[32:35]
	v_mfma_f32_16x16x32_bf16 v[132:135], v[170:173], v[214:217], v[132:135]
	s_setprio 0
	s_barrier
	s_add_i32 s36, s36, s34
	v_lshl_add_u64 v[206:207], s[68:69], 0, v[208:209]
	s_mov_b32 m0, s36
	ds_read_b128 v[174:177], v123 offset:16384
	ds_read_b128 v[178:181], v123 offset:17408
	ds_read_b128 v[182:185], v123 offset:18432
	ds_read_b128 v[190:193], v123 offset:19456
	ds_read_b128 v[194:197], v123 offset:20480
	ds_read_b128 v[198:201], v123 offset:21504
	ds_read_b128 v[202:205], v123 offset:22528
	ds_read_b128 v[214:217], v123 offset:23552
	global_load_lds_dwordx4 v[206:207], off
	s_add_i32 m0, s36, 0x2000
	s_add_u32 vcc_lo, s68, 0x40000
	v_lshl_add_u64 v[224:225], s[68:69], 0, v[112:113]
	s_addc_u32 vcc_hi, s69, 0
	s_add_i32 s36, s37, s34
	global_load_lds_dwordx4 v[224:225], off
	v_lshl_add_u64 v[226:227], vcc, 0, v[208:209]
	s_mov_b32 m0, s36
	v_lshl_add_u64 v[228:229], s[70:71], 0, v[112:113]
	global_load_lds_dwordx4 v[226:227], off
	v_lshl_add_u64 v[226:227], vcc, 0, v[112:113]
	s_add_i32 m0, s36, 0x2000
	s_nop 0
	global_load_lds_dwordx4 v[226:227], off
	v_lshl_add_u64 v[226:227], s[70:71], 0, v[208:209]
	s_mov_b32 m0, s39
	s_nop 0
	global_load_lds_dwordx4 v[226:227], off
	s_mov_b32 m0, s41
	s_nop 0
	global_load_lds_dwordx4 v[228:229], off
	s_waitcnt vmcnt(8)
	s_waitcnt lgkmcnt(0)
	s_barrier
	s_setprio 1
	s_waitcnt lgkmcnt(0)
	v_mfma_f32_16x16x32_bf16 v[92:95], v[124:127], v[174:177], v[92:95]
	v_mfma_f32_16x16x32_bf16 v[60:63], v[150:153], v[174:177], v[60:63]
	v_mfma_f32_16x16x32_bf16 v[88:91], v[124:127], v[182:185], v[88:91]
	v_mfma_f32_16x16x32_bf16 v[56:59], v[150:153], v[182:185], v[56:59]
	v_mfma_f32_16x16x32_bf16 v[80:83], v[124:127], v[194:197], v[80:83]
	v_mfma_f32_16x16x32_bf16 v[52:55], v[150:153], v[194:197], v[52:55]
	v_mfma_f32_16x16x32_bf16 v[64:67], v[124:127], v[202:205], v[64:67]
	v_mfma_f32_16x16x32_bf16 v[40:43], v[150:153], v[202:205], v[40:43]
	v_mfma_f32_16x16x32_bf16 v[92:95], v[144:147], v[178:181], v[92:95]
	v_mfma_f32_16x16x32_bf16 v[60:63], v[154:157], v[178:181], v[60:63]
	v_mfma_f32_16x16x32_bf16 v[88:91], v[144:147], v[190:193], v[88:91]
	v_mfma_f32_16x16x32_bf16 v[56:59], v[154:157], v[190:193], v[56:59]
	v_mfma_f32_16x16x32_bf16 v[80:83], v[144:147], v[198:201], v[80:83]
	v_mfma_f32_16x16x32_bf16 v[52:55], v[154:157], v[198:201], v[52:55]
	v_mfma_f32_16x16x32_bf16 v[64:67], v[144:147], v[214:217], v[64:67]
	v_mfma_f32_16x16x32_bf16 v[40:43], v[154:157], v[214:217], v[40:43]
	s_setprio 0
	s_setprio 1
	v_mfma_f32_16x16x32_bf16 v[24:27], v[158:161], v[174:177], v[24:27]
	v_mfma_f32_16x16x32_bf16 v[20:23], v[158:161], v[182:185], v[20:23]
	v_mfma_f32_16x16x32_bf16 v[8:11], v[166:169], v[182:185], v[8:11]
	v_mfma_f32_16x16x32_bf16 v[16:19], v[158:161], v[194:197], v[16:19]
	v_mfma_f32_16x16x32_bf16 v[4:7], v[166:169], v[194:197], v[4:7]
	v_mfma_f32_16x16x32_bf16 v[12:15], v[158:161], v[202:205], v[12:15]
	v_mfma_f32_16x16x32_bf16 v[0:3], v[166:169], v[202:205], v[0:3]
	v_mfma_f32_16x16x32_bf16 v[24:27], v[162:165], v[178:181], v[24:27]
	v_mfma_f32_16x16x32_bf16 v[124:127], v[166:169], v[174:177], v[128:131]
	v_mfma_f32_16x16x32_bf16 v[20:23], v[162:165], v[190:193], v[20:23]
	v_mfma_f32_16x16x32_bf16 v[8:11], v[170:173], v[190:193], v[8:11]
	v_mfma_f32_16x16x32_bf16 v[16:19], v[162:165], v[198:201], v[16:19]
	v_mfma_f32_16x16x32_bf16 v[4:7], v[170:173], v[198:201], v[4:7]
	v_mfma_f32_16x16x32_bf16 v[12:15], v[162:165], v[214:217], v[12:15]
	v_mfma_f32_16x16x32_bf16 v[0:3], v[170:173], v[214:217], v[0:3]
	v_mfma_f32_16x16x32_bf16 v[124:127], v[170:173], v[178:181], v[124:127]
	s_setprio 0
	s_barrier
	s_add_i32 s36, 0, 0x18000
	v_add_u32_e32 v149, s36, v122
	s_add_i32 s37, 0, 0x1c000
	ds_read_b128 v[128:131], v149
	ds_read_b128 v[144:147], v149 offset:1024
	ds_read_b128 v[150:153], v149 offset:2048
	ds_read_b128 v[154:157], v149 offset:3072
	v_add_u32_e32 v149, s37, v122
	ds_read_b128 v[158:161], v149
	ds_read_b128 v[162:165], v149 offset:1024
	ds_read_b128 v[166:169], v149 offset:2048
	ds_read_b128 v[170:173], v149 offset:3072
	s_add_u32 s70, s70, 0x40000
	s_addc_u32 s71, s71, 0
	s_mov_b32 m0, s55
	ds_read_b128 v[174:177], v123 offset:32768
	ds_read_b128 v[178:181], v123 offset:33792
	ds_read_b128 v[182:185], v123 offset:34816
	ds_read_b128 v[190:193], v123 offset:35840
	ds_read_b128 v[194:197], v123 offset:36864
	ds_read_b128 v[198:201], v123 offset:37888
	ds_read_b128 v[202:205], v123 offset:38912
	ds_read_b128 v[214:217], v123 offset:39936
	global_load_lds_dwordx4 v208, s[70:71]
	s_mov_b32 m0, s66
	s_nop 0
	global_load_lds_dwordx4 v112, s[70:71]
	s_waitcnt vmcnt(8)
	s_waitcnt lgkmcnt(0)
	s_barrier
	s_setprio 1
	s_waitcnt lgkmcnt(0)
	v_mfma_f32_16x16x32_bf16 v[108:111], v[128:131], v[174:177], v[108:111]
	v_mfma_f32_16x16x32_bf16 v[84:87], v[150:153], v[174:177], v[84:87]
	v_mfma_f32_16x16x32_bf16 v[104:107], v[128:131], v[182:185], v[104:107]
	v_mfma_f32_16x16x32_bf16 v[76:79], v[150:153], v[182:185], v[76:79]
	v_mfma_f32_16x16x32_bf16 v[100:103], v[128:131], v[194:197], v[100:103]
	v_mfma_f32_16x16x32_bf16 v[72:75], v[150:153], v[194:197], v[72:75]
	v_mfma_f32_16x16x32_bf16 v[96:99], v[128:131], v[202:205], v[96:99]
	v_mfma_f32_16x16x32_bf16 v[68:71], v[150:153], v[202:205], v[68:71]
	v_mfma_f32_16x16x32_bf16 v[108:111], v[144:147], v[178:181], v[108:111]
	v_mfma_f32_16x16x32_bf16 v[84:87], v[154:157], v[178:181], v[84:87]
	v_mfma_f32_16x16x32_bf16 v[104:107], v[144:147], v[190:193], v[104:107]
	v_mfma_f32_16x16x32_bf16 v[76:79], v[154:157], v[190:193], v[76:79]
	v_mfma_f32_16x16x32_bf16 v[100:103], v[144:147], v[198:201], v[100:103]
	v_mfma_f32_16x16x32_bf16 v[72:75], v[154:157], v[198:201], v[72:75]
	v_mfma_f32_16x16x32_bf16 v[96:99], v[144:147], v[214:217], v[96:99]
	v_mfma_f32_16x16x32_bf16 v[68:71], v[154:157], v[214:217], v[68:71]
	s_setprio 0
	s_setprio 1
	v_mfma_f32_16x16x32_bf16 v[48:51], v[158:161], v[174:177], v[48:51]
	v_mfma_f32_16x16x32_bf16 v[28:31], v[166:169], v[174:177], v[28:31]
	v_mfma_f32_16x16x32_bf16 v[44:47], v[158:161], v[182:185], v[44:47]
	v_mfma_f32_16x16x32_bf16 v[140:143], v[166:169], v[182:185], v[140:143]
	v_mfma_f32_16x16x32_bf16 v[36:39], v[158:161], v[194:197], v[36:39]
	v_mfma_f32_16x16x32_bf16 v[136:139], v[166:169], v[194:197], v[136:139]
	v_mfma_f32_16x16x32_bf16 v[32:35], v[158:161], v[202:205], v[32:35]
	v_mfma_f32_16x16x32_bf16 v[132:135], v[166:169], v[202:205], v[132:135]
	v_mfma_f32_16x16x32_bf16 v[48:51], v[162:165], v[178:181], v[48:51]
	v_mfma_f32_16x16x32_bf16 v[28:31], v[170:173], v[178:181], v[28:31]
	v_mfma_f32_16x16x32_bf16 v[44:47], v[162:165], v[190:193], v[44:47]
	v_mfma_f32_16x16x32_bf16 v[140:143], v[170:173], v[190:193], v[140:143]
	v_mfma_f32_16x16x32_bf16 v[36:39], v[162:165], v[198:201], v[36:39]
	v_mfma_f32_16x16x32_bf16 v[136:139], v[170:173], v[198:201], v[136:139]
	v_mfma_f32_16x16x32_bf16 v[32:35], v[162:165], v[214:217], v[32:35]
	v_mfma_f32_16x16x32_bf16 v[132:135], v[170:173], v[214:217], v[132:135]
	s_setprio 0
	s_barrier
	s_add_i32 s36, s36, s34
	v_lshl_add_u64 v[206:207], v[206:207], 0, s[92:93]
	s_mov_b32 m0, s36
	ds_read_b128 v[174:177], v123 offset:49152
	ds_read_b128 v[178:181], v123 offset:50176
	ds_read_b128 v[182:185], v123 offset:51200
	ds_read_b128 v[190:193], v123 offset:52224
	ds_read_b128 v[194:197], v123 offset:53248
	ds_read_b128 v[198:201], v123 offset:54272
	ds_read_b128 v[202:205], v123 offset:55296
	ds_read_b128 v[214:217], v123 offset:56320
	global_load_lds_dwordx4 v[206:207], off
	s_add_i32 m0, s36, 0x2000
	s_add_u32 s68, s68, 0x40080
	v_lshl_add_u64 v[206:207], v[224:225], 0, s[92:93]
	s_addc_u32 s69, s69, 0
	s_add_i32 s36, s37, s34
	global_load_lds_dwordx4 v[206:207], off
	s_mov_b32 m0, s36
	s_nop 0
	global_load_lds_dwordx4 v208, s[68:69]
	s_add_i32 m0, s36, 0x2000
	s_nop 0
	global_load_lds_dwordx4 v112, s[68:69]
	v_lshl_add_u64 v[206:207], v[226:227], 0, s[92:93]
	s_mov_b32 m0, s73
	s_nop 0
	global_load_lds_dwordx4 v[206:207], off
	v_lshl_add_u64 v[206:207], v[228:229], 0, s[92:93]
	s_mov_b32 m0, s74
	s_nop 0
	global_load_lds_dwordx4 v[206:207], off
	s_waitcnt vmcnt(8)
	s_waitcnt lgkmcnt(0)
	s_barrier
	s_setprio 1
	s_waitcnt lgkmcnt(0)
	v_mfma_f32_16x16x32_bf16 v[92:95], v[128:131], v[174:177], v[92:95]
	v_mfma_f32_16x16x32_bf16 v[60:63], v[150:153], v[174:177], v[60:63]
	v_mfma_f32_16x16x32_bf16 v[88:91], v[128:131], v[182:185], v[88:91]
	v_mfma_f32_16x16x32_bf16 v[56:59], v[150:153], v[182:185], v[56:59]
	v_mfma_f32_16x16x32_bf16 v[80:83], v[128:131], v[194:197], v[80:83]
	v_mfma_f32_16x16x32_bf16 v[52:55], v[150:153], v[194:197], v[52:55]
	v_mfma_f32_16x16x32_bf16 v[64:67], v[128:131], v[202:205], v[64:67]
	v_mfma_f32_16x16x32_bf16 v[40:43], v[150:153], v[202:205], v[40:43]
	v_mfma_f32_16x16x32_bf16 v[92:95], v[144:147], v[178:181], v[92:95]
	v_mfma_f32_16x16x32_bf16 v[60:63], v[154:157], v[178:181], v[60:63]
	v_mfma_f32_16x16x32_bf16 v[88:91], v[144:147], v[190:193], v[88:91]
	v_mfma_f32_16x16x32_bf16 v[56:59], v[154:157], v[190:193], v[56:59]
	v_mfma_f32_16x16x32_bf16 v[80:83], v[144:147], v[198:201], v[80:83]
	v_mfma_f32_16x16x32_bf16 v[52:55], v[154:157], v[198:201], v[52:55]
	v_mfma_f32_16x16x32_bf16 v[64:67], v[144:147], v[214:217], v[64:67]
	v_mfma_f32_16x16x32_bf16 v[40:43], v[154:157], v[214:217], v[40:43]
	s_setprio 0
	s_setprio 1
	v_mfma_f32_16x16x32_bf16 v[24:27], v[158:161], v[174:177], v[24:27]
	v_mfma_f32_16x16x32_bf16 v[124:127], v[166:169], v[174:177], v[124:127]
	v_mfma_f32_16x16x32_bf16 v[20:23], v[158:161], v[182:185], v[20:23]
	v_mfma_f32_16x16x32_bf16 v[8:11], v[166:169], v[182:185], v[8:11]
	v_mfma_f32_16x16x32_bf16 v[16:19], v[158:161], v[194:197], v[16:19]
	v_mfma_f32_16x16x32_bf16 v[4:7], v[166:169], v[194:197], v[4:7]
	v_mfma_f32_16x16x32_bf16 v[12:15], v[158:161], v[202:205], v[12:15]
	v_mfma_f32_16x16x32_bf16 v[0:3], v[166:169], v[202:205], v[0:3]
	v_mfma_f32_16x16x32_bf16 v[24:27], v[162:165], v[178:181], v[24:27]
	v_mfma_f32_16x16x32_bf16 v[128:131], v[170:173], v[178:181], v[124:127]
	v_mfma_f32_16x16x32_bf16 v[20:23], v[162:165], v[190:193], v[20:23]
	v_mfma_f32_16x16x32_bf16 v[8:11], v[170:173], v[190:193], v[8:11]
	v_mfma_f32_16x16x32_bf16 v[16:19], v[162:165], v[198:201], v[16:19]
	v_mfma_f32_16x16x32_bf16 v[4:7], v[170:173], v[198:201], v[4:7]
	v_mfma_f32_16x16x32_bf16 v[12:15], v[162:165], v[214:217], v[12:15]
	v_mfma_f32_16x16x32_bf16 v[0:3], v[170:173], v[214:217], v[0:3]
	s_setprio 0
	s_barrier
	s_add_i32 s80, s80, 2
	s_add_u32 s50, s50, 0x100
	s_addc_u32 s51, s51, 0
	s_cmp_gt_u32 s80, 13
	s_cbranch_scc0 .LBB0_1450
	s_add_u32 s24, s24, 0xffffff00
	s_addc_u32 s25, s25, -1
	s_andn2_b64 vcc, exec, s[8:9]
	s_cbranch_vccnz .LBB0_1441
	v_mov_b32_e32 v0, 0
	s_mov_b32 s40, s22
	s_mov_b32 s38, s42
	s_mov_b64 s[0:1], s[48:49]
	s_mov_b32 s75, s46
	v_mov_b32_e32 v1, v0
	v_mov_b32_e32 v2, v0
	v_mov_b32_e32 v3, v0
	v_mov_b32_e32 v12, v0
	v_mov_b32_e32 v13, v0
	v_mov_b32_e32 v14, v0
	v_mov_b32_e32 v15, v0
	v_mov_b32_e32 v4, v0
	v_mov_b32_e32 v5, v0
	v_mov_b32_e32 v6, v0
	v_mov_b32_e32 v7, v0
	v_mov_b32_e32 v16, v0
	v_mov_b32_e32 v17, v0
	v_mov_b32_e32 v18, v0
	v_mov_b32_e32 v19, v0
	v_mov_b32_e32 v8, v0
	v_mov_b32_e32 v9, v0
	v_mov_b32_e32 v10, v0
	v_mov_b32_e32 v11, v0
	v_mov_b32_e32 v20, v0
	v_mov_b32_e32 v21, v0
	v_mov_b32_e32 v22, v0
	v_mov_b32_e32 v23, v0
	v_mov_b32_e32 v128, v0
	v_mov_b32_e32 v129, v0
	v_mov_b32_e32 v130, v0
	v_mov_b32_e32 v131, v0
	v_mov_b32_e32 v24, v0
	v_mov_b32_e32 v25, v0
	v_mov_b32_e32 v26, v0
	v_mov_b32_e32 v27, v0
	v_mov_b32_e32 v40, v0
	v_mov_b32_e32 v41, v0
	v_mov_b32_e32 v42, v0
	v_mov_b32_e32 v43, v0
	v_mov_b32_e32 v64, v0
	v_mov_b32_e32 v65, v0
	v_mov_b32_e32 v66, v0
	v_mov_b32_e32 v67, v0
	v_mov_b32_e32 v52, v0
	v_mov_b32_e32 v53, v0
	v_mov_b32_e32 v54, v0
	v_mov_b32_e32 v55, v0
	v_mov_b32_e32 v80, v0
	v_mov_b32_e32 v81, v0
	v_mov_b32_e32 v82, v0
	v_mov_b32_e32 v83, v0
	v_mov_b32_e32 v56, v0
	v_mov_b32_e32 v57, v0
	v_mov_b32_e32 v58, v0
	v_mov_b32_e32 v59, v0
	v_mov_b32_e32 v88, v0
	v_mov_b32_e32 v89, v0
	v_mov_b32_e32 v90, v0
	v_mov_b32_e32 v91, v0
	v_mov_b32_e32 v60, v0
	v_mov_b32_e32 v61, v0
	v_mov_b32_e32 v62, v0
	v_mov_b32_e32 v63, v0
	v_mov_b32_e32 v92, v0
	v_mov_b32_e32 v93, v0
	v_mov_b32_e32 v94, v0
	v_mov_b32_e32 v95, v0
	v_mov_b32_e32 v132, v0
	v_mov_b32_e32 v133, v0
	v_mov_b32_e32 v134, v0
	v_mov_b32_e32 v135, v0
	v_mov_b32_e32 v32, v0
	v_mov_b32_e32 v33, v0
	v_mov_b32_e32 v34, v0
	v_mov_b32_e32 v35, v0
	v_mov_b32_e32 v136, v0
	v_mov_b32_e32 v137, v0
	v_mov_b32_e32 v138, v0
	v_mov_b32_e32 v139, v0
	v_mov_b32_e32 v36, v0
	v_mov_b32_e32 v37, v0
	v_mov_b32_e32 v38, v0
	v_mov_b32_e32 v39, v0
	v_mov_b32_e32 v140, v0
	v_mov_b32_e32 v141, v0
	v_mov_b32_e32 v142, v0
	v_mov_b32_e32 v143, v0
	v_mov_b32_e32 v44, v0
	v_mov_b32_e32 v45, v0
	v_mov_b32_e32 v46, v0
	v_mov_b32_e32 v47, v0
	v_mov_b32_e32 v28, v0
	v_mov_b32_e32 v29, v0
	v_mov_b32_e32 v30, v0
	v_mov_b32_e32 v31, v0
	v_mov_b32_e32 v48, v0
	v_mov_b32_e32 v49, v0
	v_mov_b32_e32 v50, v0
	v_mov_b32_e32 v51, v0
	v_mov_b32_e32 v68, v0
	v_mov_b32_e32 v69, v0
	v_mov_b32_e32 v70, v0
	v_mov_b32_e32 v71, v0
	v_mov_b32_e32 v96, v0
	v_mov_b32_e32 v97, v0
	v_mov_b32_e32 v98, v0
	v_mov_b32_e32 v99, v0
	v_mov_b32_e32 v72, v0
	v_mov_b32_e32 v73, v0
	v_mov_b32_e32 v74, v0
	v_mov_b32_e32 v75, v0
	v_mov_b32_e32 v100, v0
	v_mov_b32_e32 v101, v0
	v_mov_b32_e32 v102, v0
	v_mov_b32_e32 v103, v0
	v_mov_b32_e32 v76, v0
	v_mov_b32_e32 v77, v0
	v_mov_b32_e32 v78, v0
	v_mov_b32_e32 v79, v0
	v_mov_b32_e32 v104, v0
	v_mov_b32_e32 v105, v0
	v_mov_b32_e32 v106, v0
	v_mov_b32_e32 v107, v0
	v_mov_b32_e32 v84, v0
	v_mov_b32_e32 v85, v0
	v_mov_b32_e32 v86, v0
	v_mov_b32_e32 v87, v0
	v_mov_b32_e32 v108, v0
	v_mov_b32_e32 v109, v0
	v_mov_b32_e32 v110, v0
	v_mov_b32_e32 v111, v0
	s_andn2_b64 vcc, exec, s[6:7]
	s_cbranch_vccnz .LBB0_1442

.LBB0_1609:
	v_lshrrev_b32_e32 v16, 1, v14
	v_and_b32_e32 v16, 24, v16
	s_add_u32 s12, s6, 0x9600000
	v_and_b32_e32 v15, 15, v14
	v_lshlrev_b32_e32 v17, 1, v16
	v_lshlrev_b32_e32 v14, 2, v14
	s_addc_u32 s13, s7, 0
	v_lshl_or_b32 v140, s14, 6, v15
	v_lshl_or_b32 v15, v15, 6, v17
	s_lshl_b32 s1, s14, 13
	v_and_b32_e32 v14, 32, v14
	v_bitop3_b32 v17, v15, s1, v14 bitop3:0xde
	s_lshl_b32 s1, s5, 5
	s_and_b32 s1, s1, 0x60
	s_add_i32 m0, s23, 0x18000
	v_lshl_add_u64 v[6:7], v[6:7], 0, s[92:93]
	s_lshl_b32 s5, s1, 7
	s_waitcnt vmcnt(2)
	s_barrier
	global_load_lds_dwordx4 v[6:7], off
	v_lshl_add_u64 v[4:5], v[4:5], 0, s[92:93]
	s_add_i32 m0, s23, 0x1a000
	s_add_i32 s67, s23, 0x8000
	s_add_i32 s68, s23, 0xa000
	global_load_lds_dwordx4 v[4:5], off
	v_lshl_add_u64 v[0:1], v[0:1], 0, s[92:93]
	s_mov_b32 m0, s67
	s_add_u32 s6, s46, 0x40080
	global_load_lds_dwordx4 v[0:1], off
	v_lshl_add_u64 v[0:1], v[2:3], 0, s[92:93]
	s_mov_b32 m0, s68
	s_addc_u32 s7, s47, 0
	global_load_lds_dwordx4 v[0:1], off
	s_add_i32 m0, s23, 0x1c000
	s_nop 0
	global_load_lds_dwordx4 v208, s[6:7]
	s_add_i32 m0, s23, 0x1e000
	s_cmpk_lt_u32 s4, 0x100
	global_load_lds_dwordx4 v128, s[6:7]
	v_lshlrev_b32_e32 v0, 14, v12
	v_and_b32_e32 v0, 0xffff8000, v0
	v_lshl_add_u32 v0, v11, 11, v0
	v_and_b32_e32 v1, 1, v12
	v_lshl_or_b32 v0, v1, 6, v0
	v_lshl_add_u32 v134, v13, 1, v0
	v_lshlrev_b32_e32 v0, 14, v8
	v_and_b32_e32 v0, 0xffff8000, v0
	s_waitcnt vmcnt(6)
	v_lshl_add_u32 v0, v9, 11, v0
	v_and_b32_e32 v1, 1, v8
	v_lshl_or_b32 v0, v1, 6, v0
	v_bitop3_b32 v141, v15, s5, v14 bitop3:0xde
	s_cselect_b64 s[14:15], -1, 0
	v_or_b32_e32 v142, s1, v16
	v_mov_b32_e32 v135, v209
	v_lshl_add_u32 v136, v10, 1, v0
	v_mov_b32_e32 v137, v209
	s_mov_b32 s4, 0
	v_add_u32_e32 v143, 0, v17
	s_barrier
	s_branch .LBB0_1612

.LBB0_1619:
	s_add_u32 s46, s44, 0xfffc0080
	s_addc_u32 s47, s45, -1
	s_add_i32 s69, 0, 0x10000
	s_cmp_eq_u32 s39, 12
	s_cselect_b32 s49, s1, s47
	s_cselect_b32 s48, s5, s46
	v_add_u32_e32 v138, s69, v141
	s_cselect_b32 s47, s24, s37
	s_cselect_b32 s46, s25, s34
	s_add_i32 s72, 0, 0x14000
	ds_read_b128 v[144:147], v138
	ds_read_b128 v[148:151], v138 offset:1024
	ds_read_b128 v[152:155], v138 offset:2048
	ds_read_b128 v[156:159], v138 offset:3072
	v_add_u32_e32 v138, s72, v141
	ds_read_b128 v[160:163], v138
	ds_read_b128 v[164:167], v138 offset:1024
	ds_read_b128 v[168:171], v138 offset:2048
	ds_read_b128 v[172:175], v138 offset:3072
	s_add_i32 m0, s23, 0xc000
	ds_read_b128 v[176:179], v143
	ds_read_b128 v[180:183], v143 offset:1024
	ds_read_b128 v[184:187], v143 offset:2048
	ds_read_b128 v[188:191], v143 offset:3072
	ds_read_b128 v[192:195], v143 offset:4096
	ds_read_b128 v[196:199], v143 offset:5120
	ds_read_b128 v[200:203], v143 offset:6144
	ds_read_b128 v[204:207], v143 offset:7168
	global_load_lds_dwordx4 v134, s[44:45]
	s_add_i32 m0, s23, 0xe000
	s_nop 0
	global_load_lds_dwordx4 v136, s[44:45]
	s_waitcnt vmcnt(8)
	s_waitcnt lgkmcnt(0)
	s_barrier
	s_setprio 1
	s_waitcnt lgkmcnt(0)
	v_mfma_f32_16x16x32_bf16 v[124:127], v[144:147], v[176:179], v[124:127]
	v_mfma_f32_16x16x32_bf16 v[116:119], v[152:155], v[176:179], v[116:119]
	v_mfma_f32_16x16x32_bf16 v[108:111], v[144:147], v[184:187], v[108:111]
	v_mfma_f32_16x16x32_bf16 v[100:103], v[152:155], v[184:187], v[100:103]
	v_mfma_f32_16x16x32_bf16 v[92:95], v[144:147], v[192:195], v[92:95]
	v_mfma_f32_16x16x32_bf16 v[84:87], v[152:155], v[192:195], v[84:87]
	v_mfma_f32_16x16x32_bf16 v[76:79], v[144:147], v[200:203], v[76:79]
	v_mfma_f32_16x16x32_bf16 v[68:71], v[152:155], v[200:203], v[68:71]
	v_mfma_f32_16x16x32_bf16 v[124:127], v[148:151], v[180:183], v[124:127]
	v_mfma_f32_16x16x32_bf16 v[116:119], v[156:159], v[180:183], v[116:119]
	v_mfma_f32_16x16x32_bf16 v[108:111], v[148:151], v[188:191], v[108:111]
	v_mfma_f32_16x16x32_bf16 v[100:103], v[156:159], v[188:191], v[100:103]
	v_mfma_f32_16x16x32_bf16 v[92:95], v[148:151], v[196:199], v[92:95]
	v_mfma_f32_16x16x32_bf16 v[84:87], v[156:159], v[196:199], v[84:87]
	v_mfma_f32_16x16x32_bf16 v[76:79], v[148:151], v[204:207], v[76:79]
	v_mfma_f32_16x16x32_bf16 v[68:71], v[156:159], v[204:207], v[68:71]
	s_setprio 0
	s_setprio 1
	v_mfma_f32_16x16x32_bf16 v[120:123], v[160:163], v[176:179], v[120:123]
	v_mfma_f32_16x16x32_bf16 v[112:115], v[168:171], v[176:179], v[112:115]
	v_mfma_f32_16x16x32_bf16 v[104:107], v[160:163], v[184:187], v[104:107]
	v_mfma_f32_16x16x32_bf16 v[96:99], v[168:171], v[184:187], v[96:99]
	v_mfma_f32_16x16x32_bf16 v[88:91], v[160:163], v[192:195], v[88:91]
	v_mfma_f32_16x16x32_bf16 v[80:83], v[168:171], v[192:195], v[80:83]
	v_mfma_f32_16x16x32_bf16 v[72:75], v[160:163], v[200:203], v[72:75]
	v_mfma_f32_16x16x32_bf16 v[64:67], v[168:171], v[200:203], v[64:67]
	v_mfma_f32_16x16x32_bf16 v[120:123], v[164:167], v[180:183], v[120:123]
	v_mfma_f32_16x16x32_bf16 v[112:115], v[172:175], v[180:183], v[112:115]
	v_mfma_f32_16x16x32_bf16 v[104:107], v[164:167], v[188:191], v[104:107]
	v_mfma_f32_16x16x32_bf16 v[96:99], v[172:175], v[188:191], v[96:99]
	v_mfma_f32_16x16x32_bf16 v[88:91], v[164:167], v[196:199], v[88:91]
	v_mfma_f32_16x16x32_bf16 v[80:83], v[172:175], v[196:199], v[80:83]
	v_mfma_f32_16x16x32_bf16 v[72:75], v[164:167], v[204:207], v[72:75]
	v_mfma_f32_16x16x32_bf16 v[64:67], v[172:175], v[204:207], v[64:67]
	s_setprio 0
	s_barrier
	s_add_i32 s69, s69, s60
	v_lshl_add_u64 v[138:139], s[46:47], 0, v[208:209]
	s_mov_b32 m0, s69
	ds_read_b128 v[176:179], v143 offset:16384
	ds_read_b128 v[180:183], v143 offset:17408
	ds_read_b128 v[184:187], v143 offset:18432
	ds_read_b128 v[188:191], v143 offset:19456
	ds_read_b128 v[192:195], v143 offset:20480
	ds_read_b128 v[196:199], v143 offset:21504
	ds_read_b128 v[200:203], v143 offset:22528
	ds_read_b128 v[204:207], v143 offset:23552
	global_load_lds_dwordx4 v[138:139], off
	s_add_i32 m0, s69, 0x2000
	s_add_u32 s70, s46, 0x40000
	v_lshl_add_u64 v[214:215], s[46:47], 0, v[128:129]
	s_addc_u32 s71, s47, 0
	s_add_i32 s69, s72, s60
	global_load_lds_dwordx4 v[214:215], off
	s_mov_b32 m0, s69
	v_lshl_add_u64 v[224:225], s[48:49], 0, v[130:131]
	global_load_lds_dwordx4 v208, s[70:71]
	s_add_i32 m0, s69, 0x2000
	s_nop 0
	global_load_lds_dwordx4 v128, s[70:71]
	v_lshl_add_u64 v[216:217], s[48:49], 0, v[132:133]
	s_mov_b32 m0, s23
	s_nop 0
	global_load_lds_dwordx4 v[216:217], off
	s_mov_b32 m0, s61
	s_nop 0
	global_load_lds_dwordx4 v[224:225], off
	s_waitcnt vmcnt(8)
	s_waitcnt lgkmcnt(0)
	s_barrier
	s_setprio 1
	s_waitcnt lgkmcnt(0)
	v_mfma_f32_16x16x32_bf16 v[60:63], v[144:147], v[176:179], v[60:63]
	v_mfma_f32_16x16x32_bf16 v[52:55], v[152:155], v[176:179], v[52:55]
	v_mfma_f32_16x16x32_bf16 v[44:47], v[144:147], v[184:187], v[44:47]
	v_mfma_f32_16x16x32_bf16 v[36:39], v[152:155], v[184:187], v[36:39]
	v_mfma_f32_16x16x32_bf16 v[28:31], v[144:147], v[192:195], v[28:31]
	v_mfma_f32_16x16x32_bf16 v[20:23], v[152:155], v[192:195], v[20:23]
	v_mfma_f32_16x16x32_bf16 v[12:15], v[144:147], v[200:203], v[12:15]
	v_mfma_f32_16x16x32_bf16 v[4:7], v[152:155], v[200:203], v[4:7]
	v_mfma_f32_16x16x32_bf16 v[60:63], v[148:151], v[180:183], v[60:63]
	v_mfma_f32_16x16x32_bf16 v[52:55], v[156:159], v[180:183], v[52:55]
	v_mfma_f32_16x16x32_bf16 v[44:47], v[148:151], v[188:191], v[44:47]
	v_mfma_f32_16x16x32_bf16 v[36:39], v[156:159], v[188:191], v[36:39]
	v_mfma_f32_16x16x32_bf16 v[28:31], v[148:151], v[196:199], v[28:31]
	v_mfma_f32_16x16x32_bf16 v[20:23], v[156:159], v[196:199], v[20:23]
	v_mfma_f32_16x16x32_bf16 v[12:15], v[148:151], v[204:207], v[12:15]
	v_mfma_f32_16x16x32_bf16 v[4:7], v[156:159], v[204:207], v[4:7]
	s_setprio 0
	s_setprio 1
	v_mfma_f32_16x16x32_bf16 v[56:59], v[160:163], v[176:179], v[56:59]
	v_mfma_f32_16x16x32_bf16 v[48:51], v[168:171], v[176:179], v[48:51]
	v_mfma_f32_16x16x32_bf16 v[40:43], v[160:163], v[184:187], v[40:43]
	v_mfma_f32_16x16x32_bf16 v[32:35], v[168:171], v[184:187], v[32:35]
	v_mfma_f32_16x16x32_bf16 v[24:27], v[160:163], v[192:195], v[24:27]
	v_mfma_f32_16x16x32_bf16 v[16:19], v[168:171], v[192:195], v[16:19]
	v_mfma_f32_16x16x32_bf16 v[8:11], v[160:163], v[200:203], v[8:11]
	v_mfma_f32_16x16x32_bf16 v[0:3], v[168:171], v[200:203], v[0:3]
	v_mfma_f32_16x16x32_bf16 v[56:59], v[164:167], v[180:183], v[56:59]
	v_mfma_f32_16x16x32_bf16 v[48:51], v[172:175], v[180:183], v[48:51]
	v_mfma_f32_16x16x32_bf16 v[40:43], v[164:167], v[188:191], v[40:43]
	v_mfma_f32_16x16x32_bf16 v[32:35], v[172:175], v[188:191], v[32:35]
	v_mfma_f32_16x16x32_bf16 v[24:27], v[164:167], v[196:199], v[24:27]
	v_mfma_f32_16x16x32_bf16 v[16:19], v[172:175], v[196:199], v[16:19]
	v_mfma_f32_16x16x32_bf16 v[8:11], v[164:167], v[204:207], v[8:11]
	v_mfma_f32_16x16x32_bf16 v[0:3], v[172:175], v[204:207], v[0:3]
	s_setprio 0
	s_barrier
	s_add_i32 s69, 0, 0x18000
	s_add_i32 s70, 0, 0x1c000
	v_add_u32_e32 v156, s69, v141
	v_add_u32_e32 v172, s70, v141
	ds_read_b128 v[144:147], v156
	ds_read_b128 v[148:151], v156 offset:1024
	ds_read_b128 v[152:155], v156 offset:2048
	ds_read_b128 v[156:159], v156 offset:3072
	ds_read_b128 v[160:163], v172
	ds_read_b128 v[164:167], v172 offset:1024
	ds_read_b128 v[168:171], v172 offset:2048
	ds_read_b128 v[172:175], v172 offset:3072
	s_add_u32 s48, s48, 0x40000
	s_addc_u32 s49, s49, 0
	s_mov_b32 m0, s63
	ds_read_b128 v[176:179], v143 offset:32768
	ds_read_b128 v[180:183], v143 offset:33792
	ds_read_b128 v[184:187], v143 offset:34816
	ds_read_b128 v[188:191], v143 offset:35840
	ds_read_b128 v[192:195], v143 offset:36864
	ds_read_b128 v[196:199], v143 offset:37888
	ds_read_b128 v[200:203], v143 offset:38912
	ds_read_b128 v[204:207], v143 offset:39936
	global_load_lds_dwordx4 v132, s[48:49]
	s_mov_b32 m0, s66
	s_nop 0
	global_load_lds_dwordx4 v130, s[48:49]
	s_waitcnt vmcnt(8)
	s_waitcnt lgkmcnt(0)
	s_barrier
	s_setprio 1
	s_waitcnt lgkmcnt(0)
	v_mfma_f32_16x16x32_bf16 v[124:127], v[144:147], v[176:179], v[124:127]
	v_mfma_f32_16x16x32_bf16 v[116:119], v[152:155], v[176:179], v[116:119]
	v_mfma_f32_16x16x32_bf16 v[108:111], v[144:147], v[184:187], v[108:111]
	v_mfma_f32_16x16x32_bf16 v[100:103], v[152:155], v[184:187], v[100:103]
	v_mfma_f32_16x16x32_bf16 v[92:95], v[144:147], v[192:195], v[92:95]
	v_mfma_f32_16x16x32_bf16 v[84:87], v[152:155], v[192:195], v[84:87]
	v_mfma_f32_16x16x32_bf16 v[76:79], v[144:147], v[200:203], v[76:79]
	v_mfma_f32_16x16x32_bf16 v[68:71], v[152:155], v[200:203], v[68:71]
	v_mfma_f32_16x16x32_bf16 v[124:127], v[148:151], v[180:183], v[124:127]
	v_mfma_f32_16x16x32_bf16 v[116:119], v[156:159], v[180:183], v[116:119]
	v_mfma_f32_16x16x32_bf16 v[108:111], v[148:151], v[188:191], v[108:111]
	v_mfma_f32_16x16x32_bf16 v[100:103], v[156:159], v[188:191], v[100:103]
	v_mfma_f32_16x16x32_bf16 v[92:95], v[148:151], v[196:199], v[92:95]
	v_mfma_f32_16x16x32_bf16 v[84:87], v[156:159], v[196:199], v[84:87]
	v_mfma_f32_16x16x32_bf16 v[76:79], v[148:151], v[204:207], v[76:79]
	v_mfma_f32_16x16x32_bf16 v[68:71], v[156:159], v[204:207], v[68:71]
	s_setprio 0
	s_setprio 1
	v_mfma_f32_16x16x32_bf16 v[120:123], v[160:163], v[176:179], v[120:123]
	v_mfma_f32_16x16x32_bf16 v[112:115], v[168:171], v[176:179], v[112:115]
	v_mfma_f32_16x16x32_bf16 v[104:107], v[160:163], v[184:187], v[104:107]
	v_mfma_f32_16x16x32_bf16 v[96:99], v[168:171], v[184:187], v[96:99]
	v_mfma_f32_16x16x32_bf16 v[88:91], v[160:163], v[192:195], v[88:91]
	v_mfma_f32_16x16x32_bf16 v[80:83], v[168:171], v[192:195], v[80:83]
	v_mfma_f32_16x16x32_bf16 v[72:75], v[160:163], v[200:203], v[72:75]
	v_mfma_f32_16x16x32_bf16 v[64:67], v[168:171], v[200:203], v[64:67]
	v_mfma_f32_16x16x32_bf16 v[120:123], v[164:167], v[180:183], v[120:123]
	v_mfma_f32_16x16x32_bf16 v[112:115], v[172:175], v[180:183], v[112:115]
	v_mfma_f32_16x16x32_bf16 v[104:107], v[164:167], v[188:191], v[104:107]
	v_mfma_f32_16x16x32_bf16 v[96:99], v[172:175], v[188:191], v[96:99]
	v_mfma_f32_16x16x32_bf16 v[88:91], v[164:167], v[196:199], v[88:91]
	v_mfma_f32_16x16x32_bf16 v[80:83], v[172:175], v[196:199], v[80:83]
	v_mfma_f32_16x16x32_bf16 v[72:75], v[164:167], v[204:207], v[72:75]
	v_mfma_f32_16x16x32_bf16 v[64:67], v[172:175], v[204:207], v[64:67]
	s_setprio 0
	s_barrier
	s_add_i32 s48, s69, s60
	v_lshl_add_u64 v[138:139], v[138:139], 0, s[92:93]
	s_mov_b32 m0, s48
	ds_read_b128 v[176:179], v143 offset:49152
	ds_read_b128 v[180:183], v143 offset:50176
	ds_read_b128 v[184:187], v143 offset:51200
	ds_read_b128 v[188:191], v143 offset:52224
	ds_read_b128 v[192:195], v143 offset:53248
	ds_read_b128 v[196:199], v143 offset:54272
	ds_read_b128 v[200:203], v143 offset:55296
	ds_read_b128 v[204:207], v143 offset:56320
	global_load_lds_dwordx4 v[138:139], off
	s_add_i32 m0, s48, 0x2000
	s_add_u32 s46, s46, 0x40080
	v_lshl_add_u64 v[138:139], v[214:215], 0, s[92:93]
	s_addc_u32 s47, s47, 0
	s_add_i32 s48, s70, s60
	global_load_lds_dwordx4 v[138:139], off
	s_mov_b32 m0, s48
	s_nop 0
	global_load_lds_dwordx4 v208, s[46:47]
	s_add_i32 m0, s48, 0x2000
	s_nop 0
	global_load_lds_dwordx4 v128, s[46:47]
	v_lshl_add_u64 v[138:139], v[216:217], 0, s[92:93]
	s_mov_b32 m0, s67
	s_nop 0
	global_load_lds_dwordx4 v[138:139], off
	v_lshl_add_u64 v[138:139], v[224:225], 0, s[92:93]
	s_mov_b32 m0, s68
	s_nop 0
	global_load_lds_dwordx4 v[138:139], off
	s_waitcnt vmcnt(8)
	s_waitcnt lgkmcnt(0)
	s_barrier
	s_setprio 1
	s_waitcnt lgkmcnt(0)
	v_mfma_f32_16x16x32_bf16 v[60:63], v[144:147], v[176:179], v[60:63]
	v_mfma_f32_16x16x32_bf16 v[52:55], v[152:155], v[176:179], v[52:55]
	v_mfma_f32_16x16x32_bf16 v[44:47], v[144:147], v[184:187], v[44:47]
	v_mfma_f32_16x16x32_bf16 v[36:39], v[152:155], v[184:187], v[36:39]
	v_mfma_f32_16x16x32_bf16 v[28:31], v[144:147], v[192:195], v[28:31]
	v_mfma_f32_16x16x32_bf16 v[20:23], v[152:155], v[192:195], v[20:23]
	v_mfma_f32_16x16x32_bf16 v[12:15], v[144:147], v[200:203], v[12:15]
	v_mfma_f32_16x16x32_bf16 v[4:7], v[152:155], v[200:203], v[4:7]
	v_mfma_f32_16x16x32_bf16 v[60:63], v[148:151], v[180:183], v[60:63]
	v_mfma_f32_16x16x32_bf16 v[52:55], v[156:159], v[180:183], v[52:55]
	v_mfma_f32_16x16x32_bf16 v[44:47], v[148:151], v[188:191], v[44:47]
	v_mfma_f32_16x16x32_bf16 v[36:39], v[156:159], v[188:191], v[36:39]
	v_mfma_f32_16x16x32_bf16 v[28:31], v[148:151], v[196:199], v[28:31]
	v_mfma_f32_16x16x32_bf16 v[20:23], v[156:159], v[196:199], v[20:23]
	v_mfma_f32_16x16x32_bf16 v[12:15], v[148:151], v[204:207], v[12:15]
	v_mfma_f32_16x16x32_bf16 v[4:7], v[156:159], v[204:207], v[4:7]
	s_setprio 0
	s_setprio 1
	v_mfma_f32_16x16x32_bf16 v[56:59], v[160:163], v[176:179], v[56:59]
	v_mfma_f32_16x16x32_bf16 v[48:51], v[168:171], v[176:179], v[48:51]
	v_mfma_f32_16x16x32_bf16 v[40:43], v[160:163], v[184:187], v[40:43]
	v_mfma_f32_16x16x32_bf16 v[32:35], v[168:171], v[184:187], v[32:35]
	v_mfma_f32_16x16x32_bf16 v[24:27], v[160:163], v[192:195], v[24:27]
	v_mfma_f32_16x16x32_bf16 v[16:19], v[168:171], v[192:195], v[16:19]
	v_mfma_f32_16x16x32_bf16 v[8:11], v[160:163], v[200:203], v[8:11]
	v_mfma_f32_16x16x32_bf16 v[0:3], v[168:171], v[200:203], v[0:3]
	v_mfma_f32_16x16x32_bf16 v[56:59], v[164:167], v[180:183], v[56:59]
	v_mfma_f32_16x16x32_bf16 v[48:51], v[172:175], v[180:183], v[48:51]
	v_mfma_f32_16x16x32_bf16 v[40:43], v[164:167], v[188:191], v[40:43]
	v_mfma_f32_16x16x32_bf16 v[32:35], v[172:175], v[188:191], v[32:35]
	v_mfma_f32_16x16x32_bf16 v[24:27], v[164:167], v[196:199], v[24:27]
	v_mfma_f32_16x16x32_bf16 v[16:19], v[172:175], v[196:199], v[16:19]
	v_mfma_f32_16x16x32_bf16 v[8:11], v[164:167], v[204:207], v[8:11]
	v_mfma_f32_16x16x32_bf16 v[0:3], v[172:175], v[204:207], v[0:3]
	s_setprio 0
	s_barrier
	s_add_i32 s39, s39, 2
	s_add_u32 s44, s44, 0x100
	s_addc_u32 s45, s45, 0
	s_add_u32 s34, s34, 0x100
	s_addc_u32 s37, s37, 0
	s_cmp_gt_u32 s39, 13
	s_cbranch_scc0 .LBB0_1619
	s_and_b64 vcc, exec, s[14:15]
	s_cbranch_vccz .LBB0_1622
	s_barrier

.LBB0_1687:
	s_add_u32 s69, s51, 0x8000
	s_addc_u32 s70, s54, 0
	s_lshl_b32 s4, s4, 5
	s_and_b32 s8, s4, 0x60
	s_add_i32 m0, s49, 0x18000
	v_lshl_add_u64 v[6:7], v[6:7], 0, s[92:93]
	s_lshl_b32 s5, s1, 13
	s_lshl_b32 s9, s8, 7
	s_waitcnt vmcnt(2)
	s_barrier
	global_load_lds_dwordx4 v[6:7], off
	v_lshl_add_u64 v[4:5], v[4:5], 0, s[92:93]
	s_add_i32 m0, s49, 0x1a000
	s_add_i32 s71, s49, 0x8000
	s_add_i32 s4, s49, 0xa000
	global_load_lds_dwordx4 v[4:5], off
	v_lshl_add_u64 v[0:1], v[0:1], 0, s[92:93]
	s_mov_b32 m0, s71
	s_add_u32 s6, s42, 0xb0080
	global_load_lds_dwordx4 v[0:1], off
	v_lshl_add_u64 v[0:1], v[2:3], 0, s[92:93]
	s_mov_b32 m0, s4
	s_addc_u32 s7, s43, 0
	global_load_lds_dwordx4 v[0:1], off
	s_add_i32 m0, s49, 0x1c000
	s_nop 0
	global_load_lds_dwordx4 v208, s[6:7]
	s_add_i32 m0, s49, 0x1e000
	v_bfe_u32 v4, v12, 4, 2
	global_load_lds_dwordx4 v128, s[6:7]
	v_and_b32_e32 v1, 15, v12
	v_lshlrev_b32_e32 v2, 4, v4
	v_lshl_or_b32 v0, s1, 6, v1
	v_lshl_or_b32 v1, v1, 6, v2
	v_lshlrev_b32_e32 v2, 2, v12
	v_and_b32_e32 v2, 32, v2
	v_bitop3_b32 v5, v1, s5, v2 bitop3:0xde
	v_bitop3_b32 v170, v1, s9, v2 bitop3:0xde
	v_or_b32_e32 v2, 16, v0
	v_ashrrev_i32_e32 v3, 31, v2
	v_lshlrev_b64 v[132:133], 12, v[2:3]
	v_or_b32_e32 v2, 32, v0
	v_ashrrev_i32_e32 v3, 31, v2
	v_lshlrev_b64 v[134:135], 12, v[2:3]
	v_or_b32_e32 v2, 48, v0
	v_ashrrev_i32_e32 v3, 31, v2
	v_lshlrev_b64 v[136:137], 12, v[2:3]
	v_add_u32_e32 v2, 0x90, v0
	v_ashrrev_i32_e32 v1, 31, v0
	v_ashrrev_i32_e32 v3, 31, v2
	v_lshlrev_b64 v[130:131], 12, v[0:1]
	v_lshlrev_b64 v[140:141], 12, v[2:3]
	v_add_u32_e32 v2, 0xa0, v0
	v_add_u32_e32 v0, 0xb0, v0
	v_ashrrev_i32_e32 v1, 31, v0
	s_movk_i32 s6, 0xb00
	v_lshlrev_b64 v[144:145], 12, v[0:1]
	v_lshrrev_b32_e32 v1, 1, v14
	v_mul_lo_u32 v0, v13, s6
	s_mov_b32 s5, 0xb000
	s_cmpk_lt_u32 s0, 0x100
	v_mad_u64_u32 v[0:1], s[0:1], v1, s5, v[0:1]
	v_or_b32_e32 v0, v0, v15
	v_lshl_or_b32 v171, v4, 2, s8
	v_add_lshl_u32 v0, v0, v16, 1
	v_mov_b32_e32 v1, v209
	s_mov_b64 s[8:9], 0xb0080
	v_lshl_add_u64 v[146:147], v[0:1], 0, s[8:9]
	v_lshrrev_b32_e32 v1, 1, v8
	v_mul_lo_u32 v0, v9, s6
	v_mad_u64_u32 v[0:1], s[0:1], v1, s5, v[0:1]
	s_waitcnt vmcnt(6)
	v_or_b32_e32 v0, v0, v10
	v_ashrrev_i32_e32 v3, 31, v2
	v_add_lshl_u32 v0, v0, v11, 1
	v_mov_b32_e32 v1, v209
	s_cselect_b64 s[38:39], -1, 0
	v_lshl_add_u64 v[138:139], v[130:131], 0, s[28:29]
	v_lshlrev_b64 v[142:143], 12, v[2:3]
	v_lshl_add_u64 v[148:149], v[0:1], 0, s[8:9]
	s_mov_b32 s5, 0
	v_add_u32_e32 v172, 0, v5
	v_readlane_b32 s74, v252, 55
	v_readlane_b32 s0, v252, 53
	s_barrier
	v_readlane_b32 s1, v252, 54
	s_branch .LBB0_1690

.LBB0_1701:
	s_add_u32 s42, s22, 0x100
	s_addc_u32 s43, s23, 0
	s_add_i32 s30, 0, 0x10000
	s_cmp_eq_u32 s25, 40
	s_cselect_b32 s47, s9, s43
	s_cselect_b32 s46, s8, s42
	s_cselect_b32 s45, s41, s24
	s_cselect_b32 s44, s40, s1
	s_add_i32 s31, 0, 0x14000
	v_add_u32_e32 v162, s30, v170
	v_add_u32_e32 v173, s31, v170
	ds_read_b128 v[150:153], v162
	ds_read_b128 v[154:157], v162 offset:1024
	ds_read_b128 v[158:161], v162 offset:2048
	ds_read_b128 v[162:165], v162 offset:3072
	ds_read_b128 v[166:169], v173
	ds_read_b128 v[174:177], v173 offset:1024
	ds_read_b128 v[178:181], v173 offset:2048
	ds_read_b128 v[184:187], v173 offset:3072
	v_lshl_add_u64 v[232:233], s[22:23], 0, v[146:147]
	s_add_i32 m0, s49, 0xc000
	ds_read_b128 v[188:191], v172
	ds_read_b128 v[192:195], v172 offset:1024
	ds_read_b128 v[196:199], v172 offset:2048
	ds_read_b128 v[200:203], v172 offset:3072
	ds_read_b128 v[204:207], v172 offset:4096
	ds_read_b128 v[214:217], v172 offset:5120
	ds_read_b128 v[224:227], v172 offset:6144
	ds_read_b128 v[228:231], v172 offset:7168
	global_load_lds_dwordx4 v[232:233], off
	v_lshl_add_u64 v[232:233], s[22:23], 0, v[148:149]
	s_add_i32 m0, s49, 0xe000
	s_nop 0
	global_load_lds_dwordx4 v[232:233], off
	s_waitcnt vmcnt(8)
	s_waitcnt lgkmcnt(0)
	s_barrier
	s_setprio 1
	s_waitcnt lgkmcnt(0)
	v_mfma_f32_16x16x32_bf16 v[124:127], v[150:153], v[188:191], v[124:127]
	v_mfma_f32_16x16x32_bf16 v[120:123], v[158:161], v[188:191], v[120:123]
	v_mfma_f32_16x16x32_bf16 v[108:111], v[150:153], v[196:199], v[108:111]
	v_mfma_f32_16x16x32_bf16 v[104:107], v[158:161], v[196:199], v[104:107]
	v_mfma_f32_16x16x32_bf16 v[92:95], v[150:153], v[204:207], v[92:95]
	v_mfma_f32_16x16x32_bf16 v[88:91], v[158:161], v[204:207], v[88:91]
	v_mfma_f32_16x16x32_bf16 v[76:79], v[150:153], v[224:227], v[76:79]
	v_mfma_f32_16x16x32_bf16 v[72:75], v[158:161], v[224:227], v[72:75]
	v_mfma_f32_16x16x32_bf16 v[124:127], v[154:157], v[192:195], v[124:127]
	v_mfma_f32_16x16x32_bf16 v[120:123], v[162:165], v[192:195], v[120:123]
	v_mfma_f32_16x16x32_bf16 v[108:111], v[154:157], v[200:203], v[108:111]
	v_mfma_f32_16x16x32_bf16 v[104:107], v[162:165], v[200:203], v[104:107]
	v_mfma_f32_16x16x32_bf16 v[92:95], v[154:157], v[214:217], v[92:95]
	v_mfma_f32_16x16x32_bf16 v[88:91], v[162:165], v[214:217], v[88:91]
	v_mfma_f32_16x16x32_bf16 v[76:79], v[154:157], v[228:231], v[76:79]
	v_mfma_f32_16x16x32_bf16 v[72:75], v[162:165], v[228:231], v[72:75]
	s_setprio 0
	s_setprio 1
	v_mfma_f32_16x16x32_bf16 v[116:119], v[166:169], v[188:191], v[116:119]
	v_mfma_f32_16x16x32_bf16 v[112:115], v[178:181], v[188:191], v[112:115]
	v_mfma_f32_16x16x32_bf16 v[100:103], v[166:169], v[196:199], v[100:103]
	v_mfma_f32_16x16x32_bf16 v[96:99], v[178:181], v[196:199], v[96:99]
	v_mfma_f32_16x16x32_bf16 v[84:87], v[166:169], v[204:207], v[84:87]
	v_mfma_f32_16x16x32_bf16 v[80:83], v[178:181], v[204:207], v[80:83]
	v_mfma_f32_16x16x32_bf16 v[68:71], v[166:169], v[224:227], v[68:71]
	v_mfma_f32_16x16x32_bf16 v[64:67], v[178:181], v[224:227], v[64:67]
	v_mfma_f32_16x16x32_bf16 v[116:119], v[174:177], v[192:195], v[116:119]
	v_mfma_f32_16x16x32_bf16 v[112:115], v[184:187], v[192:195], v[112:115]
	v_mfma_f32_16x16x32_bf16 v[100:103], v[174:177], v[200:203], v[100:103]
	v_mfma_f32_16x16x32_bf16 v[96:99], v[184:187], v[200:203], v[96:99]
	v_mfma_f32_16x16x32_bf16 v[84:87], v[174:177], v[214:217], v[84:87]
	v_mfma_f32_16x16x32_bf16 v[80:83], v[184:187], v[214:217], v[80:83]
	v_mfma_f32_16x16x32_bf16 v[68:71], v[174:177], v[228:231], v[68:71]
	v_mfma_f32_16x16x32_bf16 v[64:67], v[184:187], v[228:231], v[64:67]
	s_setprio 0
	s_barrier
	s_add_i32 s22, s30, s48
	v_lshl_add_u64 v[232:233], s[44:45], 0, v[208:209]
	s_mov_b32 m0, s22
	ds_read_b128 v[188:191], v172 offset:16384
	ds_read_b128 v[192:195], v172 offset:17408
	ds_read_b128 v[196:199], v172 offset:18432
	ds_read_b128 v[200:203], v172 offset:19456
	ds_read_b128 v[204:207], v172 offset:20480
	ds_read_b128 v[214:217], v172 offset:21504
	ds_read_b128 v[224:227], v172 offset:22528
	ds_read_b128 v[228:231], v172 offset:23552
	global_load_lds_dwordx4 v[232:233], off
	s_add_i32 m0, s22, 0x2000
	s_add_u32 s22, s44, 0xb0000
	v_lshl_add_u64 v[234:235], s[44:45], 0, v[128:129]
	s_addc_u32 s23, s45, 0
	s_add_i32 s30, s31, s48
	global_load_lds_dwordx4 v[234:235], off
	s_mov_b32 m0, s30
	v_lshl_add_u64 v[240:241], s[46:47], 0, v[128:129]
	global_load_lds_dwordx4 v208, s[22:23]
	s_add_i32 m0, s30, 0x2000
	s_nop 0
	global_load_lds_dwordx4 v128, s[22:23]
	v_lshl_add_u64 v[238:239], s[46:47], 0, v[208:209]
	s_mov_b32 m0, s49
	s_nop 0
	global_load_lds_dwordx4 v[238:239], off
	s_mov_b32 m0, s66
	s_nop 0
	global_load_lds_dwordx4 v[240:241], off
	s_waitcnt vmcnt(8)
	s_waitcnt lgkmcnt(0)
	s_barrier
	s_setprio 1
	s_waitcnt lgkmcnt(0)
	v_mfma_f32_16x16x32_bf16 v[60:63], v[150:153], v[188:191], v[60:63]
	v_mfma_f32_16x16x32_bf16 v[56:59], v[158:161], v[188:191], v[56:59]
	v_mfma_f32_16x16x32_bf16 v[44:47], v[150:153], v[196:199], v[44:47]
	v_mfma_f32_16x16x32_bf16 v[40:43], v[158:161], v[196:199], v[40:43]
	v_mfma_f32_16x16x32_bf16 v[28:31], v[150:153], v[204:207], v[28:31]
	v_mfma_f32_16x16x32_bf16 v[24:27], v[158:161], v[204:207], v[24:27]
	v_mfma_f32_16x16x32_bf16 v[12:15], v[150:153], v[224:227], v[12:15]
	v_mfma_f32_16x16x32_bf16 v[8:11], v[158:161], v[224:227], v[8:11]
	v_mfma_f32_16x16x32_bf16 v[60:63], v[154:157], v[192:195], v[60:63]
	v_mfma_f32_16x16x32_bf16 v[56:59], v[162:165], v[192:195], v[56:59]
	v_mfma_f32_16x16x32_bf16 v[44:47], v[154:157], v[200:203], v[44:47]
	v_mfma_f32_16x16x32_bf16 v[40:43], v[162:165], v[200:203], v[40:43]
	v_mfma_f32_16x16x32_bf16 v[28:31], v[154:157], v[214:217], v[28:31]
	v_mfma_f32_16x16x32_bf16 v[24:27], v[162:165], v[214:217], v[24:27]
	v_mfma_f32_16x16x32_bf16 v[12:15], v[154:157], v[228:231], v[12:15]
	v_mfma_f32_16x16x32_bf16 v[8:11], v[162:165], v[228:231], v[8:11]
	s_setprio 0
	s_setprio 1
	v_mfma_f32_16x16x32_bf16 v[52:55], v[166:169], v[188:191], v[52:55]
	v_mfma_f32_16x16x32_bf16 v[48:51], v[178:181], v[188:191], v[48:51]
	v_mfma_f32_16x16x32_bf16 v[36:39], v[166:169], v[196:199], v[36:39]
	v_mfma_f32_16x16x32_bf16 v[32:35], v[178:181], v[196:199], v[32:35]
	v_mfma_f32_16x16x32_bf16 v[20:23], v[166:169], v[204:207], v[20:23]
	v_mfma_f32_16x16x32_bf16 v[16:19], v[178:181], v[204:207], v[16:19]
	v_mfma_f32_16x16x32_bf16 v[4:7], v[166:169], v[224:227], v[4:7]
	v_mfma_f32_16x16x32_bf16 v[0:3], v[178:181], v[224:227], v[0:3]
	v_mfma_f32_16x16x32_bf16 v[52:55], v[174:177], v[192:195], v[52:55]
	v_mfma_f32_16x16x32_bf16 v[48:51], v[184:187], v[192:195], v[48:51]
	v_mfma_f32_16x16x32_bf16 v[36:39], v[174:177], v[200:203], v[36:39]
	v_mfma_f32_16x16x32_bf16 v[32:35], v[184:187], v[200:203], v[32:35]
	v_mfma_f32_16x16x32_bf16 v[20:23], v[174:177], v[214:217], v[20:23]
	v_mfma_f32_16x16x32_bf16 v[16:19], v[184:187], v[214:217], v[16:19]
	v_mfma_f32_16x16x32_bf16 v[4:7], v[174:177], v[228:231], v[4:7]
	v_mfma_f32_16x16x32_bf16 v[0:3], v[184:187], v[228:231], v[0:3]
	s_setprio 0
	s_barrier
	s_add_i32 s30, 0, 0x18000
	s_add_i32 s31, 0, 0x1c000
	v_add_u32_e32 v162, s30, v170
	v_add_u32_e32 v173, s31, v170
	ds_read_b128 v[150:153], v162
	ds_read_b128 v[154:157], v162 offset:1024
	ds_read_b128 v[158:161], v162 offset:2048
	ds_read_b128 v[162:165], v162 offset:3072
	ds_read_b128 v[166:169], v173
	ds_read_b128 v[174:177], v173 offset:1024
	ds_read_b128 v[178:181], v173 offset:2048
	ds_read_b128 v[184:187], v173 offset:3072
	s_add_u32 s22, s46, 0xb0000
	s_addc_u32 s23, s47, 0
	s_mov_b32 m0, s67
	ds_read_b128 v[188:191], v172 offset:32768
	ds_read_b128 v[192:195], v172 offset:33792
	ds_read_b128 v[196:199], v172 offset:34816
	ds_read_b128 v[200:203], v172 offset:35840
	ds_read_b128 v[204:207], v172 offset:36864
	ds_read_b128 v[214:217], v172 offset:37888
	ds_read_b128 v[224:227], v172 offset:38912
	ds_read_b128 v[228:231], v172 offset:39936
	global_load_lds_dwordx4 v208, s[22:23]
	s_mov_b32 m0, s68
	s_nop 0
	global_load_lds_dwordx4 v128, s[22:23]
	s_waitcnt vmcnt(8)
	s_waitcnt lgkmcnt(0)
	s_barrier
	s_setprio 1
	s_waitcnt lgkmcnt(0)
	v_mfma_f32_16x16x32_bf16 v[124:127], v[150:153], v[188:191], v[124:127]
	v_mfma_f32_16x16x32_bf16 v[120:123], v[158:161], v[188:191], v[120:123]
	v_mfma_f32_16x16x32_bf16 v[108:111], v[150:153], v[196:199], v[108:111]
	v_mfma_f32_16x16x32_bf16 v[104:107], v[158:161], v[196:199], v[104:107]
	v_mfma_f32_16x16x32_bf16 v[92:95], v[150:153], v[204:207], v[92:95]
	v_mfma_f32_16x16x32_bf16 v[88:91], v[158:161], v[204:207], v[88:91]
	v_mfma_f32_16x16x32_bf16 v[76:79], v[150:153], v[224:227], v[76:79]
	v_mfma_f32_16x16x32_bf16 v[72:75], v[158:161], v[224:227], v[72:75]
	v_mfma_f32_16x16x32_bf16 v[124:127], v[154:157], v[192:195], v[124:127]
	v_mfma_f32_16x16x32_bf16 v[120:123], v[162:165], v[192:195], v[120:123]
	v_mfma_f32_16x16x32_bf16 v[108:111], v[154:157], v[200:203], v[108:111]
	v_mfma_f32_16x16x32_bf16 v[104:107], v[162:165], v[200:203], v[104:107]
	v_mfma_f32_16x16x32_bf16 v[92:95], v[154:157], v[214:217], v[92:95]
	v_mfma_f32_16x16x32_bf16 v[88:91], v[162:165], v[214:217], v[88:91]
	v_mfma_f32_16x16x32_bf16 v[76:79], v[154:157], v[228:231], v[76:79]
	v_mfma_f32_16x16x32_bf16 v[72:75], v[162:165], v[228:231], v[72:75]
	s_setprio 0
	s_setprio 1
	v_mfma_f32_16x16x32_bf16 v[116:119], v[166:169], v[188:191], v[116:119]
	v_mfma_f32_16x16x32_bf16 v[112:115], v[178:181], v[188:191], v[112:115]
	v_mfma_f32_16x16x32_bf16 v[100:103], v[166:169], v[196:199], v[100:103]
	v_mfma_f32_16x16x32_bf16 v[96:99], v[178:181], v[196:199], v[96:99]
	v_mfma_f32_16x16x32_bf16 v[84:87], v[166:169], v[204:207], v[84:87]
	v_mfma_f32_16x16x32_bf16 v[80:83], v[178:181], v[204:207], v[80:83]
	v_mfma_f32_16x16x32_bf16 v[68:71], v[166:169], v[224:227], v[68:71]
	v_mfma_f32_16x16x32_bf16 v[64:67], v[178:181], v[224:227], v[64:67]
	v_mfma_f32_16x16x32_bf16 v[116:119], v[174:177], v[192:195], v[116:119]
	v_mfma_f32_16x16x32_bf16 v[112:115], v[184:187], v[192:195], v[112:115]
	v_mfma_f32_16x16x32_bf16 v[100:103], v[174:177], v[200:203], v[100:103]
	v_mfma_f32_16x16x32_bf16 v[96:99], v[184:187], v[200:203], v[96:99]
	v_mfma_f32_16x16x32_bf16 v[84:87], v[174:177], v[214:217], v[84:87]
	v_mfma_f32_16x16x32_bf16 v[80:83], v[184:187], v[214:217], v[80:83]
	v_mfma_f32_16x16x32_bf16 v[68:71], v[174:177], v[228:231], v[68:71]
	v_mfma_f32_16x16x32_bf16 v[64:67], v[184:187], v[228:231], v[64:67]
	s_setprio 0
	s_barrier
	s_add_i32 s22, s30, s48
	v_lshl_add_u64 v[232:233], v[232:233], 0, s[92:93]
	s_mov_b32 m0, s22
	ds_read_b128 v[188:191], v172 offset:49152
	ds_read_b128 v[192:195], v172 offset:50176
	ds_read_b128 v[196:199], v172 offset:51200
	ds_read_b128 v[200:203], v172 offset:52224
	ds_read_b128 v[204:207], v172 offset:53248
	ds_read_b128 v[214:217], v172 offset:54272
	ds_read_b128 v[224:227], v172 offset:55296
	ds_read_b128 v[228:231], v172 offset:56320
	global_load_lds_dwordx4 v[232:233], off
	s_add_i32 m0, s22, 0x2000
	s_add_u32 s22, s44, 0xb0080
	v_lshl_add_u64 v[232:233], v[234:235], 0, s[92:93]
	s_addc_u32 s23, s45, 0
	s_add_i32 s30, s31, s48
	global_load_lds_dwordx4 v[232:233], off
	s_mov_b32 m0, s30
	s_nop 0
	global_load_lds_dwordx4 v208, s[22:23]
	s_add_i32 m0, s30, 0x2000
	s_nop 0
	global_load_lds_dwordx4 v128, s[22:23]
	v_lshl_add_u64 v[232:233], v[238:239], 0, s[92:93]
	s_mov_b32 m0, s71
	s_nop 0
	global_load_lds_dwordx4 v[232:233], off
	v_lshl_add_u64 v[232:233], v[240:241], 0, s[92:93]
	s_mov_b32 m0, s4
	s_nop 0
	global_load_lds_dwordx4 v[232:233], off
	s_waitcnt vmcnt(8)
	s_waitcnt lgkmcnt(0)
	s_barrier
	s_setprio 1
	s_waitcnt lgkmcnt(0)
	v_mfma_f32_16x16x32_bf16 v[60:63], v[150:153], v[188:191], v[60:63]
	v_mfma_f32_16x16x32_bf16 v[56:59], v[158:161], v[188:191], v[56:59]
	v_mfma_f32_16x16x32_bf16 v[44:47], v[150:153], v[196:199], v[44:47]
	v_mfma_f32_16x16x32_bf16 v[40:43], v[158:161], v[196:199], v[40:43]
	v_mfma_f32_16x16x32_bf16 v[28:31], v[150:153], v[204:207], v[28:31]
	v_mfma_f32_16x16x32_bf16 v[24:27], v[158:161], v[204:207], v[24:27]
	v_mfma_f32_16x16x32_bf16 v[12:15], v[150:153], v[224:227], v[12:15]
	v_mfma_f32_16x16x32_bf16 v[8:11], v[158:161], v[224:227], v[8:11]
	v_mfma_f32_16x16x32_bf16 v[60:63], v[154:157], v[192:195], v[60:63]
	v_mfma_f32_16x16x32_bf16 v[56:59], v[162:165], v[192:195], v[56:59]
	v_mfma_f32_16x16x32_bf16 v[44:47], v[154:157], v[200:203], v[44:47]
	v_mfma_f32_16x16x32_bf16 v[40:43], v[162:165], v[200:203], v[40:43]
	v_mfma_f32_16x16x32_bf16 v[28:31], v[154:157], v[214:217], v[28:31]
	v_mfma_f32_16x16x32_bf16 v[24:27], v[162:165], v[214:217], v[24:27]
	v_mfma_f32_16x16x32_bf16 v[12:15], v[154:157], v[228:231], v[12:15]
	v_mfma_f32_16x16x32_bf16 v[8:11], v[162:165], v[228:231], v[8:11]
	s_setprio 0
	s_setprio 1
	v_mfma_f32_16x16x32_bf16 v[52:55], v[166:169], v[188:191], v[52:55]
	v_mfma_f32_16x16x32_bf16 v[48:51], v[178:181], v[188:191], v[48:51]
	v_mfma_f32_16x16x32_bf16 v[36:39], v[166:169], v[196:199], v[36:39]
	v_mfma_f32_16x16x32_bf16 v[32:35], v[178:181], v[196:199], v[32:35]
	v_mfma_f32_16x16x32_bf16 v[20:23], v[166:169], v[204:207], v[20:23]
	v_mfma_f32_16x16x32_bf16 v[16:19], v[178:181], v[204:207], v[16:19]
	v_mfma_f32_16x16x32_bf16 v[4:7], v[166:169], v[224:227], v[4:7]
	v_mfma_f32_16x16x32_bf16 v[0:3], v[178:181], v[224:227], v[0:3]
	v_mfma_f32_16x16x32_bf16 v[52:55], v[174:177], v[192:195], v[52:55]
	v_mfma_f32_16x16x32_bf16 v[48:51], v[184:187], v[192:195], v[48:51]
	v_mfma_f32_16x16x32_bf16 v[36:39], v[174:177], v[200:203], v[36:39]
	v_mfma_f32_16x16x32_bf16 v[32:35], v[184:187], v[200:203], v[32:35]
	v_mfma_f32_16x16x32_bf16 v[20:23], v[174:177], v[214:217], v[20:23]
	v_mfma_f32_16x16x32_bf16 v[16:19], v[184:187], v[214:217], v[16:19]
	v_mfma_f32_16x16x32_bf16 v[4:7], v[174:177], v[228:231], v[4:7]
	v_mfma_f32_16x16x32_bf16 v[0:3], v[184:187], v[228:231], v[0:3]
	s_setprio 0
	s_barrier
	s_add_i32 s25, s25, 2
	s_add_u32 s1, s1, 0x100
	s_addc_u32 s24, s24, 0
	s_cmp_gt_u32 s25, 41
	s_mov_b64 s[22:23], s[42:43]
	s_cbranch_scc0 .LBB0_1701
	s_and_b64 vcc, exec, s[38:39]
	s_cbranch_vccz .LBB0_1704
	s_barrier

.LBB0_1717:
	v_and_b32_e32 v16, 15, v183
	v_lshl_add_u64 v[8:9], s[44:45], 0, v[208:209]
	v_mov_b32_e32 v131, v209
	v_lshlrev_b32_e32 v184, 6, v16
	v_lshlrev_b32_e32 v17, 2, v183
	v_lshl_add_u64 v[10:11], s[44:45], 0, v[130:131]
	s_and_b32 s31, s27, 3
	v_lshl_or_b32 v128, s30, 6, v16
	s_lshl_b32 s6, s30, 13
	v_and_or_b32 v16, v183, 48, v184
	v_and_b32_e32 v17, 32, v17
	s_add_i32 m0, s41, 0x18000
	v_lshl_add_u64 v[8:9], v[8:9], 0, s[92:93]
	v_lshl_add_u64 v[12:13], s[0:1], 0, v[208:209]
	v_bitop3_b32 v18, v16, s6, v17 bitop3:0xde
	s_lshl_b32 s6, s31, 12
	s_waitcnt vmcnt(2)
	s_barrier
	global_load_lds_dwordx4 v[8:9], off
	v_lshl_add_u64 v[8:9], v[10:11], 0, s[92:93]
	s_add_i32 m0, s41, 0x1a000
	s_add_i32 s69, s41, 0x8000
	s_add_i32 s70, s41, 0xa000
	v_lshl_add_u64 v[14:15], s[0:1], 0, v[130:131]
	v_bitop3_b32 v129, v16, s6, v17 bitop3:0xde
	global_load_lds_dwordx4 v[8:9], off
	v_lshl_add_u64 v[8:9], v[12:13], 0, s[92:93]
	s_mov_b32 m0, s69
	s_add_u32 s6, s44, 0xb0080
	global_load_lds_dwordx4 v[8:9], off
	v_lshl_add_u64 v[8:9], v[14:15], 0, s[92:93]
	s_mov_b32 m0, s70
	s_addc_u32 s7, s45, 0
	global_load_lds_dwordx4 v[8:9], off
	s_add_i32 m0, s41, 0x1c000
	s_nop 0
	global_load_lds_dwordx4 v208, s[6:7]
	s_add_i32 m0, s41, 0x1e000
	s_movk_i32 s9, 0xb00
	global_load_lds_dwordx4 v130, s[6:7]
	v_lshrrev_b32_e32 v5, 1, v5
	v_mul_lo_u32 v4, v4, s9
	s_mov_b32 s8, 0xb000
	v_mad_u64_u32 v[4:5], s[6:7], v5, s8, v[4:5]
	v_or_b32_e32 v4, v4, v6
	v_add_lshl_u32 v132, v4, v7, 1
	v_lshrrev_b32_e32 v4, 1, v0
	v_mul_lo_u32 v0, v1, s9
	v_mad_u64_u32 v[0:1], s[6:7], v4, s8, v[0:1]
	s_waitcnt vmcnt(6)
	v_or_b32_e32 v0, v0, v2
	v_readlane_b32 s6, v252, 55
	v_add_lshl_u32 v134, v0, v3, 1
	v_mov_b32_e32 v0, 0
	s_mov_b32 s40, s6
	v_readlane_b32 s6, v252, 53
	v_mov_b32_e32 v133, v209
	v_mov_b32_e32 v135, v209
	s_mov_b32 s71, 0
	v_add_u32_e32 v140, 0, v18
	s_mov_b32 s38, s6
	v_mov_b32_e32 v1, v0
	v_mov_b32_e32 v2, v0
	v_mov_b32_e32 v3, v0
	v_mov_b32_e32 v16, v0
	v_mov_b32_e32 v17, v0
	v_mov_b32_e32 v18, v0
	v_mov_b32_e32 v19, v0
	v_mov_b32_e32 v4, v0
	v_mov_b32_e32 v5, v0
	v_mov_b32_e32 v6, v0
	v_mov_b32_e32 v7, v0
	v_mov_b32_e32 v24, v0
	v_mov_b32_e32 v25, v0
	v_mov_b32_e32 v26, v0
	v_mov_b32_e32 v27, v0
	v_mov_b32_e32 v8, v0
	v_mov_b32_e32 v9, v0
	v_mov_b32_e32 v10, v0
	v_mov_b32_e32 v11, v0
	v_mov_b32_e32 v32, v0
	v_mov_b32_e32 v33, v0
	v_mov_b32_e32 v34, v0
	v_mov_b32_e32 v35, v0
	v_mov_b32_e32 v12, v0
	v_mov_b32_e32 v13, v0
	v_mov_b32_e32 v14, v0
	v_mov_b32_e32 v15, v0
	v_mov_b32_e32 v40, v0
	v_mov_b32_e32 v41, v0
	v_mov_b32_e32 v42, v0
	v_mov_b32_e32 v43, v0
	v_mov_b32_e32 v56, v0
	v_mov_b32_e32 v57, v0
	v_mov_b32_e32 v58, v0
	v_mov_b32_e32 v59, v0
	v_mov_b32_e32 v80, v0
	v_mov_b32_e32 v81, v0
	v_mov_b32_e32 v82, v0
	v_mov_b32_e32 v83, v0
	v_mov_b32_e32 v64, v0
	v_mov_b32_e32 v65, v0
	v_mov_b32_e32 v66, v0
	v_mov_b32_e32 v67, v0
	v_mov_b32_e32 v88, v0
	v_mov_b32_e32 v89, v0
	v_mov_b32_e32 v90, v0
	v_mov_b32_e32 v91, v0
	v_mov_b32_e32 v68, v0
	v_mov_b32_e32 v69, v0
	v_mov_b32_e32 v70, v0
	v_mov_b32_e32 v71, v0
	v_mov_b32_e32 v96, v0
	v_mov_b32_e32 v97, v0
	v_mov_b32_e32 v98, v0
	v_mov_b32_e32 v99, v0
	v_mov_b32_e32 v76, v0
	v_mov_b32_e32 v77, v0
	v_mov_b32_e32 v78, v0
	v_mov_b32_e32 v79, v0
	v_mov_b32_e32 v104, v0
	v_mov_b32_e32 v105, v0
	v_mov_b32_e32 v106, v0
	v_mov_b32_e32 v107, v0
	v_mov_b32_e32 v20, v0
	v_mov_b32_e32 v21, v0
	v_mov_b32_e32 v22, v0
	v_mov_b32_e32 v23, v0
	v_mov_b32_e32 v48, v0
	v_mov_b32_e32 v49, v0
	v_mov_b32_e32 v50, v0
	v_mov_b32_e32 v51, v0
	v_mov_b32_e32 v28, v0
	v_mov_b32_e32 v29, v0
	v_mov_b32_e32 v30, v0
	v_mov_b32_e32 v31, v0
	v_mov_b32_e32 v52, v0
	v_mov_b32_e32 v53, v0
	v_mov_b32_e32 v54, v0
	v_mov_b32_e32 v55, v0
	v_mov_b32_e32 v36, v0
	v_mov_b32_e32 v37, v0
	v_mov_b32_e32 v38, v0
	v_mov_b32_e32 v39, v0
	v_mov_b32_e32 v60, v0
	v_mov_b32_e32 v61, v0
	v_mov_b32_e32 v62, v0
	v_mov_b32_e32 v63, v0
	v_mov_b32_e32 v44, v0
	v_mov_b32_e32 v45, v0
	v_mov_b32_e32 v46, v0
	v_mov_b32_e32 v47, v0
	v_mov_b32_e32 v72, v0
	v_mov_b32_e32 v73, v0
	v_mov_b32_e32 v74, v0
	v_mov_b32_e32 v75, v0
	v_mov_b32_e32 v84, v0
	v_mov_b32_e32 v85, v0
	v_mov_b32_e32 v86, v0
	v_mov_b32_e32 v87, v0
	v_mov_b32_e32 v112, v0
	v_mov_b32_e32 v113, v0
	v_mov_b32_e32 v114, v0
	v_mov_b32_e32 v115, v0
	v_mov_b32_e32 v92, v0
	v_mov_b32_e32 v93, v0
	v_mov_b32_e32 v94, v0
	v_mov_b32_e32 v95, v0
	v_mov_b32_e32 v116, v0
	v_mov_b32_e32 v117, v0
	v_mov_b32_e32 v118, v0
	v_mov_b32_e32 v119, v0
	v_mov_b32_e32 v100, v0
	v_mov_b32_e32 v101, v0
	v_mov_b32_e32 v102, v0
	v_mov_b32_e32 v103, v0
	v_mov_b32_e32 v120, v0
	v_mov_b32_e32 v121, v0
	v_mov_b32_e32 v122, v0
	v_mov_b32_e32 v123, v0
	v_mov_b32_e32 v108, v0
	v_mov_b32_e32 v109, v0
	v_mov_b32_e32 v110, v0
	v_mov_b32_e32 v111, v0
	v_mov_b32_e32 v124, v0
	v_mov_b32_e32 v125, v0
	v_mov_b32_e32 v126, v0
	v_mov_b32_e32 v127, v0
	s_barrier
	v_readlane_b32 s7, v252, 54
	s_branch .LBB0_1720

.LBB0_1731:
	s_add_u32 s46, s0, s44
	s_addc_u32 s47, s1, s45
	s_add_u32 s46, s46, 0x100
	s_addc_u32 s47, s47, 0
	s_add_u32 s74, s23, s44
	s_addc_u32 s75, s25, s45
	s_add_i32 s80, 0, 0x10000
	s_cmpk_eq_i32 s44, 0x1500
	s_cselect_b32 s49, s43, s47
	s_cselect_b32 s48, s42, s46
	v_add_u32_e32 v141, s80, v129
	s_cselect_b32 s47, s11, s75
	s_cselect_b32 s46, s10, s74
	s_add_i32 vcc_lo, 0, 0x14000
	ds_read_b128 v[142:145], v141
	ds_read_b128 v[146:149], v141 offset:1024
	ds_read_b128 v[150:153], v141 offset:2048
	ds_read_b128 v[154:157], v141 offset:3072
	v_add_u32_e32 v141, vcc_lo, v129
	ds_read_b128 v[158:161], v141
	ds_read_b128 v[162:165], v141 offset:1024
	ds_read_b128 v[166:169], v141 offset:2048
	ds_read_b128 v[170:173], v141 offset:3072
	v_lshl_add_u64 v[206:207], v[136:137], 0, s[44:45]
	s_add_i32 m0, s41, 0xc000
	ds_read_b128 v[174:177], v140
	ds_read_b128 v[178:181], v140 offset:1024
	ds_read_b128 v[186:189], v140 offset:2048
	ds_read_b128 v[190:193], v140 offset:3072
	ds_read_b128 v[194:197], v140 offset:4096
	ds_read_b128 v[198:201], v140 offset:5120
	ds_read_b128 v[202:205], v140 offset:6144
	ds_read_b128 v[214:217], v140 offset:7168
	global_load_lds_dwordx4 v[206:207], off
	v_lshl_add_u64 v[206:207], v[138:139], 0, s[44:45]
	s_add_i32 m0, s41, 0xe000
	s_nop 0
	global_load_lds_dwordx4 v[206:207], off
	s_waitcnt vmcnt(8)
	s_waitcnt lgkmcnt(0)
	s_barrier
	s_setprio 1
	s_waitcnt lgkmcnt(0)
	v_mfma_f32_16x16x32_bf16 v[124:127], v[142:145], v[174:177], v[124:127]
	v_mfma_f32_16x16x32_bf16 v[108:111], v[150:153], v[174:177], v[108:111]
	v_mfma_f32_16x16x32_bf16 v[120:123], v[142:145], v[186:189], v[120:123]
	v_mfma_f32_16x16x32_bf16 v[100:103], v[150:153], v[186:189], v[100:103]
	v_mfma_f32_16x16x32_bf16 v[116:119], v[142:145], v[194:197], v[116:119]
	v_mfma_f32_16x16x32_bf16 v[92:95], v[150:153], v[194:197], v[92:95]
	v_mfma_f32_16x16x32_bf16 v[112:115], v[142:145], v[202:205], v[112:115]
	v_mfma_f32_16x16x32_bf16 v[84:87], v[150:153], v[202:205], v[84:87]
	v_mfma_f32_16x16x32_bf16 v[124:127], v[146:149], v[178:181], v[124:127]
	v_mfma_f32_16x16x32_bf16 v[108:111], v[154:157], v[178:181], v[108:111]
	v_mfma_f32_16x16x32_bf16 v[120:123], v[146:149], v[190:193], v[120:123]
	v_mfma_f32_16x16x32_bf16 v[100:103], v[154:157], v[190:193], v[100:103]
	v_mfma_f32_16x16x32_bf16 v[116:119], v[146:149], v[198:201], v[116:119]
	v_mfma_f32_16x16x32_bf16 v[92:95], v[154:157], v[198:201], v[92:95]
	v_mfma_f32_16x16x32_bf16 v[112:115], v[146:149], v[214:217], v[112:115]
	v_mfma_f32_16x16x32_bf16 v[84:87], v[154:157], v[214:217], v[84:87]
	s_setprio 0
	s_setprio 1
	v_mfma_f32_16x16x32_bf16 v[72:75], v[158:161], v[174:177], v[72:75]
	v_mfma_f32_16x16x32_bf16 v[44:47], v[166:169], v[174:177], v[44:47]
	v_mfma_f32_16x16x32_bf16 v[60:63], v[158:161], v[186:189], v[60:63]
	v_mfma_f32_16x16x32_bf16 v[36:39], v[166:169], v[186:189], v[36:39]
	v_mfma_f32_16x16x32_bf16 v[52:55], v[158:161], v[194:197], v[52:55]
	v_mfma_f32_16x16x32_bf16 v[28:31], v[166:169], v[194:197], v[28:31]
	v_mfma_f32_16x16x32_bf16 v[48:51], v[158:161], v[202:205], v[48:51]
	v_mfma_f32_16x16x32_bf16 v[20:23], v[166:169], v[202:205], v[20:23]
	v_mfma_f32_16x16x32_bf16 v[72:75], v[162:165], v[178:181], v[72:75]
	v_mfma_f32_16x16x32_bf16 v[44:47], v[170:173], v[178:181], v[44:47]
	v_mfma_f32_16x16x32_bf16 v[60:63], v[162:165], v[190:193], v[60:63]
	v_mfma_f32_16x16x32_bf16 v[36:39], v[170:173], v[190:193], v[36:39]
	v_mfma_f32_16x16x32_bf16 v[52:55], v[162:165], v[198:201], v[52:55]
	v_mfma_f32_16x16x32_bf16 v[28:31], v[170:173], v[198:201], v[28:31]
	v_mfma_f32_16x16x32_bf16 v[48:51], v[162:165], v[214:217], v[48:51]
	v_mfma_f32_16x16x32_bf16 v[20:23], v[170:173], v[214:217], v[20:23]
	s_setprio 0
	s_barrier
	s_add_i32 s74, s80, s39
	v_lshl_add_u64 v[206:207], s[46:47], 0, v[208:209]
	s_mov_b32 m0, s74
	ds_read_b128 v[174:177], v140 offset:16384
	ds_read_b128 v[178:181], v140 offset:17408
	ds_read_b128 v[186:189], v140 offset:18432
	ds_read_b128 v[190:193], v140 offset:19456
	ds_read_b128 v[194:197], v140 offset:20480
	ds_read_b128 v[198:201], v140 offset:21504
	ds_read_b128 v[202:205], v140 offset:22528
	ds_read_b128 v[214:217], v140 offset:23552
	global_load_lds_dwordx4 v[206:207], off
	s_add_i32 m0, s74, 0x2000
	s_add_u32 s74, s46, 0xb0000
	v_lshl_add_u64 v[224:225], s[46:47], 0, v[130:131]
	s_addc_u32 s75, s47, 0
	s_add_i32 s80, vcc_lo, s39
	global_load_lds_dwordx4 v[224:225], off
	s_mov_b32 m0, s80
	v_lshl_add_u64 v[228:229], s[48:49], 0, v[130:131]
	global_load_lds_dwordx4 v208, s[74:75]
	s_add_i32 m0, s80, 0x2000
	s_nop 0
	global_load_lds_dwordx4 v130, s[74:75]
	v_lshl_add_u64 v[226:227], s[48:49], 0, v[208:209]
	s_mov_b32 m0, s41
	s_nop 0
	global_load_lds_dwordx4 v[226:227], off
	s_mov_b32 m0, s66
	s_nop 0
	global_load_lds_dwordx4 v[228:229], off
	s_waitcnt vmcnt(8)
	s_waitcnt lgkmcnt(0)
	s_barrier
	s_setprio 1
	s_waitcnt lgkmcnt(0)
	v_mfma_f32_16x16x32_bf16 v[104:107], v[142:145], v[174:177], v[104:107]
	v_mfma_f32_16x16x32_bf16 v[76:79], v[150:153], v[174:177], v[76:79]
	v_mfma_f32_16x16x32_bf16 v[96:99], v[142:145], v[186:189], v[96:99]
	v_mfma_f32_16x16x32_bf16 v[68:71], v[150:153], v[186:189], v[68:71]
	v_mfma_f32_16x16x32_bf16 v[88:91], v[142:145], v[194:197], v[88:91]
	v_mfma_f32_16x16x32_bf16 v[64:67], v[150:153], v[194:197], v[64:67]
	v_mfma_f32_16x16x32_bf16 v[80:83], v[142:145], v[202:205], v[80:83]
	v_mfma_f32_16x16x32_bf16 v[56:59], v[150:153], v[202:205], v[56:59]
	v_mfma_f32_16x16x32_bf16 v[104:107], v[146:149], v[178:181], v[104:107]
	v_mfma_f32_16x16x32_bf16 v[76:79], v[154:157], v[178:181], v[76:79]
	v_mfma_f32_16x16x32_bf16 v[96:99], v[146:149], v[190:193], v[96:99]
	v_mfma_f32_16x16x32_bf16 v[68:71], v[154:157], v[190:193], v[68:71]
	v_mfma_f32_16x16x32_bf16 v[88:91], v[146:149], v[198:201], v[88:91]
	v_mfma_f32_16x16x32_bf16 v[64:67], v[154:157], v[198:201], v[64:67]
	v_mfma_f32_16x16x32_bf16 v[80:83], v[146:149], v[214:217], v[80:83]
	v_mfma_f32_16x16x32_bf16 v[56:59], v[154:157], v[214:217], v[56:59]
	s_setprio 0
	s_setprio 1
	v_mfma_f32_16x16x32_bf16 v[40:43], v[158:161], v[174:177], v[40:43]
	v_mfma_f32_16x16x32_bf16 v[12:15], v[166:169], v[174:177], v[12:15]
	v_mfma_f32_16x16x32_bf16 v[32:35], v[158:161], v[186:189], v[32:35]
	v_mfma_f32_16x16x32_bf16 v[8:11], v[166:169], v[186:189], v[8:11]
	v_mfma_f32_16x16x32_bf16 v[24:27], v[158:161], v[194:197], v[24:27]
	v_mfma_f32_16x16x32_bf16 v[4:7], v[166:169], v[194:197], v[4:7]
	v_mfma_f32_16x16x32_bf16 v[16:19], v[158:161], v[202:205], v[16:19]
	v_mfma_f32_16x16x32_bf16 v[0:3], v[166:169], v[202:205], v[0:3]
	v_mfma_f32_16x16x32_bf16 v[40:43], v[162:165], v[178:181], v[40:43]
	v_mfma_f32_16x16x32_bf16 v[12:15], v[170:173], v[178:181], v[12:15]
	v_mfma_f32_16x16x32_bf16 v[32:35], v[162:165], v[190:193], v[32:35]
	v_mfma_f32_16x16x32_bf16 v[8:11], v[170:173], v[190:193], v[8:11]
	v_mfma_f32_16x16x32_bf16 v[24:27], v[162:165], v[198:201], v[24:27]
	v_mfma_f32_16x16x32_bf16 v[4:7], v[170:173], v[198:201], v[4:7]
	v_mfma_f32_16x16x32_bf16 v[16:19], v[162:165], v[214:217], v[16:19]
	v_mfma_f32_16x16x32_bf16 v[0:3], v[170:173], v[214:217], v[0:3]
	s_setprio 0
	s_barrier
	s_add_i32 s74, 0, 0x18000
	v_add_u32_e32 v141, s74, v129
	s_add_i32 s75, 0, 0x1c000
	ds_read_b128 v[142:145], v141
	ds_read_b128 v[146:149], v141 offset:1024
	ds_read_b128 v[150:153], v141 offset:2048
	ds_read_b128 v[154:157], v141 offset:3072
	v_add_u32_e32 v141, s75, v129
	ds_read_b128 v[158:161], v141
	ds_read_b128 v[162:165], v141 offset:1024
	ds_read_b128 v[166:169], v141 offset:2048
	ds_read_b128 v[170:173], v141 offset:3072
	s_add_u32 s48, s48, 0xb0000
	s_addc_u32 s49, s49, 0
	s_mov_b32 m0, s67
	ds_read_b128 v[174:177], v140 offset:32768
	ds_read_b128 v[178:181], v140 offset:33792
	ds_read_b128 v[186:189], v140 offset:34816
	ds_read_b128 v[190:193], v140 offset:35840
	ds_read_b128 v[194:197], v140 offset:36864
	ds_read_b128 v[198:201], v140 offset:37888
	ds_read_b128 v[202:205], v140 offset:38912
	ds_read_b128 v[214:217], v140 offset:39936
	global_load_lds_dwordx4 v208, s[48:49]
	s_mov_b32 m0, s68
	s_nop 0
	global_load_lds_dwordx4 v130, s[48:49]
	s_waitcnt vmcnt(8)
	s_waitcnt lgkmcnt(0)
	s_barrier
	s_setprio 1
	s_waitcnt lgkmcnt(0)
	v_mfma_f32_16x16x32_bf16 v[124:127], v[142:145], v[174:177], v[124:127]
	v_mfma_f32_16x16x32_bf16 v[108:111], v[150:153], v[174:177], v[108:111]
	v_mfma_f32_16x16x32_bf16 v[120:123], v[142:145], v[186:189], v[120:123]
	v_mfma_f32_16x16x32_bf16 v[100:103], v[150:153], v[186:189], v[100:103]
	v_mfma_f32_16x16x32_bf16 v[116:119], v[142:145], v[194:197], v[116:119]
	v_mfma_f32_16x16x32_bf16 v[92:95], v[150:153], v[194:197], v[92:95]
	v_mfma_f32_16x16x32_bf16 v[112:115], v[142:145], v[202:205], v[112:115]
	v_mfma_f32_16x16x32_bf16 v[84:87], v[150:153], v[202:205], v[84:87]
	v_mfma_f32_16x16x32_bf16 v[124:127], v[146:149], v[178:181], v[124:127]
	v_mfma_f32_16x16x32_bf16 v[108:111], v[154:157], v[178:181], v[108:111]
	v_mfma_f32_16x16x32_bf16 v[120:123], v[146:149], v[190:193], v[120:123]
	v_mfma_f32_16x16x32_bf16 v[100:103], v[154:157], v[190:193], v[100:103]
	v_mfma_f32_16x16x32_bf16 v[116:119], v[146:149], v[198:201], v[116:119]
	v_mfma_f32_16x16x32_bf16 v[92:95], v[154:157], v[198:201], v[92:95]
	v_mfma_f32_16x16x32_bf16 v[112:115], v[146:149], v[214:217], v[112:115]
	v_mfma_f32_16x16x32_bf16 v[84:87], v[154:157], v[214:217], v[84:87]
	s_setprio 0
	s_setprio 1
	v_mfma_f32_16x16x32_bf16 v[72:75], v[158:161], v[174:177], v[72:75]
	v_mfma_f32_16x16x32_bf16 v[44:47], v[166:169], v[174:177], v[44:47]
	v_mfma_f32_16x16x32_bf16 v[60:63], v[158:161], v[186:189], v[60:63]
	v_mfma_f32_16x16x32_bf16 v[36:39], v[166:169], v[186:189], v[36:39]
	v_mfma_f32_16x16x32_bf16 v[52:55], v[158:161], v[194:197], v[52:55]
	v_mfma_f32_16x16x32_bf16 v[28:31], v[166:169], v[194:197], v[28:31]
	v_mfma_f32_16x16x32_bf16 v[48:51], v[158:161], v[202:205], v[48:51]
	v_mfma_f32_16x16x32_bf16 v[20:23], v[166:169], v[202:205], v[20:23]
	v_mfma_f32_16x16x32_bf16 v[72:75], v[162:165], v[178:181], v[72:75]
	v_mfma_f32_16x16x32_bf16 v[44:47], v[170:173], v[178:181], v[44:47]
	v_mfma_f32_16x16x32_bf16 v[60:63], v[162:165], v[190:193], v[60:63]
	v_mfma_f32_16x16x32_bf16 v[36:39], v[170:173], v[190:193], v[36:39]
	v_mfma_f32_16x16x32_bf16 v[52:55], v[162:165], v[198:201], v[52:55]
	v_mfma_f32_16x16x32_bf16 v[28:31], v[170:173], v[198:201], v[28:31]
	v_mfma_f32_16x16x32_bf16 v[48:51], v[162:165], v[214:217], v[48:51]
	v_mfma_f32_16x16x32_bf16 v[20:23], v[170:173], v[214:217], v[20:23]
	s_setprio 0
	s_barrier
	s_add_i32 s48, s74, s39
	v_lshl_add_u64 v[206:207], v[206:207], 0, s[92:93]
	s_mov_b32 m0, s48
	ds_read_b128 v[174:177], v140 offset:49152
	ds_read_b128 v[178:181], v140 offset:50176
	ds_read_b128 v[186:189], v140 offset:51200
	ds_read_b128 v[190:193], v140 offset:52224
	ds_read_b128 v[194:197], v140 offset:53248
	ds_read_b128 v[198:201], v140 offset:54272
	ds_read_b128 v[202:205], v140 offset:55296
	ds_read_b128 v[214:217], v140 offset:56320
	global_load_lds_dwordx4 v[206:207], off
	s_add_i32 m0, s48, 0x2000
	s_add_u32 s46, s46, 0xb0080
	v_lshl_add_u64 v[206:207], v[224:225], 0, s[92:93]
	s_addc_u32 s47, s47, 0
	s_add_i32 s48, s75, s39
	global_load_lds_dwordx4 v[206:207], off
	s_mov_b32 m0, s48
	s_nop 0
	global_load_lds_dwordx4 v208, s[46:47]
	s_add_i32 m0, s48, 0x2000
	s_nop 0
	global_load_lds_dwordx4 v130, s[46:47]
	v_lshl_add_u64 v[206:207], v[226:227], 0, s[92:93]
	s_mov_b32 m0, s69
	s_nop 0
	global_load_lds_dwordx4 v[206:207], off
	v_lshl_add_u64 v[206:207], v[228:229], 0, s[92:93]
	s_mov_b32 m0, s70
	s_nop 0
	global_load_lds_dwordx4 v[206:207], off
	s_waitcnt vmcnt(8)
	s_waitcnt lgkmcnt(0)
	s_barrier
	s_setprio 1
	s_waitcnt lgkmcnt(0)
	v_mfma_f32_16x16x32_bf16 v[104:107], v[142:145], v[174:177], v[104:107]
	v_mfma_f32_16x16x32_bf16 v[76:79], v[150:153], v[174:177], v[76:79]
	v_mfma_f32_16x16x32_bf16 v[96:99], v[142:145], v[186:189], v[96:99]
	v_mfma_f32_16x16x32_bf16 v[68:71], v[150:153], v[186:189], v[68:71]
	v_mfma_f32_16x16x32_bf16 v[88:91], v[142:145], v[194:197], v[88:91]
	v_mfma_f32_16x16x32_bf16 v[64:67], v[150:153], v[194:197], v[64:67]
	v_mfma_f32_16x16x32_bf16 v[80:83], v[142:145], v[202:205], v[80:83]
	v_mfma_f32_16x16x32_bf16 v[56:59], v[150:153], v[202:205], v[56:59]
	v_mfma_f32_16x16x32_bf16 v[104:107], v[146:149], v[178:181], v[104:107]
	v_mfma_f32_16x16x32_bf16 v[76:79], v[154:157], v[178:181], v[76:79]
	v_mfma_f32_16x16x32_bf16 v[96:99], v[146:149], v[190:193], v[96:99]
	v_mfma_f32_16x16x32_bf16 v[68:71], v[154:157], v[190:193], v[68:71]
	v_mfma_f32_16x16x32_bf16 v[88:91], v[146:149], v[198:201], v[88:91]
	v_mfma_f32_16x16x32_bf16 v[64:67], v[154:157], v[198:201], v[64:67]
	v_mfma_f32_16x16x32_bf16 v[80:83], v[146:149], v[214:217], v[80:83]
	v_mfma_f32_16x16x32_bf16 v[56:59], v[154:157], v[214:217], v[56:59]
	s_setprio 0
	s_setprio 1
	v_mfma_f32_16x16x32_bf16 v[40:43], v[158:161], v[174:177], v[40:43]
	v_mfma_f32_16x16x32_bf16 v[12:15], v[166:169], v[174:177], v[12:15]
	v_mfma_f32_16x16x32_bf16 v[32:35], v[158:161], v[186:189], v[32:35]
	v_mfma_f32_16x16x32_bf16 v[8:11], v[166:169], v[186:189], v[8:11]
	v_mfma_f32_16x16x32_bf16 v[24:27], v[158:161], v[194:197], v[24:27]
	v_mfma_f32_16x16x32_bf16 v[4:7], v[166:169], v[194:197], v[4:7]
	v_mfma_f32_16x16x32_bf16 v[16:19], v[158:161], v[202:205], v[16:19]
	v_mfma_f32_16x16x32_bf16 v[0:3], v[166:169], v[202:205], v[0:3]
	v_mfma_f32_16x16x32_bf16 v[40:43], v[162:165], v[178:181], v[40:43]
	v_mfma_f32_16x16x32_bf16 v[12:15], v[170:173], v[178:181], v[12:15]
	v_mfma_f32_16x16x32_bf16 v[32:35], v[162:165], v[190:193], v[32:35]
	v_mfma_f32_16x16x32_bf16 v[8:11], v[170:173], v[190:193], v[8:11]
	v_mfma_f32_16x16x32_bf16 v[24:27], v[162:165], v[198:201], v[24:27]
	v_mfma_f32_16x16x32_bf16 v[4:7], v[170:173], v[198:201], v[4:7]
	v_mfma_f32_16x16x32_bf16 v[16:19], v[162:165], v[214:217], v[16:19]
	v_mfma_f32_16x16x32_bf16 v[0:3], v[170:173], v[214:217], v[0:3]
	s_setprio 0
	s_barrier
	s_add_i32 s24, s24, 2
	s_add_u32 s44, s44, 0x100
	s_addc_u32 s45, s45, 0
	s_cmp_gt_u32 s24, 41
	s_cbranch_scc0 .LBB0_1731
	s_add_u32 s24, s23, 0xffffff00
	s_addc_u32 s25, s25, -1
	s_and_b64 vcc, exec, s[8:9]
	s_cbranch_vccnz .LBB0_1718
	v_mov_b32_e32 v0, 0
	s_mov_b32 s40, s72
	s_mov_b32 s38, s73
	s_mov_b64 s[0:1], s[42:43]
	s_mov_b32 s71, s22
	v_mov_b32_e32 v1, v0
	v_mov_b32_e32 v2, v0
	v_mov_b32_e32 v3, v0
	v_mov_b32_e32 v16, v0
	v_mov_b32_e32 v17, v0
	v_mov_b32_e32 v18, v0
	v_mov_b32_e32 v19, v0
	v_mov_b32_e32 v4, v0
	v_mov_b32_e32 v5, v0
	v_mov_b32_e32 v6, v0
	v_mov_b32_e32 v7, v0
	v_mov_b32_e32 v24, v0
	v_mov_b32_e32 v25, v0
	v_mov_b32_e32 v26, v0
	v_mov_b32_e32 v27, v0
	v_mov_b32_e32 v8, v0
	v_mov_b32_e32 v9, v0
	v_mov_b32_e32 v10, v0
	v_mov_b32_e32 v11, v0
	v_mov_b32_e32 v32, v0
	v_mov_b32_e32 v33, v0
	v_mov_b32_e32 v34, v0
	v_mov_b32_e32 v35, v0
	v_mov_b32_e32 v12, v0
	v_mov_b32_e32 v13, v0
	v_mov_b32_e32 v14, v0
	v_mov_b32_e32 v15, v0
	v_mov_b32_e32 v40, v0
	v_mov_b32_e32 v41, v0
	v_mov_b32_e32 v42, v0
	v_mov_b32_e32 v43, v0
	v_mov_b32_e32 v56, v0
	v_mov_b32_e32 v57, v0
	v_mov_b32_e32 v58, v0
	v_mov_b32_e32 v59, v0
	v_mov_b32_e32 v80, v0
	v_mov_b32_e32 v81, v0
	v_mov_b32_e32 v82, v0
	v_mov_b32_e32 v83, v0
	v_mov_b32_e32 v64, v0
	v_mov_b32_e32 v65, v0
	v_mov_b32_e32 v66, v0
	v_mov_b32_e32 v67, v0
	v_mov_b32_e32 v88, v0
	v_mov_b32_e32 v89, v0
	v_mov_b32_e32 v90, v0
	v_mov_b32_e32 v91, v0
	v_mov_b32_e32 v68, v0
	v_mov_b32_e32 v69, v0
	v_mov_b32_e32 v70, v0
	v_mov_b32_e32 v71, v0
	v_mov_b32_e32 v96, v0
	v_mov_b32_e32 v97, v0
	v_mov_b32_e32 v98, v0
	v_mov_b32_e32 v99, v0
	v_mov_b32_e32 v76, v0
	v_mov_b32_e32 v77, v0
	v_mov_b32_e32 v78, v0
	v_mov_b32_e32 v79, v0
	v_mov_b32_e32 v104, v0
	v_mov_b32_e32 v105, v0
	v_mov_b32_e32 v106, v0
	v_mov_b32_e32 v107, v0
	v_mov_b32_e32 v20, v0
	v_mov_b32_e32 v21, v0
	v_mov_b32_e32 v22, v0
	v_mov_b32_e32 v23, v0
	v_mov_b32_e32 v48, v0
	v_mov_b32_e32 v49, v0
	v_mov_b32_e32 v50, v0
	v_mov_b32_e32 v51, v0
	v_mov_b32_e32 v28, v0
	v_mov_b32_e32 v29, v0
	v_mov_b32_e32 v30, v0
	v_mov_b32_e32 v31, v0
	v_mov_b32_e32 v52, v0
	v_mov_b32_e32 v53, v0
	v_mov_b32_e32 v54, v0
	v_mov_b32_e32 v55, v0
	v_mov_b32_e32 v36, v0
	v_mov_b32_e32 v37, v0
	v_mov_b32_e32 v38, v0
	v_mov_b32_e32 v39, v0
	v_mov_b32_e32 v60, v0
	v_mov_b32_e32 v61, v0
	v_mov_b32_e32 v62, v0
	v_mov_b32_e32 v63, v0
	v_mov_b32_e32 v44, v0
	v_mov_b32_e32 v45, v0
	v_mov_b32_e32 v46, v0
	v_mov_b32_e32 v47, v0
	v_mov_b32_e32 v72, v0
	v_mov_b32_e32 v73, v0
	v_mov_b32_e32 v74, v0
	v_mov_b32_e32 v75, v0
	v_mov_b32_e32 v84, v0
	v_mov_b32_e32 v85, v0
	v_mov_b32_e32 v86, v0
	v_mov_b32_e32 v87, v0
	v_mov_b32_e32 v112, v0
	v_mov_b32_e32 v113, v0
	v_mov_b32_e32 v114, v0
	v_mov_b32_e32 v115, v0
	v_mov_b32_e32 v92, v0
	v_mov_b32_e32 v93, v0
	v_mov_b32_e32 v94, v0
	v_mov_b32_e32 v95, v0
	v_mov_b32_e32 v116, v0
	v_mov_b32_e32 v117, v0
	v_mov_b32_e32 v118, v0
	v_mov_b32_e32 v119, v0
	v_mov_b32_e32 v100, v0
	v_mov_b32_e32 v101, v0
	v_mov_b32_e32 v102, v0
	v_mov_b32_e32 v103, v0
	v_mov_b32_e32 v120, v0
	v_mov_b32_e32 v121, v0
	v_mov_b32_e32 v122, v0
	v_mov_b32_e32 v123, v0
	v_mov_b32_e32 v108, v0
	v_mov_b32_e32 v109, v0
	v_mov_b32_e32 v110, v0
	v_mov_b32_e32 v111, v0
	v_mov_b32_e32 v124, v0
	v_mov_b32_e32 v125, v0
	v_mov_b32_e32 v126, v0
	v_mov_b32_e32 v127, v0
	s_andn2_b64 vcc, exec, s[6:7]
	s_cbranch_vccnz .LBB0_1719
